# P5 epilogue loads software-pipelined one group ahead (address ops copied, destinations re-homed, vmcnt recounted)
# baseline (speedup 1.0000x reference)
;     __device__ __forceinline__ void operator()(const f32x4 (&acc)[2][2][4][2], const Unit& u, int wr, int wc, int fr, int fq) const {
;         const int row0 = u.pm * BM + wr * 64 + fr, col0 = u.pn * BM + wc * 32 + 8 * fq;
;         float rsv[2][4];
; #pragma unroll
;         for (int ai = 0; ai < 2; ++ai)
; #pragma unroll
;             for (int m = 0; m < 4; ++m) rsv[ai][m] = ssq1[row0 + ai * HALF + m * 16];
; #pragma unroll
;         for (int ai = 0; ai < 2; ++ai) { float s[4] = {0.f, 0.f, 0.f, 0.f};
; #pragma unroll
;             for (int bj = 0; bj < 2; ++bj)
; #pragma unroll
;               for (int mh = 0; mh < 2; ++mh) { f32x4 x0[2], x1[2]; u32x4 tw[2];
; #pragma unroll
;                 for (int mm = 0; mm < 2; ++mm) { const int m = 2 * mh + mm; const size_t o = (size_t)(row0 + ai * HALF + m * 16) * DM + col0 + bj * HALF; x0[mm] = *(const f32x4*)(X1 + o); x1[mm] = *(const f32x4*)(X1 + o + 4); tw[mm] = *(const u32x4*)(T + o); }
; #pragma unroll
;                 for (int mm = 0; mm < 2; ++mm) { const int m = 2 * mh + mm; const size_t o = (size_t)(row0 + ai * HALF + m * 16) * DM + col0 + bj * HALF;
;                     const float rs = rsqrtf(rsv[ai][m] * (1.f / DM) + EPS);
;                     const f32x4 a0 = acc[ai][bj][m][0], a1 = acc[ai][bj][m][1]; f32x4 v0 = x0[mm], v1 = x1[mm];
;                     v0[0] += sigm(a0[0] * rs) * bf_lo(tw[mm].x); v0[1] += sigm(a0[1] * rs) * bf_hi(tw[mm].x); v0[2] += sigm(a0[2] * rs) * bf_lo(tw[mm].y); v0[3] += sigm(a0[3] * rs) * bf_hi(tw[mm].y);
;                     v1[0] += sigm(a1[0] * rs) * bf_lo(tw[mm].z); v1[1] += sigm(a1[1] * rs) * bf_hi(tw[mm].z); v1[2] += sigm(a1[2] * rs) * bf_lo(tw[mm].w); v1[3] += sigm(a1[3] * rs) * bf_hi(tw[mm].w);
;                     *(f32x4*)(xout + o) = v0; *(f32x4*)(xout + o + 4) = v1;
;                     if (wxb) { u32x4 w; w.x = pk2(v0[0], v0[1]); w.y = pk2(v0[2], v0[3]); w.z = pk2(v1[0], v1[1]); w.w = pk2(v1[2], v1[3]); *(u32x4*)(XB + o) = w;
;                         int q0 = 0, q1 = 0; q0 = __builtin_amdgcn_cvt_pk_fp8_f32(v0[0] * 8.f, v0[1] * 8.f, q0, false); q0 = __builtin_amdgcn_cvt_pk_fp8_f32(v0[2] * 8.f, v0[3] * 8.f, q0, true);
;                         q1 = __builtin_amdgcn_cvt_pk_fp8_f32(v1[0] * 8.f, v1[1] * 8.f, q1, false); q1 = __builtin_amdgcn_cvt_pk_fp8_f32(v1[2] * 8.f, v1[3] * 8.f, q1, true);
.LBB0_1357:
	s_lshl_b32 s0, s5, 8
	v_mov_b32_e32 v180, v162
	s_add_i32 s0, s0, s43
	s_nop 0
	v_and_or_b32 v140, v180, 15, s0
	v_ashrrev_i32_e32 v128, 1, v180
	v_ashrrev_i32_e32 v141, 31, v140
	v_and_b32_e32 v130, -8, v128
	v_lshl_add_u64 v[128:129], v[140:141], 2, s[24:25]
	global_load_dword v181, v[128:129], off
	s_lshl_b32 s0, s4, 8
	s_or_b32 s0, s0, s44
	v_add_u32_e32 v142, s0, v130
	v_ashrrev_i32_e32 v143, 31, v142
	v_lshlrev_b64 v[150:151], 11, v[140:141]
	v_lshl_add_u64 v[198:199], v[150:151], 0, v[142:143]
	v_lshlrev_b64 v[200:201], 1, v[198:199]
	v_lshl_add_u64 v[130:131], s[22:23], 0, v[200:201]
	global_load_dwordx4 v[182:185], v[130:131], off
	v_lshlrev_b64 v[154:155], 2, v[198:199]
	v_lshl_add_u64 v[130:131], s[20:21], 0, v[154:155]
	global_load_dwordx4 v[186:189], v[130:131], off offset:16
	global_load_dwordx4 v[190:193], v[130:131], off
	v_or_b32_e32 v148, 16, v140
	v_or_b32_e32 v146, 32, v140
	v_or_b32_e32 v144, 48, v140
	v_ashrrev_i32_e32 v149, 31, v148
	v_ashrrev_i32_e32 v147, 31, v146
	v_ashrrev_i32_e32 v145, 31, v144
	v_lshl_add_u64 v[130:131], v[148:149], 2, s[24:25]
	v_lshl_add_u64 v[132:133], v[146:147], 2, s[24:25]
	v_lshl_add_u64 v[134:135], v[144:145], 2, s[24:25]
	global_load_dword v179, v[128:129], off offset:512
	global_load_dword v178, v[128:129], off offset:576
	global_load_dword v177, v[128:129], off offset:640
	global_load_dword v212, v[130:131], off
	global_load_dword v214, v[132:133], off
	global_load_dword v216, v[134:135], off
	global_load_dword v176, v[128:129], off offset:704
	v_lshlrev_b64 v[152:153], 11, v[148:149]
	v_lshl_add_u64 v[156:157], v[152:153], 0, v[142:143]
	v_lshlrev_b64 v[160:161], 2, v[156:157]
	v_lshlrev_b64 v[158:159], 1, v[156:157]
	v_lshl_add_u64 v[128:129], s[20:21], 0, v[160:161]
	v_lshl_add_u64 v[132:133], s[22:23], 0, v[158:159]
	global_load_dwordx4 v[194:197], v[128:129], off
	s_nop 0
	global_load_dwordx4 v[128:131], v[128:129], off offset:16
	s_nop 0
	global_load_dwordx4 v[132:135], v[132:133], off
	v_lshl_add_u64 v[154:155], s[8:9], 0, v[154:155]
	v_lshl_add_u64 v[158:159], s[26:27], 0, v[158:159]
	v_lshlrev_b64 v[242:243], 11, v[146:147]
	v_lshl_add_u64 v[244:245], v[242:243], 0, v[142:143]
	v_lshlrev_b64 v[242:243], 1, v[244:245]
	v_lshl_add_u64 v[246:247], s[22:23], 0, v[242:243]
	global_load_dwordx4 v[218:221], v[246:247], off
	v_lshlrev_b64 v[242:243], 2, v[244:245]
	v_lshl_add_u64 v[246:247], s[20:21], 0, v[242:243]
	global_load_dwordx4 v[222:225], v[246:247], off
	global_load_dwordx4 v[226:229], v[246:247], off offset:16
	v_lshlrev_b64 v[242:243], 11, v[144:145]
	v_lshl_add_u64 v[246:247], v[242:243], 0, v[142:143]
	v_lshlrev_b64 v[242:243], 2, v[246:247]
	v_lshlrev_b64 v[244:245], 1, v[246:247]
	v_lshl_add_u64 v[246:247], s[20:21], 0, v[242:243]
	v_lshl_add_u64 v[250:251], s[22:23], 0, v[244:245]
	global_load_dwordx4 v[230:233], v[246:247], off
	global_load_dwordx4 v[234:237], v[246:247], off offset:16
	global_load_dwordx4 v[238:241], v[250:251], off
	s_waitcnt vmcnt(6)
	v_fmamk_f32 v181, v181, 0x3a000000, v175
	v_mul_f32_e32 v202, 0x4b800000, v181
	v_cmp_gt_f32_e32 vcc, s49, v181
	v_lshlrev_b32_e32 v204, 16, v184
	s_nop 0
	v_cndmask_b32_e32 v181, v181, v202, vcc
	v_rsq_f32_e32 v181, v181
	v_and_b32_e32 v205, 0xffff0000, v184
	v_lshlrev_b32_e32 v206, 16, v185
	v_and_b32_e32 v207, 0xffff0000, v185
	v_mul_f32_e32 v184, 0x45800000, v181
	v_cndmask_b32_e32 v184, v181, v184, vcc
	v_mul_f32_e32 v124, v124, v184
	v_mul_f32_e32 v125, v125, v184
	v_mul_f32_e32 v120, v120, v184
	v_mul_f32_e32 v121, v121, v184
	v_mul_f32_e32 v124, 0xbfb8aa3b, v124
	v_mul_f32_e32 v125, 0xbfb8aa3b, v125
	v_mul_f32_e32 v120, 0xbfb8aa3b, v120
	v_mul_f32_e32 v121, 0xbfb8aa3b, v121
	v_exp_f32_e32 v124, v124
	v_exp_f32_e32 v125, v125
	v_mul_f32_e32 v126, v126, v184
	v_mul_f32_e32 v127, v127, v184
	v_mul_f32_e32 v122, v122, v184
	v_mul_f32_e32 v123, v123, v184
	v_exp_f32_e32 v120, v120
	v_exp_f32_e32 v121, v121
	v_mul_f32_e32 v126, 0xbfb8aa3b, v126
	v_mul_f32_e32 v127, 0xbfb8aa3b, v127
	v_mul_f32_e32 v122, 0xbfb8aa3b, v122
	v_mul_f32_e32 v123, 0xbfb8aa3b, v123
	v_exp_f32_e32 v126, v126
	v_exp_f32_e32 v127, v127
	v_exp_f32_e32 v122, v122
	v_exp_f32_e32 v123, v123
	v_add_f32_e32 v124, 1.0, v124
	v_add_f32_e32 v125, 1.0, v125
	v_add_f32_e32 v181, 1.0, v120
	v_add_f32_e32 v185, 1.0, v121
	v_rcp_f32_e32 v120, v124
	v_rcp_f32_e32 v121, v125
	v_add_f32_e32 v126, 1.0, v126
	v_add_f32_e32 v127, 1.0, v127
	v_add_f32_e32 v210, 1.0, v122
	v_add_f32_e32 v211, 1.0, v123
	v_lshlrev_b32_e32 v202, 16, v182
	v_and_b32_e32 v203, 0xffff0000, v182
	v_rcp_f32_e32 v122, v126
	v_rcp_f32_e32 v123, v127
	v_rcp_f32_e32 v208, v181
	v_rcp_f32_e32 v209, v185
	v_rcp_f32_e32 v210, v210
	v_rcp_f32_e32 v211, v211
	v_pk_fma_f32 v[124:125], v[120:121], v[202:203], v[190:191]
	v_mov_b32_e32 v190, 0
	v_mul_f32_e32 v181, 0x41000000, v124
	v_mul_f32_e32 v185, 0x41000000, v125
	v_lshlrev_b32_e32 v182, 16, v183
	v_and_b32_e32 v183, 0xffff0000, v183
	v_cvt_pk_fp8_f32 v190, v181, v185
	v_pk_fma_f32 v[126:127], v[122:123], v[182:183], v[192:193]
	v_pk_fma_f32 v[120:121], v[208:209], v[204:205], v[186:187]
	v_pk_fma_f32 v[122:123], v[210:211], v[206:207], v[188:189]
	v_cvt_pk_bf16_f32 v186, v124, v125
	v_cvt_pk_bf16_f32 v187, v126, v127
	v_cvt_pk_bf16_f32 v188, v120, v121
	v_cvt_pk_bf16_f32 v189, v122, v123
	v_lshl_add_u64 v[182:183], s[26:27], 0, v[200:201]
	global_store_dwordx4 v[154:155], v[124:127], off
	global_store_dwordx4 v[154:155], v[120:123], off offset:16
	global_store_dwordx4 v[182:183], v[186:189], off
	v_mul_f32_e32 v181, 0x41000000, v126
	v_mul_f32_e32 v182, 0x41000000, v127
	v_cvt_pk_fp8_f32 v190, v181, v182 op_sel:[0,0,1]
; __device__ __forceinline__ unsigned pk2(float lo, float hi) { f32x2 v = {lo, hi}; bf16x2_t b = __builtin_convertvector(v, bf16x2_t); return __builtin_bit_cast(unsigned, b); }
;     __device__ __forceinline__ void operator()(const f32x4 (&acc)[2][2][4][2], const Unit& u, int wr, int wc, int fr, int fq) const {
;     ...
;               for (int mh = 0; mh < 2; ++mh) { f32x4 x0[2], x1[2]; u32x4 tw[2];
; #pragma unroll
;                 for (int mm = 0; mm < 2; ++mm) { const int m = 2 * mh + mm; const size_t o = (size_t)(row0 + ai * HALF + m * 16) * DM + col0 + bj * HALF; x0[mm] = *(const f32x4*)(X1 + o); x1[mm] = *(const f32x4*)(X1 + o + 4); tw[mm] = *(const u32x4*)(T + o); }
; #pragma unroll
;                 for (int mm = 0; mm < 2; ++mm) { const int m = 2 * mh + mm; const size_t o = (size_t)(row0 + ai * HALF + m * 16) * DM + col0 + bj * HALF;
;                     const float rs = rsqrtf(rsv[ai][m] * (1.f / DM) + EPS);
;                     const f32x4 a0 = acc[ai][bj][m][0], a1 = acc[ai][bj][m][1]; f32x4 v0 = x0[mm], v1 = x1[mm];
;                     v0[0] += sigm(a0[0] * rs) * bf_lo(tw[mm].x); v0[1] += sigm(a0[1] * rs) * bf_hi(tw[mm].x); v0[2] += sigm(a0[2] * rs) * bf_lo(tw[mm].y); v0[3] += sigm(a0[3] * rs) * bf_hi(tw[mm].y);
;                     v1[0] += sigm(a1[0] * rs) * bf_lo(tw[mm].z); v1[1] += sigm(a1[1] * rs) * bf_hi(tw[mm].z); v1[2] += sigm(a1[2] * rs) * bf_lo(tw[mm].w); v1[3] += sigm(a1[3] * rs) * bf_hi(tw[mm].w);
;                     *(f32x4*)(xout + o) = v0; *(f32x4*)(xout + o + 4) = v1;
;                     if (wxb) { u32x4 w; w.x = pk2(v0[0], v0[1]); w.y = pk2(v0[2], v0[3]); w.z = pk2(v1[0], v1[1]); w.w = pk2(v1[2], v1[3]); *(u32x4*)(XB + o) = w;
;                         int q0 = 0, q1 = 0; q0 = __builtin_amdgcn_cvt_pk_fp8_f32(v0[0] * 8.f, v0[1] * 8.f, q0, false); q0 = __builtin_amdgcn_cvt_pk_fp8_f32(v0[2] * 8.f, v0[3] * 8.f, q0, true);
;                         q1 = __builtin_amdgcn_cvt_pk_fp8_f32(v1[0] * 8.f, v1[1] * 8.f, q1, false); q1 = __builtin_amdgcn_cvt_pk_fp8_f32(v1[2] * 8.f, v1[3] * 8.f, q1, true);
;                         *(u32x2*)(XB8 + o) = (u32x2){(unsigned)q0, (unsigned)q1}; }
;                     s[m] += (v0[0] * v0[0] + v0[1] * v0[1]) + (v0[2] * v0[2] + v0[3] * v0[3]) + (v1[0] * v1[0] + v1[1] * v1[1]) + (v1[2] * v1[2] + v1[3] * v1[3]); } }
	v_mul_f32_e32 v181, 0x41000000, v120
	v_mul_f32_e32 v182, 0x41000000, v121
	v_mov_b32_e32 v191, 0
	v_cvt_pk_fp8_f32 v191, v181, v182
	v_fmamk_f32 v182, v212, 0x3a000000, v175
	v_mul_f32_e32 v183, 0x4b800000, v182
	v_cmp_gt_f32_e32 vcc, s49, v182
	v_mul_f32_e32 v181, 0x41000000, v122
	v_lshl_add_u64 v[186:187], s[28:29], 0, v[198:199]
	v_cndmask_b32_e32 v182, v182, v183, vcc
	v_rsq_f32_e32 v182, v182
	v_mul_f32_e32 v183, 0x41000000, v123
	v_cvt_pk_fp8_f32 v191, v181, v183 op_sel:[0,0,1]
	v_mul_f32_e32 v94, v94, v184
	v_mul_f32_e32 v181, 0x45800000, v182
	v_cndmask_b32_e32 v182, v182, v181, vcc
	v_mul_f32_e32 v116, v116, v182
	v_mul_f32_e32 v117, v117, v182
	v_mul_f32_e32 v118, v118, v182
	v_mul_f32_e32 v119, v119, v182
	v_mul_f32_e32 v116, 0xbfb8aa3b, v116
	v_mul_f32_e32 v117, 0xbfb8aa3b, v117
	v_mul_f32_e32 v118, 0xbfb8aa3b, v118
	v_mul_f32_e32 v119, 0xbfb8aa3b, v119
	v_mul_f32_e32 v112, v112, v182
	v_mul_f32_e32 v113, v113, v182
	v_exp_f32_e32 v116, v116
	v_exp_f32_e32 v117, v117
	v_exp_f32_e32 v118, v118
	v_exp_f32_e32 v119, v119
	v_mul_f32_e32 v112, 0xbfb8aa3b, v112
	v_mul_f32_e32 v113, 0xbfb8aa3b, v113
	v_exp_f32_e32 v112, v112
	v_exp_f32_e32 v113, v113
	v_mul_f32_e32 v114, v114, v182
	v_mul_f32_e32 v115, v115, v182
	v_add_f32_e32 v116, 1.0, v116
	v_add_f32_e32 v117, 1.0, v117
	v_add_f32_e32 v118, 1.0, v118
	v_add_f32_e32 v119, 1.0, v119
	v_mul_f32_e32 v114, 0xbfb8aa3b, v114
	v_mul_f32_e32 v115, 0xbfb8aa3b, v115
	v_rcp_f32_e32 v116, v116
	v_rcp_f32_e32 v117, v117
	v_rcp_f32_e32 v118, v118
	v_rcp_f32_e32 v119, v119
	v_add_f32_e32 v112, 1.0, v112
	v_add_f32_e32 v113, 1.0, v113
	v_exp_f32_e32 v114, v114
	v_exp_f32_e32 v115, v115
	v_rcp_f32_e32 v112, v112
	v_rcp_f32_e32 v113, v113
	global_store_dwordx2 v[186:187], v[190:191], off
	v_lshlrev_b32_e32 v186, 16, v132
	v_and_b32_e32 v187, 0xffff0000, v132
	v_lshlrev_b32_e32 v132, 16, v133
	v_and_b32_e32 v133, 0xffff0000, v133
	v_pk_fma_f32 v[116:117], v[116:117], v[186:187], v[194:195]
	v_pk_fma_f32 v[118:119], v[118:119], v[132:133], v[196:197]
	v_lshlrev_b32_e32 v132, 16, v134
	v_and_b32_e32 v133, 0xffff0000, v134
	v_add_f32_e32 v114, 1.0, v114
	v_add_f32_e32 v115, 1.0, v115
	v_rcp_f32_e32 v114, v114
	v_rcp_f32_e32 v115, v115
	v_pk_fma_f32 v[112:113], v[112:113], v[132:133], v[128:129]
	v_lshlrev_b32_e32 v128, 16, v135
	v_and_b32_e32 v129, 0xffff0000, v135
	v_lshl_add_u64 v[134:135], s[8:9], 0, v[160:161]
	v_mul_f32_e32 v133, 0x41000000, v116
	v_mul_f32_e32 v160, 0x41000000, v117
	v_mov_b32_e32 v132, 0
	v_cvt_pk_fp8_f32 v132, v133, v160
	v_mul_f32_e32 v181, 0x41000000, v112
	v_mul_f32_e32 v183, 0x41000000, v113
	v_mov_b32_e32 v133, 0
	v_cvt_pk_fp8_f32 v133, v181, v183
	v_pk_fma_f32 v[114:115], v[114:115], v[128:129], v[130:131]
	v_mul_f32_e32 v160, 0x41000000, v118
	v_mul_f32_e32 v161, 0x41000000, v119
	v_cvt_pk_fp8_f32 v132, v160, v161 op_sel:[0,0,1]
	v_mul_f32_e32 v160, 0x41000000, v114
	v_mul_f32_e32 v161, 0x41000000, v115
	v_cvt_pk_bf16_f32 v128, v116, v117
	v_cvt_pk_bf16_f32 v129, v118, v119
	v_cvt_pk_bf16_f32 v130, v112, v113
	v_cvt_pk_bf16_f32 v131, v114, v115
	v_cvt_pk_fp8_f32 v133, v160, v161 op_sel:[0,0,1]
	global_store_dwordx4 v[134:135], v[116:119], off
	global_store_dwordx4 v[134:135], v[112:115], off offset:16
	global_store_dwordx4 v[158:159], v[128:131], off
	v_lshlrev_b64 v[158:159], 11, v[146:147]
	v_fmamk_f32 v160, v214, 0x3a000000, v175
	v_lshl_add_u64 v[128:129], s[28:29], 0, v[156:157]
	v_lshl_add_u64 v[156:157], v[158:159], 0, v[142:143]
	v_lshlrev_b64 v[210:211], 1, v[156:157]
	global_store_dwordx2 v[128:129], v[132:133], off
	v_lshl_add_u64 v[128:129], s[22:23], 0, v[210:211]
	s_nop 0
	v_lshlrev_b64 v[132:133], 2, v[156:157]
	v_lshl_add_u64 v[128:129], s[20:21], 0, v[132:133]
	s_nop 0
	s_nop 0
	v_lshlrev_b64 v[130:131], 11, v[144:145]
	v_mul_f32_e32 v161, 0x4b800000, v160
	v_cmp_gt_f32_e32 vcc, s49, v160
	v_lshl_add_u64 v[128:129], v[130:131], 0, v[142:143]
	v_lshlrev_b64 v[212:213], 2, v[128:129]
	v_cndmask_b32_e32 v160, v160, v161, vcc
	v_rsq_f32_e32 v181, v160
	v_lshlrev_b64 v[160:161], 1, v[128:129]
	v_lshl_add_u64 v[202:203], s[20:21], 0, v[212:213]
	v_lshl_add_u64 v[206:207], s[22:23], 0, v[160:161]
	s_nop 0
	s_nop 0
	s_nop 0
	s_nop 0
	s_nop 0
	v_mul_f32_e32 v183, 0x45800000, v181
	v_cndmask_b32_e32 v181, v181, v183, vcc
	v_mul_f32_e32 v108, v108, v181
	v_mul_f32_e32 v109, v109, v181
	v_mul_f32_e32 v108, 0xbfb8aa3b, v108
	v_mul_f32_e32 v109, 0xbfb8aa3b, v109
	v_mul_f32_e32 v110, v110, v181
	v_mul_f32_e32 v111, v111, v181
	v_exp_f32_e32 v108, v108
	v_exp_f32_e32 v109, v109
	v_mul_f32_e32 v110, 0xbfb8aa3b, v110
	v_mul_f32_e32 v111, 0xbfb8aa3b, v111
	v_exp_f32_e32 v110, v110
	v_exp_f32_e32 v111, v111
	v_mul_f32_e32 v104, v104, v181
	v_mul_f32_e32 v105, v105, v181
	v_add_f32_e32 v108, 1.0, v108
	v_add_f32_e32 v109, 1.0, v109
	v_mul_f32_e32 v104, 0xbfb8aa3b, v104
	v_mul_f32_e32 v105, 0xbfb8aa3b, v105
	v_mul_f32_e32 v106, v106, v181
	v_mul_f32_e32 v107, v107, v181
	v_rcp_f32_e32 v108, v108
	v_rcp_f32_e32 v109, v109
	v_add_f32_e32 v110, 1.0, v110
	v_add_f32_e32 v111, 1.0, v111
	v_exp_f32_e32 v104, v104
	v_exp_f32_e32 v105, v105
	v_mul_f32_e32 v106, 0xbfb8aa3b, v106
	v_mul_f32_e32 v107, 0xbfb8aa3b, v107
	v_rcp_f32_e32 v110, v110
	v_rcp_f32_e32 v111, v111
	v_exp_f32_e32 v106, v106
	v_exp_f32_e32 v107, v107
	v_add_f32_e32 v104, 1.0, v104
	v_add_f32_e32 v105, 1.0, v105
	v_rcp_f32_e32 v104, v104
	v_rcp_f32_e32 v105, v105
	v_add_f32_e32 v106, 1.0, v106
	v_add_f32_e32 v107, 1.0, v107
	v_rcp_f32_e32 v106, v106
	v_rcp_f32_e32 v107, v107
	v_lshl_add_u64 v[132:133], s[8:9], 0, v[132:133]
	v_lshl_add_u64 v[156:157], s[28:29], 0, v[156:157]
	v_lshl_add_u64 v[160:161], s[26:27], 0, v[160:161]
	v_lshl_add_u64 v[128:129], s[28:29], 0, v[128:129]
	v_mul_f32_e32 v95, v95, v184
	v_mul_f32_e32 v92, v92, v184
	v_mul_f32_e32 v93, v93, v184
	v_mul_f32_e32 v94, 0xbfb8aa3b, v94
	v_mul_f32_e32 v95, 0xbfb8aa3b, v95
	v_mul_f32_e32 v88, v88, v184
	v_mul_f32_e32 v89, v89, v184
	v_mul_f32_e32 v90, v90, v184
	v_mul_f32_e32 v91, v91, v184
	v_mul_f32_e32 v92, 0xbfb8aa3b, v92
	v_mul_f32_e32 v93, 0xbfb8aa3b, v93
	v_exp_f32_e32 v94, v94
	v_exp_f32_e32 v95, v95
	v_mul_f32_e32 v88, 0xbfb8aa3b, v88
	v_mul_f32_e32 v89, 0xbfb8aa3b, v89
	v_mul_f32_e32 v90, 0xbfb8aa3b, v90
	v_mul_f32_e32 v91, 0xbfb8aa3b, v91
	v_exp_f32_e32 v92, v92
	s_waitcnt vmcnt(13)
; __device__ __forceinline__ float bf_lo(unsigned u) { return __uint_as_float(u << 16); }
;     __device__ __forceinline__ void operator()(const f32x4 (&acc)[2][2][4][2], const Unit& u, int wr, int wc, int fr, int fq) const {
;     ...
;         for (int ai = 0; ai < 2; ++ai) { float s[4] = {0.f, 0.f, 0.f, 0.f};
; #pragma unroll
;             for (int bj = 0; bj < 2; ++bj)
; #pragma unroll
;               for (int mh = 0; mh < 2; ++mh) { f32x4 x0[2], x1[2]; u32x4 tw[2];
; #pragma unroll
;                 for (int mm = 0; mm < 2; ++mm) { const int m = 2 * mh + mm; const size_t o = (size_t)(row0 + ai * HALF + m * 16) * DM + col0 + bj * HALF; x0[mm] = *(const f32x4*)(X1 + o); x1[mm] = *(const f32x4*)(X1 + o + 4); tw[mm] = *(const u32x4*)(T + o); }
; #pragma unroll
;                 for (int mm = 0; mm < 2; ++mm) { const int m = 2 * mh + mm; const size_t o = (size_t)(row0 + ai * HALF + m * 16) * DM + col0 + bj * HALF;
;                     const float rs = rsqrtf(rsv[ai][m] * (1.f / DM) + EPS);
;                     const f32x4 a0 = acc[ai][bj][m][0], a1 = acc[ai][bj][m][1]; f32x4 v0 = x0[mm], v1 = x1[mm];
;                     v0[0] += sigm(a0[0] * rs) * bf_lo(tw[mm].x); v0[1] += sigm(a0[1] * rs) * bf_hi(tw[mm].x); v0[2] += sigm(a0[2] * rs) * bf_lo(tw[mm].y); v0[3] += sigm(a0[3] * rs) * bf_hi(tw[mm].y);
;                     v1[0] += sigm(a1[0] * rs) * bf_lo(tw[mm].z); v1[1] += sigm(a1[1] * rs) * bf_hi(tw[mm].z); v1[2] += sigm(a1[2] * rs) * bf_lo(tw[mm].w); v1[3] += sigm(a1[3] * rs) * bf_hi(tw[mm].w);
;                     *(f32x4*)(xout + o) = v0; *(f32x4*)(xout + o + 4) = v1;
;                     if (wxb) { u32x4 w; w.x = pk2(v0[0], v0[1]); w.y = pk2(v0[2], v0[3]); w.z = pk2(v1[0], v1[1]); w.w = pk2(v1[2], v1[3]); *(u32x4*)(XB + o) = w;
;                         int q0 = 0, q1 = 0; q0 = __builtin_amdgcn_cvt_pk_fp8_f32(v0[0] * 8.f, v0[1] * 8.f, q0, false); q0 = __builtin_amdgcn_cvt_pk_fp8_f32(v0[2] * 8.f, v0[3] * 8.f, q0, true);
;                         q1 = __builtin_amdgcn_cvt_pk_fp8_f32(v1[0] * 8.f, v1[1] * 8.f, q1, false); q1 = __builtin_amdgcn_cvt_pk_fp8_f32(v1[2] * 8.f, v1[3] * 8.f, q1, true);
;                         *(u32x2*)(XB8 + o) = (u32x2){(unsigned)q0, (unsigned)q1}; }
;                     s[m] += (v0[0] * v0[0] + v0[1] * v0[1]) + (v0[2] * v0[2] + v0[3] * v0[3]) + (v1[0] * v1[0] + v1[1] * v1[1]) + (v1[2] * v1[2] + v1[3] * v1[3]); } }
	v_lshlrev_b32_e32 v214, 16, v218
	v_and_b32_e32 v215, 0xffff0000, v218
	s_waitcnt vmcnt(12)
	v_pk_fma_f32 v[108:109], v[108:109], v[214:215], v[222:223]
	v_lshlrev_b32_e32 v186, 16, v219
	v_and_b32_e32 v187, 0xffff0000, v219
	v_pk_fma_f32 v[110:111], v[110:111], v[186:187], v[224:225]
	v_mul_f32_e32 v183, 0x41000000, v108
	v_mul_f32_e32 v185, 0x41000000, v109
	v_mov_b32_e32 v192, 0
	v_cvt_pk_fp8_f32 v192, v183, v185
	v_lshlrev_b32_e32 v186, 16, v220
	v_and_b32_e32 v187, 0xffff0000, v220
	s_waitcnt vmcnt(11)
	v_pk_fma_f32 v[104:105], v[104:105], v[186:187], v[226:227]
	v_lshlrev_b32_e32 v186, 16, v221
	v_and_b32_e32 v187, 0xffff0000, v221
	v_mul_f32_e32 v183, 0x41000000, v110
	v_mul_f32_e32 v185, 0x41000000, v111
	v_pk_fma_f32 v[106:107], v[106:107], v[186:187], v[228:229]
	v_cvt_pk_fp8_f32 v192, v183, v185 op_sel:[0,0,1]
	v_mul_f32_e32 v183, 0x41000000, v104
	v_mul_f32_e32 v185, 0x41000000, v105
	v_mov_b32_e32 v193, 0
	v_cvt_pk_bf16_f32 v186, v108, v109
	v_cvt_pk_bf16_f32 v187, v110, v111
	v_cvt_pk_bf16_f32 v188, v104, v105
	v_cvt_pk_bf16_f32 v189, v106, v107
	v_lshl_add_u64 v[190:191], s[26:27], 0, v[210:211]
	v_cvt_pk_fp8_f32 v193, v183, v185
	v_fmamk_f32 v185, v216, 0x3a000000, v175
	global_store_dwordx4 v[132:133], v[108:111], off
	global_store_dwordx4 v[132:133], v[104:107], off offset:16
	global_store_dwordx4 v[190:191], v[186:189], off
	v_cmp_gt_f32_e32 vcc, s49, v185
	v_mul_f32_e32 v183, 0x41000000, v106
	v_mul_f32_e32 v186, 0x4b800000, v185
	v_cndmask_b32_e32 v185, v185, v186, vcc
	v_rsq_f32_e32 v185, v185
	v_mul_f32_e32 v186, 0x41000000, v107
	v_cvt_pk_fp8_f32 v193, v183, v186 op_sel:[0,0,1]
	v_mov_b32_e32 v190, 0
	v_mul_f32_e32 v183, 0x45800000, v185
	v_cndmask_b32_e32 v183, v185, v183, vcc
	v_mul_f32_e32 v100, v100, v183
	v_mul_f32_e32 v101, v101, v183
	v_mul_f32_e32 v100, 0xbfb8aa3b, v100
	v_mul_f32_e32 v101, 0xbfb8aa3b, v101
	v_mul_f32_e32 v102, v102, v183
	v_mul_f32_e32 v103, v103, v183
	v_exp_f32_e32 v100, v100
	v_exp_f32_e32 v101, v101
	v_mul_f32_e32 v102, 0xbfb8aa3b, v102
	v_mul_f32_e32 v103, 0xbfb8aa3b, v103
	v_mul_f32_e32 v96, v96, v183
	v_mul_f32_e32 v97, v97, v183
	v_exp_f32_e32 v102, v102
	v_exp_f32_e32 v103, v103
	v_mul_f32_e32 v96, 0xbfb8aa3b, v96
	v_mul_f32_e32 v97, 0xbfb8aa3b, v97
	v_exp_f32_e32 v96, v96
	v_exp_f32_e32 v97, v97
	v_add_f32_e32 v100, 1.0, v100
	v_add_f32_e32 v101, 1.0, v101
	v_mul_f32_e32 v98, v98, v183
	v_mul_f32_e32 v99, v99, v183
	v_rcp_f32_e32 v100, v100
	v_rcp_f32_e32 v101, v101
	v_add_f32_e32 v102, 1.0, v102
	v_add_f32_e32 v103, 1.0, v103
	v_mul_f32_e32 v98, 0xbfb8aa3b, v98
	v_mul_f32_e32 v99, 0xbfb8aa3b, v99
	v_rcp_f32_e32 v102, v102
	v_rcp_f32_e32 v103, v103
	v_add_f32_e32 v96, 1.0, v96
	v_add_f32_e32 v97, 1.0, v97
	v_exp_f32_e32 v98, v98
	v_exp_f32_e32 v99, v99
	v_rcp_f32_e32 v96, v96
	v_rcp_f32_e32 v97, v97
	global_store_dwordx2 v[156:157], v[192:193], off
	s_waitcnt vmcnt(12)
	v_lshlrev_b32_e32 v156, 16, v238
	v_and_b32_e32 v157, 0xffff0000, v238
	v_pk_fma_f32 v[100:101], v[100:101], v[156:157], v[230:231]
	v_lshlrev_b32_e32 v156, 16, v239
	v_and_b32_e32 v157, 0xffff0000, v239
	v_pk_fma_f32 v[102:103], v[102:103], v[156:157], v[232:233]
	v_lshlrev_b32_e32 v156, 16, v240
	v_and_b32_e32 v157, 0xffff0000, v240
	v_add_f32_e32 v98, 1.0, v98
	v_add_f32_e32 v99, 1.0, v99
	v_rcp_f32_e32 v98, v98
	v_rcp_f32_e32 v99, v99
	v_pk_fma_f32 v[96:97], v[96:97], v[156:157], v[234:235]
	v_mul_f32_e32 v185, 0x41000000, v100
	v_mul_f32_e32 v191, 0x41000000, v101
	v_cvt_pk_fp8_f32 v190, v185, v191
	v_mul_f32_e32 v193, 0x41000000, v96
	v_mul_f32_e32 v194, 0x41000000, v97
	v_mov_b32_e32 v191, 0
	v_cvt_pk_fp8_f32 v191, v193, v194
	v_lshlrev_b32_e32 v156, 16, v241
	v_and_b32_e32 v157, 0xffff0000, v241
	v_pk_fma_f32 v[98:99], v[98:99], v[156:157], v[236:237]
	v_mul_f32_e32 v185, 0x41000000, v102
	v_mul_f32_e32 v192, 0x41000000, v103
	v_cvt_pk_fp8_f32 v190, v185, v192 op_sel:[0,0,1]
	v_mul_f32_e32 v185, 0x41000000, v98
	v_mul_f32_e32 v192, 0x41000000, v99
	v_cvt_pk_fp8_f32 v191, v185, v192 op_sel:[0,0,1]
	v_lshl_add_u64 v[156:157], s[8:9], 0, v[212:213]
	v_cvt_pk_bf16_f32 v186, v100, v101
	v_cvt_pk_bf16_f32 v187, v102, v103
	v_cvt_pk_bf16_f32 v188, v96, v97
	v_cvt_pk_bf16_f32 v189, v98, v99
	global_store_dwordx4 v[156:157], v[100:103], off
	global_store_dwordx4 v[156:157], v[96:99], off offset:16
	global_store_dwordx4 v[160:161], v[186:189], off
	global_store_dwordx2 v[128:129], v[190:191], off
	v_lshl_add_u64 v[128:129], v[142:143], 0, s[34:35]
	v_lshl_add_u64 v[160:161], v[128:129], 0, v[150:151]
	v_lshlrev_b64 v[210:211], 1, v[160:161]
	v_lshl_add_u64 v[150:151], s[22:23], 0, v[210:211]
	global_load_dwordx4 v[186:189], v[150:151], off
	v_lshl_add_u64 v[150:151], v[160:161], 2, s[20:21]
	global_load_dwordx4 v[190:193], v[150:151], off
	global_load_dwordx4 v[194:197], v[150:151], off offset:16
	v_lshl_add_u64 v[150:151], v[128:129], 0, v[152:153]
	v_lshlrev_b64 v[152:153], 1, v[150:151]
	v_lshl_add_u64 v[202:203], v[150:151], 2, s[20:21]
	v_lshl_add_u64 v[206:207], s[22:23], 0, v[152:153]
	global_load_dwordx4 v[198:201], v[202:203], off
	s_nop 0
	global_load_dwordx4 v[202:205], v[202:203], off offset:16
	s_nop 0
	global_load_dwordx4 v[206:209], v[206:207], off
	v_exp_f32_e32 v93, v93
	v_exp_f32_e32 v88, v88
	v_exp_f32_e32 v89, v89
	v_exp_f32_e32 v90, v90
	v_exp_f32_e32 v91, v91
	v_add_f32_e32 v94, 1.0, v94
	v_add_f32_e32 v95, 1.0, v95
	v_add_f32_e32 v92, 1.0, v92
	v_add_f32_e32 v93, 1.0, v93
	v_rcp_f32_e32 v94, v94
	v_rcp_f32_e32 v95, v95
	v_add_f32_e32 v88, 1.0, v88
	v_add_f32_e32 v89, 1.0, v89
	v_add_f32_e32 v90, 1.0, v90
	v_add_f32_e32 v91, 1.0, v91
	v_rcp_f32_e32 v92, v92
	v_rcp_f32_e32 v93, v93
; __device__ __forceinline__ float bf_lo(unsigned u) { return __uint_as_float(u << 16); }
;     __device__ __forceinline__ void operator()(const f32x4 (&acc)[2][2][4][2], const Unit& u, int wr, int wc, int fr, int fq) const {
;     ...
;         for (int ai = 0; ai < 2; ++ai) { float s[4] = {0.f, 0.f, 0.f, 0.f};
; #pragma unroll
;             for (int bj = 0; bj < 2; ++bj)
; #pragma unroll
;               for (int mh = 0; mh < 2; ++mh) { f32x4 x0[2], x1[2]; u32x4 tw[2];
; #pragma unroll
;                 for (int mm = 0; mm < 2; ++mm) { const int m = 2 * mh + mm; const size_t o = (size_t)(row0 + ai * HALF + m * 16) * DM + col0 + bj * HALF; x0[mm] = *(const f32x4*)(X1 + o); x1[mm] = *(const f32x4*)(X1 + o + 4); tw[mm] = *(const u32x4*)(T + o); }
; #pragma unroll
;                 for (int mm = 0; mm < 2; ++mm) { const int m = 2 * mh + mm; const size_t o = (size_t)(row0 + ai * HALF + m * 16) * DM + col0 + bj * HALF;
;                     const float rs = rsqrtf(rsv[ai][m] * (1.f / DM) + EPS);
;                     const f32x4 a0 = acc[ai][bj][m][0], a1 = acc[ai][bj][m][1]; f32x4 v0 = x0[mm], v1 = x1[mm];
;                     v0[0] += sigm(a0[0] * rs) * bf_lo(tw[mm].x); v0[1] += sigm(a0[1] * rs) * bf_hi(tw[mm].x); v0[2] += sigm(a0[2] * rs) * bf_lo(tw[mm].y); v0[3] += sigm(a0[3] * rs) * bf_hi(tw[mm].y);
;                     v1[0] += sigm(a1[0] * rs) * bf_lo(tw[mm].z); v1[1] += sigm(a1[1] * rs) * bf_hi(tw[mm].z); v1[2] += sigm(a1[2] * rs) * bf_lo(tw[mm].w); v1[3] += sigm(a1[3] * rs) * bf_hi(tw[mm].w);
;                     *(f32x4*)(xout + o) = v0; *(f32x4*)(xout + o + 4) = v1;
;                     if (wxb) { u32x4 w; w.x = pk2(v0[0], v0[1]); w.y = pk2(v0[2], v0[3]); w.z = pk2(v1[0], v1[1]); w.w = pk2(v1[2], v1[3]); *(u32x4*)(XB + o) = w;
;                         int q0 = 0, q1 = 0; q0 = __builtin_amdgcn_cvt_pk_fp8_f32(v0[0] * 8.f, v0[1] * 8.f, q0, false); q0 = __builtin_amdgcn_cvt_pk_fp8_f32(v0[2] * 8.f, v0[3] * 8.f, q0, true);
;                         q1 = __builtin_amdgcn_cvt_pk_fp8_f32(v1[0] * 8.f, v1[1] * 8.f, q1, false); q1 = __builtin_amdgcn_cvt_pk_fp8_f32(v1[2] * 8.f, v1[3] * 8.f, q1, true);
;                         *(u32x2*)(XB8 + o) = (u32x2){(unsigned)q0, (unsigned)q1}; }
;                     s[m] += (v0[0] * v0[0] + v0[1] * v0[1]) + (v0[2] * v0[2] + v0[3] * v0[3]) + (v1[0] * v1[0] + v1[1] * v1[1]) + (v1[2] * v1[2] + v1[3] * v1[3]); } }
; #pragma unroll
	v_rcp_f32_e32 v88, v88
	v_rcp_f32_e32 v89, v89
	v_rcp_f32_e32 v90, v90
	v_rcp_f32_e32 v91, v91
	v_mul_f32_e32 v84, v84, v182
	v_mul_f32_e32 v85, v85, v182
	v_mul_f32_e32 v84, 0xbfb8aa3b, v84
	v_mul_f32_e32 v85, 0xbfb8aa3b, v85
	v_mul_f32_e32 v86, v86, v182
	v_mul_f32_e32 v87, v87, v182
	v_exp_f32_e32 v84, v84
	v_exp_f32_e32 v85, v85
	v_mul_f32_e32 v86, 0xbfb8aa3b, v86
	v_mul_f32_e32 v87, 0xbfb8aa3b, v87
	v_mul_f32_e32 v80, v80, v182
	v_mul_f32_e32 v81, v81, v182
	v_exp_f32_e32 v86, v86
	v_exp_f32_e32 v87, v87
	v_mul_f32_e32 v80, 0xbfb8aa3b, v80
	v_mul_f32_e32 v81, 0xbfb8aa3b, v81
	v_mul_f32_e32 v82, v82, v182
	v_mul_f32_e32 v83, v83, v182
	v_exp_f32_e32 v80, v80
	v_exp_f32_e32 v81, v81
	v_mul_f32_e32 v82, 0xbfb8aa3b, v82
	v_mul_f32_e32 v83, 0xbfb8aa3b, v83
	v_exp_f32_e32 v82, v82
	v_exp_f32_e32 v83, v83
	v_add_f32_e32 v84, 1.0, v84
	v_add_f32_e32 v85, 1.0, v85
	v_rcp_f32_e32 v84, v84
	v_rcp_f32_e32 v85, v85
	v_add_f32_e32 v86, 1.0, v86
	v_add_f32_e32 v87, 1.0, v87
	v_rcp_f32_e32 v86, v86
	v_rcp_f32_e32 v87, v87
	v_add_f32_e32 v80, 1.0, v80
	v_add_f32_e32 v81, 1.0, v81
	v_lshl_add_u64 v[160:161], s[28:29], 0, v[160:161]
	v_rcp_f32_e32 v80, v80
	v_rcp_f32_e32 v81, v81
	v_add_f32_e32 v82, 1.0, v82
	v_add_f32_e32 v83, 1.0, v83
	v_rcp_f32_e32 v82, v82
	v_rcp_f32_e32 v83, v83
	v_lshl_add_u64 v[152:153], s[26:27], 0, v[152:153]
	v_lshl_add_u64 v[150:151], s[28:29], 0, v[150:151]
	v_pk_mul_f32 v[124:125], v[124:125], v[124:125]
	v_pk_mul_f32 v[126:127], v[126:127], v[126:127]
	v_pk_mul_f32 v[120:121], v[120:121], v[120:121]
	v_add_f32_e32 v126, v126, v127
	v_add_f32_e32 v124, v124, v125
	v_pk_mul_f32 v[122:123], v[122:123], v[122:123]
	v_add_f32_e32 v124, v124, v126
	v_lshl_add_u64 v[242:243], v[128:129], 0, v[158:159]
	v_lshlrev_b64 v[244:245], 1, v[242:243]
	v_lshl_add_u64 v[246:247], s[22:23], 0, v[244:245]
	global_load_dwordx4 v[218:221], v[246:247], off
	v_lshl_add_u64 v[244:245], v[242:243], 2, s[20:21]
	global_load_dwordx4 v[222:225], v[244:245], off
	global_load_dwordx4 v[226:229], v[244:245], off offset:16
	v_lshl_add_u64 v[242:243], v[128:129], 0, v[130:131]
	v_lshlrev_b64 v[244:245], 1, v[242:243]
	v_lshl_add_u64 v[246:247], v[242:243], 2, s[20:21]
	v_lshl_add_u64 v[250:251], s[22:23], 0, v[244:245]
	global_load_dwordx4 v[230:233], v[246:247], off
	global_load_dwordx4 v[234:237], v[246:247], off offset:16
	global_load_dwordx4 v[238:241], v[250:251], off
	s_waitcnt vmcnt(11)
	v_lshlrev_b32_e32 v212, 16, v186
	v_and_b32_e32 v213, 0xffff0000, v186
	v_lshlrev_b32_e32 v186, 16, v187
	v_and_b32_e32 v187, 0xffff0000, v187
	s_waitcnt vmcnt(10)
	v_pk_fma_f32 v[94:95], v[94:95], v[186:187], v[192:193]
	v_lshlrev_b32_e32 v186, 16, v188
	v_and_b32_e32 v187, 0xffff0000, v188
	v_lshlrev_b32_e32 v184, 16, v189
	v_and_b32_e32 v185, 0xffff0000, v189
	v_pk_fma_f32 v[92:93], v[92:93], v[212:213], v[190:191]
	s_waitcnt vmcnt(9)
	v_pk_fma_f32 v[88:89], v[88:89], v[186:187], v[194:195]
	v_pk_fma_f32 v[90:91], v[90:91], v[184:185], v[196:197]
	global_store_dwordx4 v[154:155], v[92:95], off offset:512
	global_store_dwordx4 v[154:155], v[88:91], off offset:528
	v_cvt_pk_bf16_f32 v184, v92, v93
	v_cvt_pk_bf16_f32 v185, v94, v95
	v_cvt_pk_bf16_f32 v186, v88, v89
	v_cvt_pk_bf16_f32 v187, v90, v91
	v_lshl_add_u64 v[154:155], s[26:27], 0, v[210:211]
	global_store_dwordx4 v[154:155], v[184:187], off
	v_mul_f32_e32 v155, 0x41000000, v92
	v_mov_b32_e32 v154, 0
	v_mul_f32_e32 v184, 0x41000000, v93
	v_cvt_pk_fp8_f32 v154, v155, v184
	v_mul_f32_e32 v186, 0x41000000, v88
	v_mul_f32_e32 v187, 0x41000000, v89
	v_mov_b32_e32 v155, 0
	v_cvt_pk_fp8_f32 v155, v186, v187
	v_mul_f32_e32 v184, 0x41000000, v94
	v_mul_f32_e32 v185, 0x41000000, v95
	v_cvt_pk_fp8_f32 v154, v184, v185 op_sel:[0,0,1]
	v_mul_f32_e32 v184, 0x41000000, v90
	v_mul_f32_e32 v185, 0x41000000, v91
	v_cvt_pk_fp8_f32 v155, v184, v185 op_sel:[0,0,1]
	v_pk_mul_f32 v[92:93], v[92:93], v[92:93]
	v_pk_mul_f32 v[94:95], v[94:95], v[94:95]
	v_pk_mul_f32 v[88:89], v[88:89], v[88:89]
	global_store_dwordx2 v[160:161], v[154:155], off
	s_waitcnt vmcnt(10)
	v_lshlrev_b32_e32 v154, 16, v206
	v_and_b32_e32 v155, 0xffff0000, v206
	v_pk_fma_f32 v[84:85], v[84:85], v[154:155], v[198:199]
	v_lshlrev_b32_e32 v154, 16, v207
	v_and_b32_e32 v155, 0xffff0000, v207
	v_pk_fma_f32 v[86:87], v[86:87], v[154:155], v[200:201]
	v_lshlrev_b32_e32 v154, 16, v208
	v_and_b32_e32 v155, 0xffff0000, v208
	v_pk_fma_f32 v[80:81], v[80:81], v[154:155], v[202:203]
	v_lshlrev_b32_e32 v154, 16, v209
	v_and_b32_e32 v155, 0xffff0000, v209
	v_pk_fma_f32 v[82:83], v[82:83], v[154:155], v[204:205]
	global_store_dwordx4 v[134:135], v[84:87], off offset:512
	global_store_dwordx4 v[134:135], v[80:83], off offset:528
	v_mul_f32_e32 v135, 0x41000000, v84
	v_mul_f32_e32 v154, 0x41000000, v85
	v_mov_b32_e32 v134, 0
	v_cvt_pk_fp8_f32 v134, v135, v154
	v_mul_f32_e32 v160, 0x41000000, v80
	v_mul_f32_e32 v161, 0x41000000, v81
	v_mov_b32_e32 v135, 0
	v_cvt_pk_fp8_f32 v135, v160, v161
	v_mul_f32_e32 v154, 0x41000000, v86
	v_mul_f32_e32 v155, 0x41000000, v87
	v_cvt_pk_fp8_f32 v134, v154, v155 op_sel:[0,0,1]
	v_mul_f32_e32 v154, 0x41000000, v82
	v_mul_f32_e32 v155, 0x41000000, v83
	v_cvt_pk_fp8_f32 v135, v154, v155 op_sel:[0,0,1]
	v_cvt_pk_bf16_f32 v184, v84, v85
	v_cvt_pk_bf16_f32 v185, v86, v87
	v_cvt_pk_bf16_f32 v186, v80, v81
	v_cvt_pk_bf16_f32 v187, v82, v83
	global_store_dwordx4 v[152:153], v[184:187], off
	global_store_dwordx2 v[150:151], v[134:135], off
	v_lshl_add_u64 v[134:135], v[128:129], 0, v[158:159]
	v_lshlrev_b64 v[154:155], 1, v[134:135]
	v_lshl_add_u64 v[150:151], s[22:23], 0, v[154:155]
	s_nop 0
	v_lshl_add_u64 v[184:185], v[134:135], 2, s[20:21]
; __device__ __forceinline__ float bf_lo(unsigned u) { return __uint_as_float(u << 16); }
;     __device__ __forceinline__ void operator()(const f32x4 (&acc)[2][2][4][2], const Unit& u, int wr, int wc, int fr, int fq) const {
;     ...
;         for (int ai = 0; ai < 2; ++ai) { float s[4] = {0.f, 0.f, 0.f, 0.f};
; #pragma unroll
;             for (int bj = 0; bj < 2; ++bj)
; #pragma unroll
;               for (int mh = 0; mh < 2; ++mh) { f32x4 x0[2], x1[2]; u32x4 tw[2];
; #pragma unroll
;                 for (int mm = 0; mm < 2; ++mm) { const int m = 2 * mh + mm; const size_t o = (size_t)(row0 + ai * HALF + m * 16) * DM + col0 + bj * HALF; x0[mm] = *(const f32x4*)(X1 + o); x1[mm] = *(const f32x4*)(X1 + o + 4); tw[mm] = *(const u32x4*)(T + o); }
; #pragma unroll
;                 for (int mm = 0; mm < 2; ++mm) { const int m = 2 * mh + mm; const size_t o = (size_t)(row0 + ai * HALF + m * 16) * DM + col0 + bj * HALF;
;                     const float rs = rsqrtf(rsv[ai][m] * (1.f / DM) + EPS);
;                     const f32x4 a0 = acc[ai][bj][m][0], a1 = acc[ai][bj][m][1]; f32x4 v0 = x0[mm], v1 = x1[mm];
;                     v0[0] += sigm(a0[0] * rs) * bf_lo(tw[mm].x); v0[1] += sigm(a0[1] * rs) * bf_hi(tw[mm].x); v0[2] += sigm(a0[2] * rs) * bf_lo(tw[mm].y); v0[3] += sigm(a0[3] * rs) * bf_hi(tw[mm].y);
;                     v1[0] += sigm(a1[0] * rs) * bf_lo(tw[mm].z); v1[1] += sigm(a1[1] * rs) * bf_hi(tw[mm].z); v1[2] += sigm(a1[2] * rs) * bf_lo(tw[mm].w); v1[3] += sigm(a1[3] * rs) * bf_hi(tw[mm].w);
;                     *(f32x4*)(xout + o) = v0; *(f32x4*)(xout + o + 4) = v1;
;                     if (wxb) { u32x4 w; w.x = pk2(v0[0], v0[1]); w.y = pk2(v0[2], v0[3]); w.z = pk2(v1[0], v1[1]); w.w = pk2(v1[2], v1[3]); *(u32x4*)(XB + o) = w;
;                         int q0 = 0, q1 = 0; q0 = __builtin_amdgcn_cvt_pk_fp8_f32(v0[0] * 8.f, v0[1] * 8.f, q0, false); q0 = __builtin_amdgcn_cvt_pk_fp8_f32(v0[2] * 8.f, v0[3] * 8.f, q0, true);
;                         q1 = __builtin_amdgcn_cvt_pk_fp8_f32(v1[0] * 8.f, v1[1] * 8.f, q1, false); q1 = __builtin_amdgcn_cvt_pk_fp8_f32(v1[2] * 8.f, v1[3] * 8.f, q1, true);
;                         *(u32x2*)(XB8 + o) = (u32x2){(unsigned)q0, (unsigned)q1}; }
;                     s[m] += (v0[0] * v0[0] + v0[1] * v0[1]) + (v0[2] * v0[2] + v0[3] * v0[3]) + (v1[0] * v1[0] + v1[1] * v1[1]) + (v1[2] * v1[2] + v1[3] * v1[3]); } }
; #pragma unroll
	s_nop 0
	s_nop 0
	s_nop 0
	v_add_f32_e32 v94, v94, v95
	v_add_f32_e32 v92, v92, v93
	v_pk_mul_f32 v[90:91], v[90:91], v[90:91]
	v_add_f32_e32 v120, v120, v121
	v_add_f32_e32 v92, v92, v94
	v_add_f32_e32 v88, v88, v89
	v_add_f32_e32 v120, v120, v124
	v_add_f32_e32 v121, v122, v123
	v_add_f32_e32 v88, v88, v92
	v_add_f32_e32 v89, v90, v91
	v_add_f32_e32 v120, v121, v120
	v_add_f32_e32 v88, v89, v88
	v_cmp_gt_u32_e32 vcc, 16, v180
	v_add_f32_e32 v180, v120, v88
	v_lshl_add_u64 v[88:89], v[128:129], 0, v[130:131]
	v_lshlrev_b64 v[90:91], 1, v[88:89]
	v_lshl_add_u64 v[120:121], v[88:89], 2, s[20:21]
	v_lshl_add_u64 v[124:125], s[22:23], 0, v[90:91]
	s_nop 0
	s_nop 0
	s_nop 0
	s_nop 0
	s_nop 0
	v_mul_f32_e32 v76, v76, v181
	v_mul_f32_e32 v77, v77, v181
	v_mul_f32_e32 v76, 0xbfb8aa3b, v76
	v_mul_f32_e32 v77, 0xbfb8aa3b, v77
	v_mul_f32_e32 v78, v78, v181
	v_mul_f32_e32 v79, v79, v181
	v_exp_f32_e32 v76, v76
	v_exp_f32_e32 v77, v77
	v_mul_f32_e32 v78, 0xbfb8aa3b, v78
	v_mul_f32_e32 v79, 0xbfb8aa3b, v79
	v_mul_f32_e32 v72, v72, v181
	v_mul_f32_e32 v73, v73, v181
	v_exp_f32_e32 v78, v78
	v_exp_f32_e32 v79, v79
	v_mul_f32_e32 v72, 0xbfb8aa3b, v72
	v_mul_f32_e32 v73, 0xbfb8aa3b, v73
	v_mul_f32_e32 v74, v74, v181
	v_mul_f32_e32 v75, v75, v181
	v_exp_f32_e32 v72, v72
	v_exp_f32_e32 v73, v73
	v_mul_f32_e32 v74, 0xbfb8aa3b, v74
	v_mul_f32_e32 v75, 0xbfb8aa3b, v75
	v_exp_f32_e32 v74, v74
	v_exp_f32_e32 v75, v75
	v_add_f32_e32 v76, 1.0, v76
	v_add_f32_e32 v77, 1.0, v77
	v_rcp_f32_e32 v76, v76
	v_rcp_f32_e32 v77, v77
	v_add_f32_e32 v78, 1.0, v78
	v_add_f32_e32 v79, 1.0, v79
	v_rcp_f32_e32 v78, v78
	v_rcp_f32_e32 v79, v79
	v_add_f32_e32 v72, 1.0, v72
	v_add_f32_e32 v73, 1.0, v73
	v_rcp_f32_e32 v72, v72
	v_rcp_f32_e32 v73, v73
	v_add_f32_e32 v74, 1.0, v74
	v_add_f32_e32 v75, 1.0, v75
	v_rcp_f32_e32 v74, v74
	v_rcp_f32_e32 v75, v75
	v_mul_f32_e32 v68, v68, v183
	v_mul_f32_e32 v69, v69, v183
	v_mul_f32_e32 v68, 0xbfb8aa3b, v68
	v_mul_f32_e32 v69, 0xbfb8aa3b, v69
	v_mul_f32_e32 v70, v70, v183
	v_mul_f32_e32 v71, v71, v183
	v_exp_f32_e32 v68, v68
	v_exp_f32_e32 v69, v69
	v_mul_f32_e32 v70, 0xbfb8aa3b, v70
	v_mul_f32_e32 v71, 0xbfb8aa3b, v71
	v_mul_f32_e32 v64, v64, v183
	v_mul_f32_e32 v65, v65, v183
	v_exp_f32_e32 v70, v70
	v_exp_f32_e32 v71, v71
	v_mul_f32_e32 v64, 0xbfb8aa3b, v64
	v_mul_f32_e32 v65, 0xbfb8aa3b, v65
	v_mul_f32_e32 v66, v66, v183
	s_waitcnt vmcnt(13)
	v_lshlrev_b32_e32 v130, 16, v218
	v_and_b32_e32 v131, 0xffff0000, v218
	s_waitcnt vmcnt(12)
	v_pk_fma_f32 v[76:77], v[76:77], v[130:131], v[222:223]
	v_lshlrev_b32_e32 v130, 16, v219
	v_and_b32_e32 v131, 0xffff0000, v219
	v_pk_fma_f32 v[78:79], v[78:79], v[130:131], v[224:225]
	v_lshlrev_b32_e32 v130, 16, v220
	v_and_b32_e32 v131, 0xffff0000, v220
	s_waitcnt vmcnt(11)
	v_pk_fma_f32 v[72:73], v[72:73], v[130:131], v[226:227]
	v_lshlrev_b32_e32 v130, 16, v221
	v_and_b32_e32 v131, 0xffff0000, v221
	v_pk_fma_f32 v[74:75], v[74:75], v[130:131], v[228:229]
	global_store_dwordx4 v[132:133], v[76:79], off offset:512
	global_store_dwordx4 v[132:133], v[72:75], off offset:528
	v_cvt_pk_bf16_f32 v130, v76, v77
	v_cvt_pk_bf16_f32 v131, v78, v79
	v_cvt_pk_bf16_f32 v132, v72, v73
	v_cvt_pk_bf16_f32 v133, v74, v75
	v_lshl_add_u64 v[150:151], s[26:27], 0, v[154:155]
	global_store_dwordx4 v[150:151], v[130:133], off
	v_mul_f32_e32 v150, 0x41000000, v72
	v_mul_f32_e32 v151, 0x41000000, v73
	v_mul_f32_e32 v131, 0x41000000, v76
	v_mul_f32_e32 v132, 0x41000000, v77
	v_mov_b32_e32 v130, 0
	v_cvt_pk_fp8_f32 v130, v131, v132
	v_mov_b32_e32 v131, 0
	v_cvt_pk_fp8_f32 v131, v150, v151
	v_mul_f32_e32 v67, v67, v183
	v_mul_f32_e32 v132, 0x41000000, v78
	v_mul_f32_e32 v133, 0x41000000, v79
	v_exp_f32_e32 v64, v64
	v_exp_f32_e32 v65, v65
	v_mul_f32_e32 v66, 0xbfb8aa3b, v66
	v_mul_f32_e32 v67, 0xbfb8aa3b, v67
	v_cvt_pk_fp8_f32 v130, v132, v133 op_sel:[0,0,1]
	v_mul_f32_e32 v132, 0x41000000, v74
	v_mul_f32_e32 v133, 0x41000000, v75
	v_exp_f32_e32 v66, v66
	v_exp_f32_e32 v67, v67
	v_cvt_pk_fp8_f32 v131, v132, v133 op_sel:[0,0,1]
	v_add_f32_e32 v68, 1.0, v68
	v_add_f32_e32 v69, 1.0, v69
	v_rcp_f32_e32 v68, v68
	v_rcp_f32_e32 v69, v69
	v_add_f32_e32 v70, 1.0, v70
	v_add_f32_e32 v71, 1.0, v71
	v_rcp_f32_e32 v70, v70
	v_rcp_f32_e32 v71, v71
	v_add_f32_e32 v64, 1.0, v64
	v_add_f32_e32 v65, 1.0, v65
	v_lshl_add_u64 v[132:133], s[28:29], 0, v[134:135]
	v_rcp_f32_e32 v64, v64
	v_rcp_f32_e32 v65, v65
	v_add_f32_e32 v66, 1.0, v66
	v_add_f32_e32 v67, 1.0, v67
	global_store_dwordx2 v[132:133], v[130:131], off
	s_waitcnt vmcnt(12)
	v_lshlrev_b32_e32 v130, 16, v238
	v_and_b32_e32 v131, 0xffff0000, v238
	v_rcp_f32_e32 v66, v66
	v_rcp_f32_e32 v67, v67
	v_pk_fma_f32 v[68:69], v[68:69], v[130:131], v[230:231]
	v_lshlrev_b32_e32 v92, 16, v239
	v_and_b32_e32 v93, 0xffff0000, v239
	v_pk_fma_f32 v[70:71], v[70:71], v[92:93], v[232:233]
	v_lshlrev_b32_e32 v92, 16, v240
	v_and_b32_e32 v93, 0xffff0000, v240
	v_pk_fma_f32 v[64:65], v[64:65], v[92:93], v[234:235]
	v_lshlrev_b32_e32 v92, 16, v241
	v_and_b32_e32 v93, 0xffff0000, v241
	v_pk_fma_f32 v[66:67], v[66:67], v[92:93], v[236:237]
	v_mul_f32_e32 v92, 0x41000000, v68
	v_mul_f32_e32 v93, 0x41000000, v69
	v_mov_b32_e32 v94, 0
	v_mul_f32_e32 v124, 0x41000000, v64
	v_mul_f32_e32 v125, 0x41000000, v65
	v_mov_b32_e32 v95, 0
	v_cvt_pk_fp8_f32 v94, v92, v93
	v_cvt_pk_fp8_f32 v95, v124, v125
	ds_bpermute_b32 v124, v168, v180
	v_mul_f32_e32 v92, 0x41000000, v70
	v_mul_f32_e32 v93, 0x41000000, v71
	v_cvt_pk_fp8_f32 v94, v92, v93 op_sel:[0,0,1]
	v_mul_f32_e32 v92, 0x41000000, v66
	v_mul_f32_e32 v93, 0x41000000, v67
	v_cvt_pk_fp8_f32 v95, v92, v93 op_sel:[0,0,1]
	s_waitcnt lgkmcnt(0)
	v_add_f32_e32 v92, v180, v124
	ds_bpermute_b32 v93, v169, v92
	v_cvt_pk_bf16_f32 v120, v68, v69
	v_cvt_pk_bf16_f32 v121, v70, v71
	v_cvt_pk_bf16_f32 v122, v64, v65
	v_cvt_pk_bf16_f32 v123, v66, v67
	v_lshl_add_u64 v[90:91], s[26:27], 0, v[90:91]
	v_lshl_add_u64 v[88:89], s[28:29], 0, v[88:89]
	global_store_dwordx4 v[156:157], v[68:71], off offset:512
	global_store_dwordx4 v[156:157], v[64:67], off offset:528
	global_store_dwordx4 v[90:91], v[120:123], off
	global_store_dwordx2 v[88:89], v[94:95], off
	s_and_saveexec_b64 s[0:1], vcc
	s_cbranch_execz .LBB0_1359
	s_waitcnt lgkmcnt(0)
	v_add_f32_e32 v90, v92, v93
	v_lshl_add_u64 v[88:89], v[140:141], 2, s[10:11]
	global_atomic_add_f32 v[88:89], v90, off

; __device__ __forceinline__ float bf_lo(unsigned u) { return __uint_as_float(u << 16); }
;     __device__ __forceinline__ void operator()(const f32x4 (&acc)[2][2][4][2], const Unit& u, int wr, int wc, int fr, int fq) const {
;     ...
;         for (int ai = 0; ai < 2; ++ai) { float s[4] = {0.f, 0.f, 0.f, 0.f};
; #pragma unroll
;             for (int bj = 0; bj < 2; ++bj)
; #pragma unroll
;               for (int mh = 0; mh < 2; ++mh) { f32x4 x0[2], x1[2]; u32x4 tw[2];
; #pragma unroll
;                 for (int mm = 0; mm < 2; ++mm) { const int m = 2 * mh + mm; const size_t o = (size_t)(row0 + ai * HALF + m * 16) * DM + col0 + bj * HALF; x0[mm] = *(const f32x4*)(X1 + o); x1[mm] = *(const f32x4*)(X1 + o + 4); tw[mm] = *(const u32x4*)(T + o); }
; #pragma unroll
;                 for (int mm = 0; mm < 2; ++mm) { const int m = 2 * mh + mm; const size_t o = (size_t)(row0 + ai * HALF + m * 16) * DM + col0 + bj * HALF;
;                     const float rs = rsqrtf(rsv[ai][m] * (1.f / DM) + EPS);
;                     const f32x4 a0 = acc[ai][bj][m][0], a1 = acc[ai][bj][m][1]; f32x4 v0 = x0[mm], v1 = x1[mm];
;                     v0[0] += sigm(a0[0] * rs) * bf_lo(tw[mm].x); v0[1] += sigm(a0[1] * rs) * bf_hi(tw[mm].x); v0[2] += sigm(a0[2] * rs) * bf_lo(tw[mm].y); v0[3] += sigm(a0[3] * rs) * bf_hi(tw[mm].y);
;                     v1[0] += sigm(a1[0] * rs) * bf_lo(tw[mm].z); v1[1] += sigm(a1[1] * rs) * bf_hi(tw[mm].z); v1[2] += sigm(a1[2] * rs) * bf_lo(tw[mm].w); v1[3] += sigm(a1[3] * rs) * bf_hi(tw[mm].w);
;                     *(f32x4*)(xout + o) = v0; *(f32x4*)(xout + o + 4) = v1;
;                     if (wxb) { u32x4 w; w.x = pk2(v0[0], v0[1]); w.y = pk2(v0[2], v0[3]); w.z = pk2(v1[0], v1[1]); w.w = pk2(v1[2], v1[3]); *(u32x4*)(XB + o) = w;
;                         int q0 = 0, q1 = 0; q0 = __builtin_amdgcn_cvt_pk_fp8_f32(v0[0] * 8.f, v0[1] * 8.f, q0, false); q0 = __builtin_amdgcn_cvt_pk_fp8_f32(v0[2] * 8.f, v0[3] * 8.f, q0, true);
;                         q1 = __builtin_amdgcn_cvt_pk_fp8_f32(v1[0] * 8.f, v1[1] * 8.f, q1, false); q1 = __builtin_amdgcn_cvt_pk_fp8_f32(v1[2] * 8.f, v1[3] * 8.f, q1, true);
;                         *(u32x2*)(XB8 + o) = (u32x2){(unsigned)q0, (unsigned)q1}; }
;                     s[m] += (v0[0] * v0[0] + v0[1] * v0[1]) + (v0[2] * v0[2] + v0[3] * v0[3]) + (v1[0] * v1[0] + v1[1] * v1[1]) + (v1[2] * v1[2] + v1[3] * v1[3]); } }
.LBB0_1365:
	s_or_b64 exec, exec, s[0:1]
	v_add_u32_e32 v68, 0x80, v140
	v_ashrrev_i32_e32 v69, 31, v68
	v_lshlrev_b64 v[72:73], 11, v[68:69]
	v_lshl_add_u64 v[108:109], v[72:73], 0, v[142:143]
	v_lshlrev_b64 v[110:111], 1, v[108:109]
	s_waitcnt lgkmcnt(0)
	v_lshl_add_u64 v[64:65], s[22:23], 0, v[110:111]
	global_load_dwordx4 v[82:85], v[64:65], off
	v_lshlrev_b64 v[74:75], 2, v[108:109]
	v_lshl_add_u64 v[64:65], s[20:21], 0, v[74:75]
	global_load_dwordx4 v[86:89], v[64:65], off
	global_load_dwordx4 v[90:93], v[64:65], off offset:16
	v_add_u32_e32 v66, 0x90, v140
	v_fmamk_f32 v70, v179, 0x3a000000, v175
	v_ashrrev_i32_e32 v67, 31, v66
	v_mul_f32_e32 v71, 0x4b800000, v70
	v_lshlrev_b64 v[76:77], 11, v[66:67]
	v_cmp_gt_f32_e64 s[4:5], s49, v70
	v_lshl_add_u64 v[74:75], s[8:9], 0, v[74:75]
	v_add_u32_e32 v64, 0xa0, v140
	v_cndmask_b32_e64 v78, v70, v71, s[4:5]
	v_lshl_add_u64 v[70:71], v[76:77], 0, v[142:143]
	v_rsq_f32_e32 v112, v78
	v_lshlrev_b64 v[80:81], 2, v[70:71]
	v_lshlrev_b64 v[78:79], 1, v[70:71]
	v_lshl_add_u64 v[94:95], s[20:21], 0, v[80:81]
	v_lshl_add_u64 v[104:105], s[22:23], 0, v[78:79]
	global_load_dwordx4 v[96:99], v[94:95], off
	global_load_dwordx4 v[100:103], v[94:95], off offset:16
	s_nop 0
	global_load_dwordx4 v[104:107], v[104:105], off
	v_mul_f32_e32 v94, 0x45800000, v112
	v_cndmask_b32_e64 v95, v112, v94, s[4:5]
	v_mul_f32_e32 v60, v60, v95
	v_mul_f32_e32 v61, v61, v95
	v_mul_f32_e32 v62, v62, v95
	v_mul_f32_e32 v63, v63, v95
	v_mul_f32_e32 v56, v56, v95
	v_mul_f32_e32 v57, v57, v95
	v_mul_f32_e32 v60, 0xbfb8aa3b, v60
	v_mul_f32_e32 v61, 0xbfb8aa3b, v61
	v_mul_f32_e32 v58, v58, v95
	v_mul_f32_e32 v59, v59, v95
	v_mul_f32_e32 v62, 0xbfb8aa3b, v62
	v_mul_f32_e32 v63, 0xbfb8aa3b, v63
	v_mul_f32_e32 v56, 0xbfb8aa3b, v56
	v_mul_f32_e32 v57, 0xbfb8aa3b, v57
	v_exp_f32_e32 v60, v60
	v_exp_f32_e32 v61, v61
	v_mul_f32_e32 v58, 0xbfb8aa3b, v58
	v_mul_f32_e32 v59, 0xbfb8aa3b, v59
	v_exp_f32_e32 v62, v62
	v_exp_f32_e32 v63, v63
	v_exp_f32_e32 v56, v56
	v_exp_f32_e32 v57, v57
	v_exp_f32_e32 v58, v58
	v_exp_f32_e32 v59, v59
	v_add_f32_e32 v60, 1.0, v60
	v_add_f32_e32 v61, 1.0, v61
	v_add_f32_e32 v62, 1.0, v62
	v_add_f32_e32 v63, 1.0, v63
	v_add_f32_e32 v94, 1.0, v56
	v_add_f32_e32 v113, 1.0, v57
	v_rcp_f32_e32 v56, v60
	v_rcp_f32_e32 v57, v61
	v_add_f32_e32 v114, 1.0, v58
	v_add_f32_e32 v115, 1.0, v59
	v_rcp_f32_e32 v58, v62
	v_rcp_f32_e32 v59, v63
	v_rcp_f32_e32 v112, v94
	v_rcp_f32_e32 v113, v113
	v_rcp_f32_e32 v114, v114
	v_rcp_f32_e32 v115, v115
	v_ashrrev_i32_e32 v65, 31, v64
	v_lshl_add_u64 v[78:79], s[26:27], 0, v[78:79]
	v_lshl_add_u64 v[70:71], s[28:29], 0, v[70:71]
	v_mul_f32_e32 v30, v30, v95
	v_mul_f32_e32 v31, v31, v95
	v_mul_f32_e32 v30, 0xbfb8aa3b, v30
	v_mul_f32_e32 v31, 0xbfb8aa3b, v31
	v_mul_f32_e32 v24, v24, v95
	v_mul_f32_e32 v25, v25, v95
	v_mul_f32_e32 v28, v28, v95
	v_mul_f32_e32 v29, v29, v95
	v_exp_f32_e32 v30, v30
	v_exp_f32_e32 v31, v31
	v_mul_f32_e32 v24, 0xbfb8aa3b, v24
	v_mul_f32_e32 v25, 0xbfb8aa3b, v25
	v_mul_f32_e32 v26, v26, v95
	v_mul_f32_e32 v27, v27, v95
	v_mul_f32_e32 v28, 0xbfb8aa3b, v28
	v_lshlrev_b64 v[242:243], 11, v[64:65]
	v_lshl_add_u64 v[244:245], v[242:243], 0, v[142:143]
	v_lshlrev_b64 v[242:243], 1, v[244:245]
	v_lshl_add_u64 v[246:247], s[22:23], 0, v[242:243]
	global_load_dwordx4 v[218:221], v[246:247], off
	v_lshlrev_b64 v[242:243], 2, v[244:245]
	v_lshl_add_u64 v[246:247], s[20:21], 0, v[242:243]
	global_load_dwordx4 v[222:225], v[246:247], off
	global_load_dwordx4 v[226:229], v[246:247], off offset:16
	v_add_u32_e32 v246, 0xb0, v140
	v_ashrrev_i32_e32 v247, 31, v246
	v_lshlrev_b64 v[242:243], 11, v[246:247]
	v_lshl_add_u64 v[244:245], v[242:243], 0, v[142:143]
	v_lshlrev_b64 v[242:243], 2, v[244:245]
	v_lshlrev_b64 v[246:247], 1, v[244:245]
	v_lshl_add_u64 v[248:249], s[20:21], 0, v[242:243]
	v_lshl_add_u64 v[242:243], s[22:23], 0, v[246:247]
	global_load_dwordx4 v[230:233], v[248:249], off
	global_load_dwordx4 v[234:237], v[248:249], off offset:16
	global_load_dwordx4 v[238:241], v[242:243], off
	s_waitcnt vmcnt(11)
	v_lshlrev_b32_e32 v60, 16, v82
	v_and_b32_e32 v61, 0xffff0000, v82
	v_lshlrev_b32_e32 v62, 16, v83
	v_and_b32_e32 v63, 0xffff0000, v83
	v_lshlrev_b32_e32 v82, 16, v84
	v_and_b32_e32 v83, 0xffff0000, v84
	s_waitcnt vmcnt(10)
	v_pk_fma_f32 v[60:61], v[56:57], v[60:61], v[86:87]
	v_pk_fma_f32 v[62:63], v[58:59], v[62:63], v[88:89]
	s_waitcnt vmcnt(9)
; __device__ __forceinline__ unsigned pk2(float lo, float hi) { f32x2 v = {lo, hi}; bf16x2_t b = __builtin_convertvector(v, bf16x2_t); return __builtin_bit_cast(unsigned, b); }
;     __device__ __forceinline__ void operator()(const f32x4 (&acc)[2][2][4][2], const Unit& u, int wr, int wc, int fr, int fq) const {
;     ...
;               for (int mh = 0; mh < 2; ++mh) { f32x4 x0[2], x1[2]; u32x4 tw[2];
; #pragma unroll
;                 for (int mm = 0; mm < 2; ++mm) { const int m = 2 * mh + mm; const size_t o = (size_t)(row0 + ai * HALF + m * 16) * DM + col0 + bj * HALF; x0[mm] = *(const f32x4*)(X1 + o); x1[mm] = *(const f32x4*)(X1 + o + 4); tw[mm] = *(const u32x4*)(T + o); }
; #pragma unroll
;                 for (int mm = 0; mm < 2; ++mm) { const int m = 2 * mh + mm; const size_t o = (size_t)(row0 + ai * HALF + m * 16) * DM + col0 + bj * HALF;
;                     const float rs = rsqrtf(rsv[ai][m] * (1.f / DM) + EPS);
;                     const f32x4 a0 = acc[ai][bj][m][0], a1 = acc[ai][bj][m][1]; f32x4 v0 = x0[mm], v1 = x1[mm];
;                     v0[0] += sigm(a0[0] * rs) * bf_lo(tw[mm].x); v0[1] += sigm(a0[1] * rs) * bf_hi(tw[mm].x); v0[2] += sigm(a0[2] * rs) * bf_lo(tw[mm].y); v0[3] += sigm(a0[3] * rs) * bf_hi(tw[mm].y);
;                     v1[0] += sigm(a1[0] * rs) * bf_lo(tw[mm].z); v1[1] += sigm(a1[1] * rs) * bf_hi(tw[mm].z); v1[2] += sigm(a1[2] * rs) * bf_lo(tw[mm].w); v1[3] += sigm(a1[3] * rs) * bf_hi(tw[mm].w);
;                     *(f32x4*)(xout + o) = v0; *(f32x4*)(xout + o + 4) = v1;
;                     if (wxb) { u32x4 w; w.x = pk2(v0[0], v0[1]); w.y = pk2(v0[2], v0[3]); w.z = pk2(v1[0], v1[1]); w.w = pk2(v1[2], v1[3]); *(u32x4*)(XB + o) = w;
;                         int q0 = 0, q1 = 0; q0 = __builtin_amdgcn_cvt_pk_fp8_f32(v0[0] * 8.f, v0[1] * 8.f, q0, false); q0 = __builtin_amdgcn_cvt_pk_fp8_f32(v0[2] * 8.f, v0[3] * 8.f, q0, true);
;                         q1 = __builtin_amdgcn_cvt_pk_fp8_f32(v1[0] * 8.f, v1[1] * 8.f, q1, false); q1 = __builtin_amdgcn_cvt_pk_fp8_f32(v1[2] * 8.f, v1[3] * 8.f, q1, true);
;                         *(u32x2*)(XB8 + o) = (u32x2){(unsigned)q0, (unsigned)q1}; }
;                     s[m] += (v0[0] * v0[0] + v0[1] * v0[1]) + (v0[2] * v0[2] + v0[3] * v0[3]) + (v1[0] * v1[0] + v1[1] * v1[1]) + (v1[2] * v1[2] + v1[3] * v1[3]); } }
	v_pk_fma_f32 v[56:57], v[112:113], v[82:83], v[90:91]
	v_mul_f32_e32 v89, 0x41000000, v60
	v_mul_f32_e32 v90, 0x41000000, v61
	v_mov_b32_e32 v88, 0
	v_lshlrev_b32_e32 v84, 16, v85
	v_and_b32_e32 v85, 0xffff0000, v85
	v_cvt_pk_fp8_f32 v88, v89, v90
	v_pk_fma_f32 v[58:59], v[114:115], v[84:85], v[92:93]
	v_cvt_pk_bf16_f32 v82, v60, v61
	v_cvt_pk_bf16_f32 v83, v62, v63
	v_cvt_pk_bf16_f32 v84, v56, v57
	v_cvt_pk_bf16_f32 v85, v58, v59
	v_lshl_add_u64 v[86:87], s[26:27], 0, v[110:111]
	global_store_dwordx4 v[74:75], v[60:63], off
	global_store_dwordx4 v[74:75], v[56:59], off offset:16
	global_store_dwordx4 v[86:87], v[82:85], off
	v_mov_b32_e32 v89, 0
	v_mul_f32_e32 v29, 0xbfb8aa3b, v29
	v_mul_f32_e32 v82, 0x41000000, v62
	v_mul_f32_e32 v83, 0x41000000, v63
	v_cvt_pk_fp8_f32 v88, v82, v83 op_sel:[0,0,1]
	v_mul_f32_e32 v82, 0x41000000, v56
	v_mul_f32_e32 v83, 0x41000000, v57
	v_cvt_pk_fp8_f32 v89, v82, v83
	v_fmamk_f32 v83, v178, 0x3a000000, v175
	v_mul_f32_e32 v84, 0x4b800000, v83
	v_cmp_gt_f32_e64 s[4:5], s49, v83
	v_mul_f32_e32 v82, 0x41000000, v58
	v_exp_f32_e32 v24, v24
	v_cndmask_b32_e64 v83, v83, v84, s[4:5]
	v_rsq_f32_e32 v84, v83
	v_mul_f32_e32 v83, 0x41000000, v59
	v_cvt_pk_fp8_f32 v89, v82, v83 op_sel:[0,0,1]
	v_lshl_add_u64 v[82:83], s[28:29], 0, v[108:109]
	v_mul_f32_e32 v85, 0x45800000, v84
	v_cndmask_b32_e64 v93, v84, v85, s[4:5]
	v_mul_f32_e32 v52, v52, v93
	v_mul_f32_e32 v53, v53, v93
	v_mul_f32_e32 v52, 0xbfb8aa3b, v52
	v_mul_f32_e32 v53, 0xbfb8aa3b, v53
	v_mul_f32_e32 v54, v54, v93
	v_mul_f32_e32 v55, v55, v93
	v_exp_f32_e32 v52, v52
	v_exp_f32_e32 v53, v53
	v_mul_f32_e32 v54, 0xbfb8aa3b, v54
	v_mul_f32_e32 v55, 0xbfb8aa3b, v55
	v_mul_f32_e32 v48, v48, v93
	v_mul_f32_e32 v49, v49, v93
	v_exp_f32_e32 v54, v54
	v_exp_f32_e32 v55, v55
	v_mul_f32_e32 v48, 0xbfb8aa3b, v48
	v_mul_f32_e32 v49, 0xbfb8aa3b, v49
	v_mul_f32_e32 v50, v50, v93
	v_mul_f32_e32 v51, v51, v93
	v_exp_f32_e32 v48, v48
	v_exp_f32_e32 v49, v49
	v_mul_f32_e32 v50, 0xbfb8aa3b, v50
	v_mul_f32_e32 v51, 0xbfb8aa3b, v51
	v_exp_f32_e32 v50, v50
	v_exp_f32_e32 v51, v51
	v_add_f32_e32 v52, 1.0, v52
	v_add_f32_e32 v53, 1.0, v53
	v_rcp_f32_e32 v52, v52
	v_rcp_f32_e32 v53, v53
	v_add_f32_e32 v54, 1.0, v54
	v_add_f32_e32 v55, 1.0, v55
	v_rcp_f32_e32 v54, v54
	v_rcp_f32_e32 v55, v55
	v_add_f32_e32 v48, 1.0, v48
	v_add_f32_e32 v49, 1.0, v49
	v_rcp_f32_e32 v48, v48
	v_rcp_f32_e32 v49, v49
	v_add_f32_e32 v50, 1.0, v50
	v_add_f32_e32 v51, 1.0, v51
	global_store_dwordx2 v[82:83], v[88:89], off
	s_waitcnt vmcnt(10)
	v_lshlrev_b32_e32 v82, 16, v104
	v_and_b32_e32 v83, 0xffff0000, v104
	v_rcp_f32_e32 v50, v50
	v_rcp_f32_e32 v51, v51
	v_pk_fma_f32 v[52:53], v[52:53], v[82:83], v[96:97]
	v_lshlrev_b32_e32 v82, 16, v105
	v_and_b32_e32 v83, 0xffff0000, v105
	v_pk_fma_f32 v[54:55], v[54:55], v[82:83], v[98:99]
	v_lshlrev_b32_e32 v82, 16, v106
	v_and_b32_e32 v83, 0xffff0000, v106
	v_pk_fma_f32 v[48:49], v[48:49], v[82:83], v[100:101]
	v_lshlrev_b32_e32 v82, 16, v107
	v_and_b32_e32 v83, 0xffff0000, v107
	v_pk_fma_f32 v[50:51], v[50:51], v[82:83], v[102:103]
	v_lshl_add_u64 v[82:83], s[8:9], 0, v[80:81]
	v_mul_f32_e32 v81, 0x41000000, v52
	v_mul_f32_e32 v88, 0x41000000, v53
	v_mov_b32_e32 v80, 0
	v_cvt_pk_fp8_f32 v80, v81, v88
	v_mul_f32_e32 v90, 0x41000000, v48
	v_mul_f32_e32 v91, 0x41000000, v49
	v_mov_b32_e32 v81, 0
	v_cvt_pk_fp8_f32 v81, v90, v91
	v_mul_f32_e32 v88, 0x41000000, v54
	v_mul_f32_e32 v89, 0x41000000, v55
	v_cvt_pk_fp8_f32 v80, v88, v89 op_sel:[0,0,1]
	v_mul_f32_e32 v88, 0x41000000, v50
	v_mul_f32_e32 v89, 0x41000000, v51
	v_cvt_pk_bf16_f32 v84, v52, v53
	v_cvt_pk_bf16_f32 v85, v54, v55
	v_cvt_pk_bf16_f32 v86, v48, v49
	v_cvt_pk_bf16_f32 v87, v50, v51
	v_cvt_pk_fp8_f32 v81, v88, v89 op_sel:[0,0,1]
	global_store_dwordx4 v[82:83], v[52:55], off
	global_store_dwordx4 v[82:83], v[48:51], off offset:16
	global_store_dwordx4 v[78:79], v[84:87], off
	v_fmamk_f32 v90, v177, 0x3a000000, v175
	global_store_dwordx2 v[70:71], v[80:81], off
	v_lshlrev_b64 v[86:87], 11, v[64:65]
	v_lshl_add_u64 v[84:85], v[86:87], 0, v[142:143]
	v_lshlrev_b64 v[120:121], 1, v[84:85]
	v_lshl_add_u64 v[70:71], s[22:23], 0, v[120:121]
	s_nop 0
	v_lshlrev_b64 v[80:81], 2, v[84:85]
	v_lshl_add_u64 v[70:71], s[20:21], 0, v[80:81]
	s_nop 0
	s_nop 0
	v_add_u32_e32 v70, 0xb0, v140
	v_ashrrev_i32_e32 v71, 31, v70
	v_lshlrev_b64 v[78:79], 11, v[70:71]
	v_mul_f32_e32 v91, 0x4b800000, v90
	v_cmp_gt_f32_e64 s[4:5], s49, v90
	v_lshl_add_u64 v[88:89], v[78:79], 0, v[142:143]
	v_lshlrev_b64 v[122:123], 2, v[88:89]
	v_cndmask_b32_e64 v90, v90, v91, s[4:5]
	v_rsq_f32_e32 v92, v90
	v_lshlrev_b64 v[90:91], 1, v[88:89]
	v_lshl_add_u64 v[112:113], s[20:21], 0, v[122:123]
	v_lshl_add_u64 v[116:117], s[22:23], 0, v[90:91]
	s_nop 0
	s_nop 0
	s_nop 0
	s_nop 0
	s_nop 0
	v_mul_f32_e32 v94, 0x45800000, v92
	v_cndmask_b32_e64 v92, v92, v94, s[4:5]
	v_mul_f32_e32 v44, v44, v92
	v_mul_f32_e32 v45, v45, v92
	v_mul_f32_e32 v44, 0xbfb8aa3b, v44
	v_mul_f32_e32 v45, 0xbfb8aa3b, v45
	v_mul_f32_e32 v46, v46, v92
	v_mul_f32_e32 v47, v47, v92
	v_exp_f32_e32 v44, v44
	v_exp_f32_e32 v45, v45
	v_mul_f32_e32 v46, 0xbfb8aa3b, v46
	v_mul_f32_e32 v47, 0xbfb8aa3b, v47
	v_mul_f32_e32 v40, v40, v92
	v_mul_f32_e32 v41, v41, v92
	v_exp_f32_e32 v46, v46
	v_exp_f32_e32 v47, v47
	v_mul_f32_e32 v40, 0xbfb8aa3b, v40
	v_mul_f32_e32 v41, 0xbfb8aa3b, v41
	v_mul_f32_e32 v42, v42, v92
	v_mul_f32_e32 v43, v43, v92
	v_exp_f32_e32 v40, v40
	v_exp_f32_e32 v41, v41
	v_mul_f32_e32 v42, 0xbfb8aa3b, v42
	v_mul_f32_e32 v43, 0xbfb8aa3b, v43
	v_exp_f32_e32 v42, v42
	v_exp_f32_e32 v43, v43
	v_add_f32_e32 v44, 1.0, v44
	v_add_f32_e32 v45, 1.0, v45
	v_rcp_f32_e32 v44, v44
; __device__ __forceinline__ unsigned pk2(float lo, float hi) { f32x2 v = {lo, hi}; bf16x2_t b = __builtin_convertvector(v, bf16x2_t); return __builtin_bit_cast(unsigned, b); }
;     __device__ __forceinline__ void operator()(const f32x4 (&acc)[2][2][4][2], const Unit& u, int wr, int wc, int fr, int fq) const {
;     ...
;               for (int mh = 0; mh < 2; ++mh) { f32x4 x0[2], x1[2]; u32x4 tw[2];
; #pragma unroll
;                 for (int mm = 0; mm < 2; ++mm) { const int m = 2 * mh + mm; const size_t o = (size_t)(row0 + ai * HALF + m * 16) * DM + col0 + bj * HALF; x0[mm] = *(const f32x4*)(X1 + o); x1[mm] = *(const f32x4*)(X1 + o + 4); tw[mm] = *(const u32x4*)(T + o); }
; #pragma unroll
;                 for (int mm = 0; mm < 2; ++mm) { const int m = 2 * mh + mm; const size_t o = (size_t)(row0 + ai * HALF + m * 16) * DM + col0 + bj * HALF;
;                     const float rs = rsqrtf(rsv[ai][m] * (1.f / DM) + EPS);
;                     const f32x4 a0 = acc[ai][bj][m][0], a1 = acc[ai][bj][m][1]; f32x4 v0 = x0[mm], v1 = x1[mm];
;                     v0[0] += sigm(a0[0] * rs) * bf_lo(tw[mm].x); v0[1] += sigm(a0[1] * rs) * bf_hi(tw[mm].x); v0[2] += sigm(a0[2] * rs) * bf_lo(tw[mm].y); v0[3] += sigm(a0[3] * rs) * bf_hi(tw[mm].y);
;                     v1[0] += sigm(a1[0] * rs) * bf_lo(tw[mm].z); v1[1] += sigm(a1[1] * rs) * bf_hi(tw[mm].z); v1[2] += sigm(a1[2] * rs) * bf_lo(tw[mm].w); v1[3] += sigm(a1[3] * rs) * bf_hi(tw[mm].w);
;                     *(f32x4*)(xout + o) = v0; *(f32x4*)(xout + o + 4) = v1;
;                     if (wxb) { u32x4 w; w.x = pk2(v0[0], v0[1]); w.y = pk2(v0[2], v0[3]); w.z = pk2(v1[0], v1[1]); w.w = pk2(v1[2], v1[3]); *(u32x4*)(XB + o) = w;
;                         int q0 = 0, q1 = 0; q0 = __builtin_amdgcn_cvt_pk_fp8_f32(v0[0] * 8.f, v0[1] * 8.f, q0, false); q0 = __builtin_amdgcn_cvt_pk_fp8_f32(v0[2] * 8.f, v0[3] * 8.f, q0, true);
;                         q1 = __builtin_amdgcn_cvt_pk_fp8_f32(v1[0] * 8.f, v1[1] * 8.f, q1, false); q1 = __builtin_amdgcn_cvt_pk_fp8_f32(v1[2] * 8.f, v1[3] * 8.f, q1, true);
;                         *(u32x2*)(XB8 + o) = (u32x2){(unsigned)q0, (unsigned)q1}; }
;                     s[m] += (v0[0] * v0[0] + v0[1] * v0[1]) + (v0[2] * v0[2] + v0[3] * v0[3]) + (v1[0] * v1[0] + v1[1] * v1[1]) + (v1[2] * v1[2] + v1[3] * v1[3]); } }
	v_rcp_f32_e32 v45, v45
	v_add_f32_e32 v46, 1.0, v46
	v_add_f32_e32 v47, 1.0, v47
	v_rcp_f32_e32 v46, v46
	v_rcp_f32_e32 v47, v47
	v_add_f32_e32 v40, 1.0, v40
	v_add_f32_e32 v41, 1.0, v41
	v_rcp_f32_e32 v40, v40
	v_rcp_f32_e32 v41, v41
	v_add_f32_e32 v42, 1.0, v42
	v_add_f32_e32 v43, 1.0, v43
	v_rcp_f32_e32 v42, v42
	v_rcp_f32_e32 v43, v43
	v_lshl_add_u64 v[80:81], s[8:9], 0, v[80:81]
	v_lshl_add_u64 v[84:85], s[28:29], 0, v[84:85]
	v_lshl_add_u64 v[90:91], s[26:27], 0, v[90:91]
	v_lshl_add_u64 v[88:89], s[28:29], 0, v[88:89]
	v_exp_f32_e32 v25, v25
	v_mul_f32_e32 v26, 0xbfb8aa3b, v26
	v_mul_f32_e32 v27, 0xbfb8aa3b, v27
	v_exp_f32_e32 v28, v28
	v_exp_f32_e32 v29, v29
	v_exp_f32_e32 v26, v26
	v_exp_f32_e32 v27, v27
	v_add_f32_e32 v30, 1.0, v30
	v_add_f32_e32 v31, 1.0, v31
	v_rcp_f32_e32 v30, v30
	v_rcp_f32_e32 v31, v31
	v_add_f32_e32 v24, 1.0, v24
	v_add_f32_e32 v25, 1.0, v25
	v_add_f32_e32 v28, 1.0, v28
	v_add_f32_e32 v29, 1.0, v29
	v_rcp_f32_e32 v24, v24
	v_lshl_add_u64 v[94:95], v[128:129], 0, v[72:73]
	v_lshlrev_b64 v[96:97], 1, v[94:95]
	v_lshl_add_u64 v[98:99], s[22:23], 0, v[96:97]
	global_load_dwordx4 v[242:245], v[98:99], off
	v_lshl_add_u64 v[98:99], v[94:95], 2, s[20:21]
	global_load_dwordx4 v[246:249], v[98:99], off
	global_load_dwordx4 v[250:253], v[98:99], off offset:16
	v_lshl_add_u64 v[98:99], v[128:129], 0, v[76:77]
	v_lshlrev_b64 v[94:95], 1, v[98:99]
	v_lshl_add_u64 v[100:101], v[98:99], 2, s[20:21]
	v_lshl_add_u64 v[96:97], s[22:23], 0, v[94:95]
	global_load_dwordx4 v[148:151], v[100:101], off
	global_load_dwordx4 v[156:159], v[100:101], off offset:16
	global_load_dwordx4 v[178:181], v[96:97], off
	s_waitcnt vmcnt(19)
	v_lshlrev_b32_e32 v124, 16, v218
	v_and_b32_e32 v125, 0xffff0000, v218
	s_waitcnt vmcnt(18)
	v_pk_fma_f32 v[44:45], v[44:45], v[124:125], v[222:223]
	v_lshlrev_b32_e32 v96, 16, v219
	v_and_b32_e32 v97, 0xffff0000, v219
	v_pk_fma_f32 v[46:47], v[46:47], v[96:97], v[224:225]
	v_lshlrev_b32_e32 v96, 16, v220
	v_and_b32_e32 v97, 0xffff0000, v220
	v_mul_f32_e32 v94, 0x41000000, v44
	v_mul_f32_e32 v103, 0x41000000, v45
	v_mov_b32_e32 v102, 0
	s_waitcnt vmcnt(17)
	v_pk_fma_f32 v[40:41], v[40:41], v[96:97], v[226:227]
	v_lshlrev_b32_e32 v96, 16, v221
	v_and_b32_e32 v97, 0xffff0000, v221
	v_cvt_pk_fp8_f32 v102, v94, v103
	v_pk_fma_f32 v[42:43], v[42:43], v[96:97], v[228:229]
	v_cvt_pk_bf16_f32 v96, v44, v45
	v_cvt_pk_bf16_f32 v97, v46, v47
	v_cvt_pk_bf16_f32 v98, v40, v41
	v_cvt_pk_bf16_f32 v99, v42, v43
	v_lshl_add_u64 v[100:101], s[26:27], 0, v[120:121]
	global_store_dwordx4 v[80:81], v[44:47], off
	global_store_dwordx4 v[80:81], v[40:43], off offset:16
	global_store_dwordx4 v[100:101], v[96:99], off
	v_mul_f32_e32 v94, 0x41000000, v46
	v_mov_b32_e32 v103, 0
	v_mul_f32_e32 v96, 0x41000000, v47
	v_cvt_pk_fp8_f32 v102, v94, v96 op_sel:[0,0,1]
	v_mul_f32_e32 v94, 0x41000000, v40
	v_mul_f32_e32 v96, 0x41000000, v41
	v_cvt_pk_fp8_f32 v103, v94, v96
	v_fmamk_f32 v96, v176, 0x3a000000, v175
	v_mul_f32_e32 v97, 0x4b800000, v96
	v_cmp_gt_f32_e64 s[4:5], s49, v96
	v_mul_f32_e32 v94, 0x41000000, v42
	v_mov_b32_e32 v100, 0
	v_cndmask_b32_e64 v96, v96, v97, s[4:5]
	v_rsq_f32_e32 v96, v96
	v_mul_f32_e32 v97, 0x41000000, v43
	v_cvt_pk_fp8_f32 v103, v94, v97 op_sel:[0,0,1]
	v_rcp_f32_e32 v25, v25
	v_mul_f32_e32 v94, 0x45800000, v96
	v_cndmask_b32_e64 v94, v96, v94, s[4:5]
	v_mul_f32_e32 v36, v36, v94
	v_mul_f32_e32 v37, v37, v94
	v_mul_f32_e32 v36, 0xbfb8aa3b, v36
	v_mul_f32_e32 v37, 0xbfb8aa3b, v37
	v_mul_f32_e32 v38, v38, v94
	v_mul_f32_e32 v39, v39, v94
	v_exp_f32_e32 v36, v36
	v_exp_f32_e32 v37, v37
	v_mul_f32_e32 v38, 0xbfb8aa3b, v38
	v_mul_f32_e32 v39, 0xbfb8aa3b, v39
	v_mul_f32_e32 v32, v32, v94
	v_mul_f32_e32 v33, v33, v94
	v_exp_f32_e32 v38, v38
	v_exp_f32_e32 v39, v39
	v_mul_f32_e32 v32, 0xbfb8aa3b, v32
	v_mul_f32_e32 v33, 0xbfb8aa3b, v33
	v_exp_f32_e32 v32, v32
	v_exp_f32_e32 v33, v33
	v_add_f32_e32 v36, 1.0, v36
	v_add_f32_e32 v37, 1.0, v37
	v_mul_f32_e32 v34, v34, v94
	v_mul_f32_e32 v35, v35, v94
	v_rcp_f32_e32 v36, v36
	v_rcp_f32_e32 v37, v37
	v_add_f32_e32 v38, 1.0, v38
	v_add_f32_e32 v39, 1.0, v39
	v_mul_f32_e32 v34, 0xbfb8aa3b, v34
	v_mul_f32_e32 v35, 0xbfb8aa3b, v35
	v_rcp_f32_e32 v38, v38
	v_rcp_f32_e32 v39, v39
	v_add_f32_e32 v32, 1.0, v32
	v_add_f32_e32 v33, 1.0, v33
	v_exp_f32_e32 v34, v34
	v_exp_f32_e32 v35, v35
	v_rcp_f32_e32 v32, v32
	v_rcp_f32_e32 v33, v33
	global_store_dwordx2 v[84:85], v[102:103], off
	s_waitcnt vmcnt(18)
; __device__ __forceinline__ float bf_lo(unsigned u) { return __uint_as_float(u << 16); }
;     __device__ __forceinline__ void operator()(const f32x4 (&acc)[2][2][4][2], const Unit& u, int wr, int wc, int fr, int fq) const {
;     ...
;         for (int ai = 0; ai < 2; ++ai) { float s[4] = {0.f, 0.f, 0.f, 0.f};
; #pragma unroll
;             for (int bj = 0; bj < 2; ++bj)
; #pragma unroll
;               for (int mh = 0; mh < 2; ++mh) { f32x4 x0[2], x1[2]; u32x4 tw[2];
; #pragma unroll
;                 for (int mm = 0; mm < 2; ++mm) { const int m = 2 * mh + mm; const size_t o = (size_t)(row0 + ai * HALF + m * 16) * DM + col0 + bj * HALF; x0[mm] = *(const f32x4*)(X1 + o); x1[mm] = *(const f32x4*)(X1 + o + 4); tw[mm] = *(const u32x4*)(T + o); }
; #pragma unroll
;                 for (int mm = 0; mm < 2; ++mm) { const int m = 2 * mh + mm; const size_t o = (size_t)(row0 + ai * HALF + m * 16) * DM + col0 + bj * HALF;
;                     const float rs = rsqrtf(rsv[ai][m] * (1.f / DM) + EPS);
;                     const f32x4 a0 = acc[ai][bj][m][0], a1 = acc[ai][bj][m][1]; f32x4 v0 = x0[mm], v1 = x1[mm];
;                     v0[0] += sigm(a0[0] * rs) * bf_lo(tw[mm].x); v0[1] += sigm(a0[1] * rs) * bf_hi(tw[mm].x); v0[2] += sigm(a0[2] * rs) * bf_lo(tw[mm].y); v0[3] += sigm(a0[3] * rs) * bf_hi(tw[mm].y);
;                     v1[0] += sigm(a1[0] * rs) * bf_lo(tw[mm].z); v1[1] += sigm(a1[1] * rs) * bf_hi(tw[mm].z); v1[2] += sigm(a1[2] * rs) * bf_lo(tw[mm].w); v1[3] += sigm(a1[3] * rs) * bf_hi(tw[mm].w);
;                     *(f32x4*)(xout + o) = v0; *(f32x4*)(xout + o + 4) = v1;
;                     if (wxb) { u32x4 w; w.x = pk2(v0[0], v0[1]); w.y = pk2(v0[2], v0[3]); w.z = pk2(v1[0], v1[1]); w.w = pk2(v1[2], v1[3]); *(u32x4*)(XB + o) = w;
;                         int q0 = 0, q1 = 0; q0 = __builtin_amdgcn_cvt_pk_fp8_f32(v0[0] * 8.f, v0[1] * 8.f, q0, false); q0 = __builtin_amdgcn_cvt_pk_fp8_f32(v0[2] * 8.f, v0[3] * 8.f, q0, true);
;                         q1 = __builtin_amdgcn_cvt_pk_fp8_f32(v1[0] * 8.f, v1[1] * 8.f, q1, false); q1 = __builtin_amdgcn_cvt_pk_fp8_f32(v1[2] * 8.f, v1[3] * 8.f, q1, true);
;                         *(u32x2*)(XB8 + o) = (u32x2){(unsigned)q0, (unsigned)q1}; }
;                     s[m] += (v0[0] * v0[0] + v0[1] * v0[1]) + (v0[2] * v0[2] + v0[3] * v0[3]) + (v1[0] * v1[0] + v1[1] * v1[1]) + (v1[2] * v1[2] + v1[3] * v1[3]); } }
	v_lshlrev_b32_e32 v84, 16, v238
	v_and_b32_e32 v85, 0xffff0000, v238
	v_pk_fma_f32 v[36:37], v[36:37], v[84:85], v[230:231]
	v_lshlrev_b32_e32 v84, 16, v239
	v_and_b32_e32 v85, 0xffff0000, v239
	v_pk_fma_f32 v[38:39], v[38:39], v[84:85], v[232:233]
	v_lshlrev_b32_e32 v84, 16, v240
	v_and_b32_e32 v85, 0xffff0000, v240
	v_add_f32_e32 v34, 1.0, v34
	v_add_f32_e32 v35, 1.0, v35
	v_rcp_f32_e32 v34, v34
	v_rcp_f32_e32 v35, v35
	v_pk_fma_f32 v[32:33], v[32:33], v[84:85], v[234:235]
	v_mul_f32_e32 v101, 0x41000000, v36
	v_mul_f32_e32 v102, 0x41000000, v37
	v_cvt_pk_fp8_f32 v100, v101, v102
	v_mul_f32_e32 v104, 0x41000000, v32
	v_mul_f32_e32 v105, 0x41000000, v33
	v_mov_b32_e32 v101, 0
	v_cvt_pk_fp8_f32 v101, v104, v105
	v_lshlrev_b32_e32 v84, 16, v241
	v_and_b32_e32 v85, 0xffff0000, v241
	v_pk_fma_f32 v[34:35], v[34:35], v[84:85], v[236:237]
	v_mul_f32_e32 v102, 0x41000000, v38
	v_mul_f32_e32 v103, 0x41000000, v39
	v_cvt_pk_fp8_f32 v100, v102, v103 op_sel:[0,0,1]
	v_mul_f32_e32 v102, 0x41000000, v34
	v_mul_f32_e32 v103, 0x41000000, v35
	v_cvt_pk_fp8_f32 v101, v102, v103 op_sel:[0,0,1]
	v_lshl_add_u64 v[116:117], v[128:129], 0, v[72:73]
	v_lshl_add_u64 v[84:85], s[8:9], 0, v[122:123]
	v_cvt_pk_bf16_f32 v96, v36, v37
	v_cvt_pk_bf16_f32 v97, v38, v39
	v_cvt_pk_bf16_f32 v98, v32, v33
	v_cvt_pk_bf16_f32 v99, v34, v35
	v_lshlrev_b64 v[118:119], 1, v[116:117]
	global_store_dwordx4 v[84:85], v[36:39], off
	global_store_dwordx4 v[84:85], v[32:35], off offset:16
	global_store_dwordx4 v[90:91], v[96:99], off
	global_store_dwordx2 v[88:89], v[100:101], off
	v_lshl_add_u64 v[72:73], s[22:23], 0, v[118:119]
	s_nop 0
	v_lshl_add_u64 v[72:73], v[116:117], 2, s[20:21]
	s_nop 0
	s_nop 0
	v_lshl_add_u64 v[72:73], v[128:129], 0, v[76:77]
	v_lshlrev_b64 v[76:77], 1, v[72:73]
	v_lshl_add_u64 v[108:109], v[72:73], 2, s[20:21]
	v_lshl_add_u64 v[112:113], s[22:23], 0, v[76:77]
	s_nop 0
	s_nop 0
	s_nop 0
	s_nop 0
	s_nop 0
	v_add_f32_e32 v26, 1.0, v26
	v_add_f32_e32 v27, 1.0, v27
	v_rcp_f32_e32 v28, v28
	v_rcp_f32_e32 v29, v29
	v_rcp_f32_e32 v26, v26
	v_rcp_f32_e32 v27, v27
	v_mul_f32_e32 v20, v20, v93
	v_mul_f32_e32 v21, v21, v93
	v_mul_f32_e32 v20, 0xbfb8aa3b, v20
	v_mul_f32_e32 v21, 0xbfb8aa3b, v21
	v_mul_f32_e32 v22, v22, v93
	v_mul_f32_e32 v23, v23, v93
	v_exp_f32_e32 v20, v20
	v_exp_f32_e32 v21, v21
	v_mul_f32_e32 v22, 0xbfb8aa3b, v22
	v_mul_f32_e32 v23, 0xbfb8aa3b, v23
	v_mul_f32_e32 v16, v16, v93
	v_mul_f32_e32 v17, v17, v93
	v_exp_f32_e32 v22, v22
	v_exp_f32_e32 v23, v23
	v_mul_f32_e32 v16, 0xbfb8aa3b, v16
	v_mul_f32_e32 v17, 0xbfb8aa3b, v17
	v_mul_f32_e32 v18, v18, v93
	v_mul_f32_e32 v19, v19, v93
	v_exp_f32_e32 v16, v16
	v_exp_f32_e32 v17, v17
	v_mul_f32_e32 v18, 0xbfb8aa3b, v18
	v_mul_f32_e32 v19, 0xbfb8aa3b, v19
	v_exp_f32_e32 v18, v18
	v_exp_f32_e32 v19, v19
	v_add_f32_e32 v20, 1.0, v20
	v_add_f32_e32 v21, 1.0, v21
	v_rcp_f32_e32 v20, v20
	v_rcp_f32_e32 v21, v21
	v_add_f32_e32 v22, 1.0, v22
	v_add_f32_e32 v23, 1.0, v23
	v_rcp_f32_e32 v22, v22
	v_rcp_f32_e32 v23, v23
	v_add_f32_e32 v16, 1.0, v16
	v_add_f32_e32 v17, 1.0, v17
	v_rcp_f32_e32 v16, v16
	v_rcp_f32_e32 v17, v17
	v_add_f32_e32 v18, 1.0, v18
	v_add_f32_e32 v19, 1.0, v19
	v_rcp_f32_e32 v18, v18
	v_rcp_f32_e32 v19, v19
	v_lshl_add_u64 v[76:77], s[26:27], 0, v[76:77]
	v_lshl_add_u64 v[72:73], s[28:29], 0, v[72:73]
	v_pk_mul_f32 v[60:61], v[60:61], v[60:61]
	v_pk_mul_f32 v[62:63], v[62:63], v[62:63]
	v_pk_mul_f32 v[56:57], v[56:57], v[56:57]
	v_add_f32_e32 v62, v62, v63
	v_add_f32_e32 v60, v60, v61
	v_pk_mul_f32 v[58:59], v[58:59], v[58:59]
	v_add_f32_e32 v60, v60, v62
	v_add_f32_e32 v56, v56, v57
	v_add_f32_e32 v56, v56, v60
	v_add_f32_e32 v57, v58, v59
	v_add_f32_e32 v56, v57, v56
	v_mul_f32_e32 v14, v14, v92
	v_mul_f32_e32 v15, v15, v92
	v_mul_f32_e32 v14, 0xbfb8aa3b, v14
	v_mul_f32_e32 v15, 0xbfb8aa3b, v15
	v_mul_f32_e32 v8, v8, v92
	v_mul_f32_e32 v9, v9, v92
	v_mul_f32_e32 v12, v12, v92
	v_mul_f32_e32 v13, v13, v92
	v_exp_f32_e32 v14, v14
	v_exp_f32_e32 v15, v15
	v_mul_f32_e32 v8, 0xbfb8aa3b, v8
	v_mul_f32_e32 v9, 0xbfb8aa3b, v9
	v_lshl_add_u64 v[238:239], v[128:129], 0, v[86:87]
	v_lshlrev_b64 v[240:241], 1, v[238:239]
	v_lshl_add_u64 v[182:183], s[22:23], 0, v[240:241]
	global_load_dwordx4 v[218:221], v[182:183], off
	v_lshl_add_u64 v[240:241], v[238:239], 2, s[20:21]
	global_load_dwordx4 v[222:225], v[240:241], off
	global_load_dwordx4 v[96:99], v[240:241], off offset:16
	v_lshl_add_u64 v[238:239], v[128:129], 0, v[78:79]
	v_lshlrev_b64 v[240:241], 1, v[238:239]
	v_lshl_add_u64 v[182:183], v[238:239], 2, s[20:21]
	v_lshl_add_u64 v[186:187], s[22:23], 0, v[240:241]
	global_load_dwordx4 v[226:229], v[182:183], off
	global_load_dwordx4 v[230:233], v[182:183], off offset:16
	global_load_dwordx4 v[234:237], v[186:187], off
	s_waitcnt vmcnt(19)
	v_lshlrev_b32_e32 v120, 16, v242
	v_and_b32_e32 v121, 0xffff0000, v242
	v_lshlrev_b32_e32 v88, 16, v243
	v_and_b32_e32 v89, 0xffff0000, v243
	s_waitcnt vmcnt(18)
	v_pk_fma_f32 v[30:31], v[30:31], v[88:89], v[248:249]
	v_lshlrev_b32_e32 v88, 16, v244
	v_and_b32_e32 v89, 0xffff0000, v244
	s_waitcnt vmcnt(17)
; __device__ __forceinline__ unsigned pk2(float lo, float hi) { f32x2 v = {lo, hi}; bf16x2_t b = __builtin_convertvector(v, bf16x2_t); return __builtin_bit_cast(unsigned, b); }
;     __device__ __forceinline__ void operator()(const f32x4 (&acc)[2][2][4][2], const Unit& u, int wr, int wc, int fr, int fq) const {
;     ...
;               for (int mh = 0; mh < 2; ++mh) { f32x4 x0[2], x1[2]; u32x4 tw[2];
; #pragma unroll
;                 for (int mm = 0; mm < 2; ++mm) { const int m = 2 * mh + mm; const size_t o = (size_t)(row0 + ai * HALF + m * 16) * DM + col0 + bj * HALF; x0[mm] = *(const f32x4*)(X1 + o); x1[mm] = *(const f32x4*)(X1 + o + 4); tw[mm] = *(const u32x4*)(T + o); }
; #pragma unroll
;                 for (int mm = 0; mm < 2; ++mm) { const int m = 2 * mh + mm; const size_t o = (size_t)(row0 + ai * HALF + m * 16) * DM + col0 + bj * HALF;
;                     const float rs = rsqrtf(rsv[ai][m] * (1.f / DM) + EPS);
;                     const f32x4 a0 = acc[ai][bj][m][0], a1 = acc[ai][bj][m][1]; f32x4 v0 = x0[mm], v1 = x1[mm];
;                     v0[0] += sigm(a0[0] * rs) * bf_lo(tw[mm].x); v0[1] += sigm(a0[1] * rs) * bf_hi(tw[mm].x); v0[2] += sigm(a0[2] * rs) * bf_lo(tw[mm].y); v0[3] += sigm(a0[3] * rs) * bf_hi(tw[mm].y);
;                     v1[0] += sigm(a1[0] * rs) * bf_lo(tw[mm].z); v1[1] += sigm(a1[1] * rs) * bf_hi(tw[mm].z); v1[2] += sigm(a1[2] * rs) * bf_lo(tw[mm].w); v1[3] += sigm(a1[3] * rs) * bf_hi(tw[mm].w);
;                     *(f32x4*)(xout + o) = v0; *(f32x4*)(xout + o + 4) = v1;
;                     if (wxb) { u32x4 w; w.x = pk2(v0[0], v0[1]); w.y = pk2(v0[2], v0[3]); w.z = pk2(v1[0], v1[1]); w.w = pk2(v1[2], v1[3]); *(u32x4*)(XB + o) = w;
;                         int q0 = 0, q1 = 0; q0 = __builtin_amdgcn_cvt_pk_fp8_f32(v0[0] * 8.f, v0[1] * 8.f, q0, false); q0 = __builtin_amdgcn_cvt_pk_fp8_f32(v0[2] * 8.f, v0[3] * 8.f, q0, true);
;                         q1 = __builtin_amdgcn_cvt_pk_fp8_f32(v1[0] * 8.f, v1[1] * 8.f, q1, false); q1 = __builtin_amdgcn_cvt_pk_fp8_f32(v1[2] * 8.f, v1[3] * 8.f, q1, true);
;                         *(u32x2*)(XB8 + o) = (u32x2){(unsigned)q0, (unsigned)q1}; }
;                     s[m] += (v0[0] * v0[0] + v0[1] * v0[1]) + (v0[2] * v0[2] + v0[3] * v0[3]) + (v1[0] * v1[0] + v1[1] * v1[1]) + (v1[2] * v1[2] + v1[3] * v1[3]); } }
	v_pk_fma_f32 v[24:25], v[24:25], v[88:89], v[250:251]
	v_lshlrev_b32_e32 v88, 16, v245
	v_and_b32_e32 v89, 0xffff0000, v245
	v_pk_fma_f32 v[28:29], v[28:29], v[120:121], v[246:247]
	v_pk_fma_f32 v[26:27], v[26:27], v[88:89], v[252:253]
	global_store_dwordx4 v[74:75], v[28:31], off offset:512
	global_store_dwordx4 v[74:75], v[24:27], off offset:528
	v_cvt_pk_bf16_f32 v88, v28, v29
	v_cvt_pk_bf16_f32 v89, v30, v31
	v_cvt_pk_bf16_f32 v90, v24, v25
	v_cvt_pk_bf16_f32 v91, v26, v27
	v_lshl_add_u64 v[74:75], s[26:27], 0, v[118:119]
	global_store_dwordx4 v[74:75], v[88:91], off
	v_mul_f32_e32 v75, 0x41000000, v28
	v_mov_b32_e32 v74, 0
	v_mul_f32_e32 v88, 0x41000000, v29
	v_cvt_pk_fp8_f32 v74, v75, v88
	v_mul_f32_e32 v90, 0x41000000, v24
	v_mul_f32_e32 v91, 0x41000000, v25
	v_mov_b32_e32 v75, 0
	v_cvt_pk_fp8_f32 v75, v90, v91
	v_mul_f32_e32 v88, 0x41000000, v30
	v_mul_f32_e32 v89, 0x41000000, v31
	v_cvt_pk_fp8_f32 v74, v88, v89 op_sel:[0,0,1]
	v_mul_f32_e32 v88, 0x41000000, v26
	v_mul_f32_e32 v89, 0x41000000, v27
	v_cvt_pk_fp8_f32 v75, v88, v89 op_sel:[0,0,1]
	v_lshl_add_u64 v[88:89], s[28:29], 0, v[116:117]
	v_pk_mul_f32 v[28:29], v[28:29], v[28:29]
	v_pk_mul_f32 v[30:31], v[30:31], v[30:31]
	global_store_dwordx2 v[88:89], v[74:75], off
	s_waitcnt vmcnt(18)
	v_lshlrev_b32_e32 v74, 16, v178
	v_and_b32_e32 v75, 0xffff0000, v178
	v_pk_fma_f32 v[20:21], v[20:21], v[74:75], v[148:149]
	v_lshlrev_b32_e32 v74, 16, v179
	v_and_b32_e32 v75, 0xffff0000, v179
	v_pk_fma_f32 v[22:23], v[22:23], v[74:75], v[150:151]
	v_lshlrev_b32_e32 v74, 16, v180
	v_and_b32_e32 v75, 0xffff0000, v180
	v_pk_fma_f32 v[16:17], v[16:17], v[74:75], v[156:157]
	v_lshlrev_b32_e32 v74, 16, v181
	v_and_b32_e32 v75, 0xffff0000, v181
	v_pk_fma_f32 v[18:19], v[18:19], v[74:75], v[158:159]
	global_store_dwordx4 v[82:83], v[20:23], off offset:512
	global_store_dwordx4 v[82:83], v[16:19], off offset:528
	v_mul_f32_e32 v75, 0x41000000, v20
	v_mul_f32_e32 v82, 0x41000000, v21
	v_mov_b32_e32 v74, 0
	v_cvt_pk_fp8_f32 v74, v75, v82
	v_mul_f32_e32 v93, 0x41000000, v16
	v_mul_f32_e32 v95, 0x41000000, v17
	v_mov_b32_e32 v75, 0
	v_cvt_pk_fp8_f32 v75, v93, v95
	v_mul_f32_e32 v82, 0x41000000, v22
	v_mul_f32_e32 v83, 0x41000000, v23
	v_cvt_pk_fp8_f32 v74, v82, v83 op_sel:[0,0,1]
	v_mul_f32_e32 v82, 0x41000000, v18
	v_mul_f32_e32 v83, 0x41000000, v19
	v_cvt_pk_fp8_f32 v75, v82, v83 op_sel:[0,0,1]
	v_cvt_pk_bf16_f32 v88, v20, v21
	v_cvt_pk_bf16_f32 v89, v22, v23
	v_cvt_pk_bf16_f32 v90, v16, v17
	v_cvt_pk_bf16_f32 v91, v18, v19
	global_store_dwordx4 v[76:77], v[88:91], off
	v_lshl_add_u64 v[76:77], v[128:129], 0, v[86:87]
	v_lshlrev_b64 v[82:83], 1, v[76:77]
	global_store_dwordx2 v[72:73], v[74:75], off
	v_lshl_add_u64 v[72:73], s[22:23], 0, v[82:83]
	s_nop 0
	v_lshl_add_u64 v[90:91], v[76:77], 2, s[20:21]
	s_nop 0
	s_nop 0
	v_pk_mul_f32 v[24:25], v[24:25], v[24:25]
	v_add_f32_e32 v30, v30, v31
	v_add_f32_e32 v28, v28, v29
	v_pk_mul_f32 v[26:27], v[26:27], v[26:27]
	v_add_f32_e32 v28, v28, v30
	v_add_f32_e32 v24, v24, v25
	v_add_f32_e32 v24, v24, v28
	v_add_f32_e32 v25, v26, v27
	v_add_f32_e32 v24, v25, v24
	v_add_f32_e32 v90, v56, v24
	v_lshl_add_u64 v[24:25], v[128:129], 0, v[78:79]
	v_lshlrev_b64 v[26:27], 1, v[24:25]
	v_lshl_add_u64 v[56:57], v[24:25], 2, s[20:21]
	v_lshl_add_u64 v[60:61], s[22:23], 0, v[26:27]
	s_nop 0
	s_nop 0
	s_nop 0
	s_nop 0
	s_nop 0
	v_mul_f32_e32 v10, v10, v92
	v_mul_f32_e32 v11, v11, v92
	v_mul_f32_e32 v12, 0xbfb8aa3b, v12
	v_mul_f32_e32 v13, 0xbfb8aa3b, v13
	v_exp_f32_e32 v8, v8
	v_exp_f32_e32 v9, v9
	v_mul_f32_e32 v10, 0xbfb8aa3b, v10
	v_mul_f32_e32 v11, 0xbfb8aa3b, v11
	v_exp_f32_e32 v12, v12
	v_exp_f32_e32 v13, v13
	v_exp_f32_e32 v10, v10
	v_exp_f32_e32 v11, v11
	v_add_f32_e32 v14, 1.0, v14
	v_add_f32_e32 v15, 1.0, v15
	v_rcp_f32_e32 v14, v14
	v_rcp_f32_e32 v15, v15
	v_add_f32_e32 v8, 1.0, v8
	v_add_f32_e32 v9, 1.0, v9
	v_add_f32_e32 v12, 1.0, v12
	v_add_f32_e32 v13, 1.0, v13
	v_rcp_f32_e32 v8, v8
	v_rcp_f32_e32 v9, v9
	v_add_f32_e32 v10, 1.0, v10
	v_add_f32_e32 v11, 1.0, v11
	v_rcp_f32_e32 v12, v12
	v_rcp_f32_e32 v13, v13
	v_rcp_f32_e32 v10, v10
	v_rcp_f32_e32 v11, v11
	v_mul_f32_e32 v4, v4, v94
	v_mul_f32_e32 v5, v5, v94
	v_mul_f32_e32 v4, 0xbfb8aa3b, v4
	v_mul_f32_e32 v5, 0xbfb8aa3b, v5
	v_mul_f32_e32 v6, v6, v94
	v_mul_f32_e32 v7, v7, v94
	v_exp_f32_e32 v4, v4
	v_exp_f32_e32 v5, v5
	v_mul_f32_e32 v6, 0xbfb8aa3b, v6
	v_mul_f32_e32 v7, 0xbfb8aa3b, v7
	v_mul_f32_e32 v0, v0, v94
	v_mul_f32_e32 v1, v1, v94
	v_exp_f32_e32 v6, v6
	v_exp_f32_e32 v7, v7
	v_mul_f32_e32 v0, 0xbfb8aa3b, v0
	v_mul_f32_e32 v1, 0xbfb8aa3b, v1
	v_mul_f32_e32 v2, v2, v94
	v_mul_f32_e32 v3, v3, v94
	v_exp_f32_e32 v0, v0
	v_exp_f32_e32 v1, v1
	v_mul_f32_e32 v2, 0xbfb8aa3b, v2
	v_mul_f32_e32 v3, 0xbfb8aa3b, v3
	v_exp_f32_e32 v2, v2
	v_exp_f32_e32 v3, v3
	v_add_f32_e32 v4, 1.0, v4
	v_add_f32_e32 v5, 1.0, v5
	v_rcp_f32_e32 v4, v4
	v_rcp_f32_e32 v5, v5
	v_add_f32_e32 v6, 1.0, v6
	v_add_f32_e32 v7, 1.0, v7
	v_rcp_f32_e32 v6, v6
	v_rcp_f32_e32 v7, v7
	v_add_f32_e32 v0, 1.0, v0
	s_waitcnt vmcnt(13)
;     __device__ __forceinline__ void operator()(const f32x4 (&acc)[2][2][4][2], const Unit& u, int wr, int wc, int fr, int fq) const {
;     ...
;               for (int mh = 0; mh < 2; ++mh) { f32x4 x0[2], x1[2]; u32x4 tw[2];
; #pragma unroll
;                 for (int mm = 0; mm < 2; ++mm) { const int m = 2 * mh + mm; const size_t o = (size_t)(row0 + ai * HALF + m * 16) * DM + col0 + bj * HALF; x0[mm] = *(const f32x4*)(X1 + o); x1[mm] = *(const f32x4*)(X1 + o + 4); tw[mm] = *(const u32x4*)(T + o); }
; #pragma unroll
;                 for (int mm = 0; mm < 2; ++mm) { const int m = 2 * mh + mm; const size_t o = (size_t)(row0 + ai * HALF + m * 16) * DM + col0 + bj * HALF;
;                     const float rs = rsqrtf(rsv[ai][m] * (1.f / DM) + EPS);
;                     const f32x4 a0 = acc[ai][bj][m][0], a1 = acc[ai][bj][m][1]; f32x4 v0 = x0[mm], v1 = x1[mm];
;                     v0[0] += sigm(a0[0] * rs) * bf_lo(tw[mm].x); v0[1] += sigm(a0[1] * rs) * bf_hi(tw[mm].x); v0[2] += sigm(a0[2] * rs) * bf_lo(tw[mm].y); v0[3] += sigm(a0[3] * rs) * bf_hi(tw[mm].y);
;                     v1[0] += sigm(a1[0] * rs) * bf_lo(tw[mm].z); v1[1] += sigm(a1[1] * rs) * bf_hi(tw[mm].z); v1[2] += sigm(a1[2] * rs) * bf_lo(tw[mm].w); v1[3] += sigm(a1[3] * rs) * bf_hi(tw[mm].w);
;                     *(f32x4*)(xout + o) = v0; *(f32x4*)(xout + o + 4) = v1;
;                     if (wxb) { u32x4 w; w.x = pk2(v0[0], v0[1]); w.y = pk2(v0[2], v0[3]); w.z = pk2(v1[0], v1[1]); w.w = pk2(v1[2], v1[3]); *(u32x4*)(XB + o) = w;
;                         int q0 = 0, q1 = 0; q0 = __builtin_amdgcn_cvt_pk_fp8_f32(v0[0] * 8.f, v0[1] * 8.f, q0, false); q0 = __builtin_amdgcn_cvt_pk_fp8_f32(v0[2] * 8.f, v0[3] * 8.f, q0, true);
;                         q1 = __builtin_amdgcn_cvt_pk_fp8_f32(v1[0] * 8.f, v1[1] * 8.f, q1, false); q1 = __builtin_amdgcn_cvt_pk_fp8_f32(v1[2] * 8.f, v1[3] * 8.f, q1, true);
;                         *(u32x2*)(XB8 + o) = (u32x2){(unsigned)q0, (unsigned)q1}; }
;                     s[m] += (v0[0] * v0[0] + v0[1] * v0[1]) + (v0[2] * v0[2] + v0[3] * v0[3]) + (v1[0] * v1[0] + v1[1] * v1[1]) + (v1[2] * v1[2] + v1[3] * v1[3]); } }
; #pragma unroll
;             for (int m = 0; m < 4; ++m) { float t = s[m]; t += __shfl_xor(t, 16); t += __shfl_xor(t, 32);
;                 if (fq == 0) atomicAdd(ssq2 + (row0 + ai * HALF + m * 16), t); } }
	v_lshlrev_b32_e32 v78, 16, v218
	v_and_b32_e32 v79, 0xffff0000, v218
	v_lshlrev_b32_e32 v72, 16, v219
	v_and_b32_e32 v73, 0xffff0000, v219
	s_waitcnt vmcnt(12)
	v_pk_fma_f32 v[14:15], v[14:15], v[72:73], v[224:225]
	v_lshlrev_b32_e32 v72, 16, v220
	v_and_b32_e32 v73, 0xffff0000, v220
	s_waitcnt vmcnt(11)
	v_pk_fma_f32 v[8:9], v[8:9], v[72:73], v[96:97]
	v_lshlrev_b32_e32 v72, 16, v221
	v_and_b32_e32 v73, 0xffff0000, v221
	v_pk_fma_f32 v[12:13], v[12:13], v[78:79], v[222:223]
	v_pk_fma_f32 v[10:11], v[10:11], v[72:73], v[98:99]
	v_cvt_pk_bf16_f32 v72, v12, v13
	v_cvt_pk_bf16_f32 v73, v14, v15
	v_cvt_pk_bf16_f32 v74, v8, v9
	v_cvt_pk_bf16_f32 v75, v10, v11
	v_lshl_add_u64 v[78:79], s[26:27], 0, v[82:83]
	global_store_dwordx4 v[80:81], v[12:15], off offset:512
	global_store_dwordx4 v[80:81], v[8:11], off offset:528
	global_store_dwordx4 v[78:79], v[72:75], off
	v_mul_f32_e32 v78, 0x41000000, v8
	v_mul_f32_e32 v79, 0x41000000, v9
	v_mul_f32_e32 v73, 0x41000000, v12
	v_mul_f32_e32 v74, 0x41000000, v13
	v_mov_b32_e32 v72, 0
	v_cvt_pk_fp8_f32 v72, v73, v74
	v_mov_b32_e32 v73, 0
	v_cvt_pk_fp8_f32 v73, v78, v79
	v_mul_f32_e32 v74, 0x41000000, v14
	v_mul_f32_e32 v75, 0x41000000, v15
	v_cvt_pk_fp8_f32 v72, v74, v75 op_sel:[0,0,1]
	v_mul_f32_e32 v74, 0x41000000, v10
	v_mul_f32_e32 v75, 0x41000000, v11
	v_cvt_pk_fp8_f32 v73, v74, v75 op_sel:[0,0,1]
	v_add_f32_e32 v1, 1.0, v1
	v_lshl_add_u64 v[74:75], s[28:29], 0, v[76:77]
	v_rcp_f32_e32 v0, v0
	v_rcp_f32_e32 v1, v1
	v_add_f32_e32 v2, 1.0, v2
	v_add_f32_e32 v3, 1.0, v3
	global_store_dwordx2 v[74:75], v[72:73], off
	s_waitcnt vmcnt(12)
	v_lshlrev_b32_e32 v72, 16, v234
	v_and_b32_e32 v73, 0xffff0000, v234
	v_rcp_f32_e32 v2, v2
	v_rcp_f32_e32 v3, v3
	v_pk_fma_f32 v[4:5], v[4:5], v[72:73], v[226:227]
	v_lshlrev_b32_e32 v28, 16, v235
	v_and_b32_e32 v29, 0xffff0000, v235
	v_pk_fma_f32 v[6:7], v[6:7], v[28:29], v[228:229]
	v_lshlrev_b32_e32 v28, 16, v236
	v_and_b32_e32 v29, 0xffff0000, v236
	v_pk_fma_f32 v[0:1], v[0:1], v[28:29], v[230:231]
	v_lshlrev_b32_e32 v28, 16, v237
	v_and_b32_e32 v29, 0xffff0000, v237
	v_pk_fma_f32 v[2:3], v[2:3], v[28:29], v[232:233]
	v_mul_f32_e32 v28, 0x41000000, v4
	v_mul_f32_e32 v29, 0x41000000, v5
	v_mov_b32_e32 v30, 0
	v_mul_f32_e32 v60, 0x41000000, v0
	v_mul_f32_e32 v61, 0x41000000, v1
	v_mov_b32_e32 v31, 0
	v_cvt_pk_fp8_f32 v30, v28, v29
	v_cvt_pk_fp8_f32 v31, v60, v61
	ds_bpermute_b32 v60, v168, v90
	v_mul_f32_e32 v28, 0x41000000, v6
	v_mul_f32_e32 v29, 0x41000000, v7
	v_cvt_pk_fp8_f32 v30, v28, v29 op_sel:[0,0,1]
	v_mul_f32_e32 v28, 0x41000000, v2
	v_mul_f32_e32 v29, 0x41000000, v3
	v_cvt_pk_fp8_f32 v31, v28, v29 op_sel:[0,0,1]
	s_waitcnt lgkmcnt(0)
	v_add_f32_e32 v28, v90, v60
	ds_bpermute_b32 v29, v169, v28
	v_cvt_pk_bf16_f32 v56, v4, v5
	v_cvt_pk_bf16_f32 v57, v6, v7
	v_cvt_pk_bf16_f32 v58, v0, v1
	v_cvt_pk_bf16_f32 v59, v2, v3
	v_lshl_add_u64 v[26:27], s[26:27], 0, v[26:27]
	v_lshl_add_u64 v[24:25], s[28:29], 0, v[24:25]
	global_store_dwordx4 v[84:85], v[4:7], off offset:512
	global_store_dwordx4 v[84:85], v[0:3], off offset:528
	global_store_dwordx4 v[26:27], v[56:59], off
	global_store_dwordx2 v[24:25], v[30:31], off
	s_and_saveexec_b64 s[0:1], vcc
	s_cbranch_execz .LBB0_1367
	s_waitcnt lgkmcnt(0)
	v_add_f32_e32 v26, v28, v29
	v_lshl_add_u64 v[24:25], v[68:69], 2, s[10:11]
	global_atomic_add_f32 v[24:25], v26, off

;     __device__ __forceinline__ void operator()(const f32x4 (&acc)[2][2][4][2], const Unit& u, int wr, int wc, int fr, int fq) const {
;         const int row0 = u.pm * BM + wr * 64 + fr, col0 = u.pn * BM + wc * 32 + 8 * fq;
;         float rsv[2][4];
; #pragma unroll
;         for (int ai = 0; ai < 2; ++ai)
; #pragma unroll
;             for (int m = 0; m < 4; ++m) rsv[ai][m] = ssq1[row0 + ai * HALF + m * 16];
; #pragma unroll
;         for (int ai = 0; ai < 2; ++ai) { float s[4] = {0.f, 0.f, 0.f, 0.f};
; #pragma unroll
;             for (int bj = 0; bj < 2; ++bj)
; #pragma unroll
;               for (int mh = 0; mh < 2; ++mh) { f32x4 x0[2], x1[2]; u32x4 tw[2];
; #pragma unroll
;                 for (int mm = 0; mm < 2; ++mm) { const int m = 2 * mh + mm; const size_t o = (size_t)(row0 + ai * HALF + m * 16) * DM + col0 + bj * HALF; x0[mm] = *(const f32x4*)(X1 + o); x1[mm] = *(const f32x4*)(X1 + o + 4); tw[mm] = *(const u32x4*)(T + o); }
; #pragma unroll
;                 for (int mm = 0; mm < 2; ++mm) { const int m = 2 * mh + mm; const size_t o = (size_t)(row0 + ai * HALF + m * 16) * DM + col0 + bj * HALF;
;                     const float rs = rsqrtf(rsv[ai][m] * (1.f / DM) + EPS);
;                     const f32x4 a0 = acc[ai][bj][m][0], a1 = acc[ai][bj][m][1]; f32x4 v0 = x0[mm], v1 = x1[mm];
;                     v0[0] += sigm(a0[0] * rs) * bf_lo(tw[mm].x); v0[1] += sigm(a0[1] * rs) * bf_hi(tw[mm].x); v0[2] += sigm(a0[2] * rs) * bf_lo(tw[mm].y); v0[3] += sigm(a0[3] * rs) * bf_hi(tw[mm].y);
;                     v1[0] += sigm(a1[0] * rs) * bf_lo(tw[mm].z); v1[1] += sigm(a1[1] * rs) * bf_hi(tw[mm].z); v1[2] += sigm(a1[2] * rs) * bf_lo(tw[mm].w); v1[3] += sigm(a1[3] * rs) * bf_hi(tw[mm].w);
;                     *(f32x4*)(xout + o) = v0; *(f32x4*)(xout + o + 4) = v1;
;                     if (wxb) { u32x4 w; w.x = pk2(v0[0], v0[1]); w.y = pk2(v0[2], v0[3]); w.z = pk2(v1[0], v1[1]); w.w = pk2(v1[2], v1[3]); *(u32x4*)(XB + o) = w;
;                         int q0 = 0, q1 = 0; q0 = __builtin_amdgcn_cvt_pk_fp8_f32(v0[0] * 8.f, v0[1] * 8.f, q0, false); q0 = __builtin_amdgcn_cvt_pk_fp8_f32(v0[2] * 8.f, v0[3] * 8.f, q0, true);
;                         q1 = __builtin_amdgcn_cvt_pk_fp8_f32(v1[0] * 8.f, v1[1] * 8.f, q1, false); q1 = __builtin_amdgcn_cvt_pk_fp8_f32(v1[2] * 8.f, v1[3] * 8.f, q1, true);
.LBB0_2209:
	s_lshl_b32 s0, s5, 8
	v_mov_b32_e32 v178, v160
	s_add_i32 s0, s0, s41
	s_nop 0
	v_and_or_b32 v132, v178, 15, s0
	v_ashrrev_i32_e32 v133, 1, v178
	v_and_b32_e32 v138, -8, v133
	v_ashrrev_i32_e32 v133, 31, v132
	v_or_b32_e32 v140, 16, v132
	v_lshl_add_u64 v[136:137], v[132:133], 2, s[26:27]
	v_ashrrev_i32_e32 v141, 31, v140
	v_lshl_add_u64 v[134:135], v[140:141], 2, s[26:27]
	global_load_dword v179, v[136:137], off
	global_load_dword v194, v[134:135], off
	s_lshl_b32 s0, s4, 8
	s_or_b32 s0, s0, s42
	v_add_u32_e32 v134, s0, v138
	v_ashrrev_i32_e32 v135, 31, v134
	v_lshlrev_b64 v[144:145], 11, v[132:133]
	v_lshl_add_u64 v[138:139], v[144:145], 0, v[134:135]
	v_lshl_add_u64 v[142:143], v[138:139], 1, s[24:25]
	global_load_dwordx4 v[148:151], v[142:143], off
	v_lshlrev_b64 v[180:181], 2, v[138:139]
	v_lshl_add_u64 v[138:139], s[22:23], 0, v[180:181]
	global_load_dwordx4 v[152:155], v[138:139], off
	global_load_dwordx4 v[156:159], v[138:139], off offset:16
	v_or_b32_e32 v142, 32, v132
	v_or_b32_e32 v138, 48, v132
	v_ashrrev_i32_e32 v143, 31, v142
	v_ashrrev_i32_e32 v139, 31, v138
	v_lshl_add_u64 v[182:183], v[142:143], 2, s[26:27]
	v_lshlrev_b64 v[146:147], 11, v[140:141]
	v_lshl_add_u64 v[184:185], v[138:139], 2, s[26:27]
	global_load_dword v177, v[136:137], off offset:512
	global_load_dword v176, v[136:137], off offset:576
	global_load_dword v175, v[136:137], off offset:640
	global_load_dword v202, v[182:183], off
	global_load_dword v206, v[184:185], off
	global_load_dword v174, v[136:137], off offset:704
	v_lshl_add_u64 v[182:183], v[146:147], 0, v[134:135]
	v_lshlrev_b64 v[136:137], 2, v[182:183]
	v_lshl_add_u64 v[190:191], v[182:183], 1, s[24:25]
	v_lshl_add_u64 v[186:187], s[22:23], 0, v[136:137]
	global_load_dwordx4 v[182:185], v[186:187], off
	s_nop 0
	global_load_dwordx4 v[186:189], v[186:187], off offset:16
	s_nop 0
	global_load_dwordx4 v[190:193], v[190:191], off
	v_lshlrev_b64 v[232:233], 11, v[142:143]
	v_lshl_add_u64 v[234:235], v[232:233], 0, v[134:135]
	v_lshl_add_u64 v[232:233], v[234:235], 1, s[24:25]
	global_load_dwordx4 v[208:211], v[232:233], off
	v_lshlrev_b64 v[234:235], 2, v[234:235]
	v_lshl_add_u64 v[232:233], s[22:23], 0, v[234:235]
	global_load_dwordx4 v[212:215], v[232:233], off
	global_load_dwordx4 v[216:219], v[232:233], off offset:16
	v_lshlrev_b64 v[234:235], 11, v[138:139]
	v_lshl_add_u64 v[232:233], v[234:235], 0, v[134:135]
	v_lshl_add_u64 v[234:235], v[232:233], 1, s[24:25]
	global_load_dwordx4 v[220:223], v[234:235], off
	v_lshlrev_b64 v[232:233], 2, v[232:233]
	v_lshl_add_u64 v[234:235], s[22:23], 0, v[232:233]
	global_load_dwordx4 v[224:227], v[234:235], off
	global_load_dwordx4 v[228:231], v[234:235], off offset:16
	s_waitcnt vmcnt(6)
	v_fmamk_f32 v179, v179, 0x3a000000, v173
	v_mul_f32_e32 v195, 0x4b800000, v179
	v_cmp_gt_f32_e32 vcc, s47, v179
	v_fmamk_f32 v203, v194, 0x3a000000, v173
	v_mul_f32_e32 v204, 0x4b800000, v203
	v_cndmask_b32_e32 v179, v179, v195, vcc
	v_rsq_f32_e32 v179, v179
	v_lshlrev_b32_e32 v194, 16, v148
	v_mul_f32_e32 v198, 0x45800000, v179
	v_cndmask_b32_e32 v207, v179, v198, vcc
	v_mul_f32_e32 v126, v126, v207
	v_mul_f32_e32 v127, v127, v207
	v_mul_f32_e32 v122, v122, v207
	v_mul_f32_e32 v123, v123, v207
	v_mul_f32_e32 v126, 0xbfb8aa3b, v126
	v_mul_f32_e32 v127, 0xbfb8aa3b, v127
	v_mul_f32_e32 v122, 0xbfb8aa3b, v122
	v_mul_f32_e32 v123, 0xbfb8aa3b, v123
	v_exp_f32_e32 v126, v126
	v_exp_f32_e32 v127, v127
	v_exp_f32_e32 v122, v122
	v_exp_f32_e32 v123, v123
	v_add_f32_e32 v126, 1.0, v126
	v_add_f32_e32 v127, 1.0, v127
	v_add_f32_e32 v200, 1.0, v122
	v_add_f32_e32 v201, 1.0, v123
	v_rcp_f32_e32 v122, v126
	v_rcp_f32_e32 v123, v127
	v_and_b32_e32 v195, 0xffff0000, v148
	v_lshlrev_b32_e32 v148, 16, v149
	v_and_b32_e32 v149, 0xffff0000, v149
	v_cmp_gt_f32_e32 vcc, s47, v203
	v_pk_fma_f32 v[126:127], v[122:123], v[148:149], v[154:155]
	v_rcp_f32_e32 v200, v200
	v_cndmask_b32_e32 v122, v203, v204, vcc
	v_rsq_f32_e32 v148, v122
	v_rcp_f32_e32 v201, v201
	v_lshlrev_b32_e32 v196, 16, v150
	v_and_b32_e32 v197, 0xffff0000, v150
	v_lshlrev_b32_e32 v150, 16, v151
	v_and_b32_e32 v151, 0xffff0000, v151
	v_mul_f32_e32 v149, 0x45800000, v148
	v_pk_fma_f32 v[122:123], v[200:201], v[150:151], v[158:159]
	v_lshl_add_u64 v[150:151], s[8:9], 0, v[180:181]
	v_cndmask_b32_e32 v180, v148, v149, vcc
	v_mul_f32_e32 v116, v116, v180
	v_mul_f32_e32 v117, v117, v180
	v_mul_f32_e32 v116, 0xbfb8aa3b, v116
	v_mul_f32_e32 v117, 0xbfb8aa3b, v117
	v_mul_f32_e32 v118, v118, v180
	v_mul_f32_e32 v119, v119, v180
	v_mul_f32_e32 v124, v124, v207
	v_mul_f32_e32 v125, v125, v207
	v_mul_f32_e32 v120, v120, v207
	v_mul_f32_e32 v121, v121, v207
	v_exp_f32_e32 v116, v116
	v_exp_f32_e32 v117, v117
	v_mul_f32_e32 v118, 0xbfb8aa3b, v118
	v_mul_f32_e32 v119, 0xbfb8aa3b, v119
	v_mul_f32_e32 v112, v112, v180
	v_mul_f32_e32 v113, v113, v180
	v_mul_f32_e32 v124, 0xbfb8aa3b, v124
	v_mul_f32_e32 v125, 0xbfb8aa3b, v125
	v_mul_f32_e32 v120, 0xbfb8aa3b, v120
	v_mul_f32_e32 v121, 0xbfb8aa3b, v121
	v_exp_f32_e32 v118, v118
	v_exp_f32_e32 v119, v119
	v_mul_f32_e32 v112, 0xbfb8aa3b, v112
	v_mul_f32_e32 v113, 0xbfb8aa3b, v113
	v_mul_f32_e32 v114, v114, v180
	v_mul_f32_e32 v115, v115, v180
	v_exp_f32_e32 v124, v124
	v_exp_f32_e32 v125, v125
	v_exp_f32_e32 v120, v120
	v_exp_f32_e32 v121, v121
	v_exp_f32_e32 v112, v112
	v_exp_f32_e32 v113, v113
	v_mul_f32_e32 v114, 0xbfb8aa3b, v114
	v_mul_f32_e32 v115, 0xbfb8aa3b, v115
	v_exp_f32_e32 v114, v114
	v_exp_f32_e32 v115, v115
	v_add_f32_e32 v116, 1.0, v116
	v_add_f32_e32 v117, 1.0, v117
	v_rcp_f32_e32 v116, v116
	v_rcp_f32_e32 v117, v117
	v_add_f32_e32 v118, 1.0, v118
	v_add_f32_e32 v119, 1.0, v119
; __device__ __forceinline__ float bf_lo(unsigned u) { return __uint_as_float(u << 16); }
;     __device__ __forceinline__ void operator()(const f32x4 (&acc)[2][2][4][2], const Unit& u, int wr, int wc, int fr, int fq) const {
;     ...
;         for (int ai = 0; ai < 2; ++ai) { float s[4] = {0.f, 0.f, 0.f, 0.f};
; #pragma unroll
;             for (int bj = 0; bj < 2; ++bj)
; #pragma unroll
;               for (int mh = 0; mh < 2; ++mh) { f32x4 x0[2], x1[2]; u32x4 tw[2];
; #pragma unroll
;                 for (int mm = 0; mm < 2; ++mm) { const int m = 2 * mh + mm; const size_t o = (size_t)(row0 + ai * HALF + m * 16) * DM + col0 + bj * HALF; x0[mm] = *(const f32x4*)(X1 + o); x1[mm] = *(const f32x4*)(X1 + o + 4); tw[mm] = *(const u32x4*)(T + o); }
; #pragma unroll
;                 for (int mm = 0; mm < 2; ++mm) { const int m = 2 * mh + mm; const size_t o = (size_t)(row0 + ai * HALF + m * 16) * DM + col0 + bj * HALF;
;                     const float rs = rsqrtf(rsv[ai][m] * (1.f / DM) + EPS);
;                     const f32x4 a0 = acc[ai][bj][m][0], a1 = acc[ai][bj][m][1]; f32x4 v0 = x0[mm], v1 = x1[mm];
;                     v0[0] += sigm(a0[0] * rs) * bf_lo(tw[mm].x); v0[1] += sigm(a0[1] * rs) * bf_hi(tw[mm].x); v0[2] += sigm(a0[2] * rs) * bf_lo(tw[mm].y); v0[3] += sigm(a0[3] * rs) * bf_hi(tw[mm].y);
;                     v1[0] += sigm(a1[0] * rs) * bf_lo(tw[mm].z); v1[1] += sigm(a1[1] * rs) * bf_hi(tw[mm].z); v1[2] += sigm(a1[2] * rs) * bf_lo(tw[mm].w); v1[3] += sigm(a1[3] * rs) * bf_hi(tw[mm].w);
;                     *(f32x4*)(xout + o) = v0; *(f32x4*)(xout + o + 4) = v1;
;                     if (wxb) { u32x4 w; w.x = pk2(v0[0], v0[1]); w.y = pk2(v0[2], v0[3]); w.z = pk2(v1[0], v1[1]); w.w = pk2(v1[2], v1[3]); *(u32x4*)(XB + o) = w;
;                         int q0 = 0, q1 = 0; q0 = __builtin_amdgcn_cvt_pk_fp8_f32(v0[0] * 8.f, v0[1] * 8.f, q0, false); q0 = __builtin_amdgcn_cvt_pk_fp8_f32(v0[2] * 8.f, v0[3] * 8.f, q0, true);
;                         q1 = __builtin_amdgcn_cvt_pk_fp8_f32(v1[0] * 8.f, v1[1] * 8.f, q1, false); q1 = __builtin_amdgcn_cvt_pk_fp8_f32(v1[2] * 8.f, v1[3] * 8.f, q1, true);
;                         *(u32x2*)(XB8 + o) = (u32x2){(unsigned)q0, (unsigned)q1}; }
;                     s[m] += (v0[0] * v0[0] + v0[1] * v0[1]) + (v0[2] * v0[2] + v0[3] * v0[3]) + (v1[0] * v1[0] + v1[1] * v1[1]) + (v1[2] * v1[2] + v1[3] * v1[3]); } }
	v_add_f32_e32 v124, 1.0, v124
	v_add_f32_e32 v125, 1.0, v125
	v_add_f32_e32 v179, 1.0, v120
	v_add_f32_e32 v199, 1.0, v121
	v_rcp_f32_e32 v118, v118
	v_rcp_f32_e32 v119, v119
	v_add_f32_e32 v112, 1.0, v112
	v_add_f32_e32 v113, 1.0, v113
	v_rcp_f32_e32 v120, v124
	v_rcp_f32_e32 v121, v125
	v_rcp_f32_e32 v198, v179
	v_rcp_f32_e32 v199, v199
	v_rcp_f32_e32 v112, v112
	v_rcp_f32_e32 v113, v113
	v_add_f32_e32 v114, 1.0, v114
	v_add_f32_e32 v115, 1.0, v115
	v_lshlrev_b32_e32 v148, 16, v190
	v_and_b32_e32 v149, 0xffff0000, v190
	v_rcp_f32_e32 v114, v114
	v_rcp_f32_e32 v115, v115
	v_pk_fma_f32 v[116:117], v[116:117], v[148:149], v[182:183]
	v_lshlrev_b32_e32 v148, 16, v191
	v_and_b32_e32 v149, 0xffff0000, v191
	v_pk_fma_f32 v[118:119], v[118:119], v[148:149], v[184:185]
	v_lshlrev_b32_e32 v148, 16, v192
	v_and_b32_e32 v149, 0xffff0000, v192
	v_lshlrev_b64 v[158:159], 11, v[142:143]
	v_pk_fma_f32 v[124:125], v[120:121], v[194:195], v[152:153]
	v_pk_fma_f32 v[120:121], v[198:199], v[196:197], v[156:157]
	v_pk_fma_f32 v[112:113], v[112:113], v[148:149], v[186:187]
	v_lshlrev_b32_e32 v148, 16, v193
	v_and_b32_e32 v149, 0xffff0000, v193
	v_lshl_add_u64 v[152:153], s[8:9], 0, v[136:137]
	v_lshl_add_u64 v[136:137], v[158:159], 0, v[134:135]
	global_store_dwordx4 v[150:151], v[124:127], off
	global_store_dwordx4 v[150:151], v[120:123], off offset:16
	v_pk_fma_f32 v[114:115], v[114:115], v[148:149], v[188:189]
	global_store_dwordx4 v[152:153], v[116:119], off
	global_store_dwordx4 v[152:153], v[112:115], off offset:16
	v_lshl_add_u64 v[148:149], v[136:137], 1, s[24:25]
	s_nop 0
	v_lshlrev_b64 v[136:137], 2, v[136:137]
	v_lshl_add_u64 v[148:149], s[22:23], 0, v[136:137]
	s_nop 0
	s_nop 0
	v_lshlrev_b64 v[156:157], 11, v[138:139]
	v_lshl_add_u64 v[148:149], v[156:157], 0, v[134:135]
	v_lshl_add_u64 v[154:155], v[148:149], 1, s[24:25]
	s_nop 0
	v_fmamk_f32 v154, v202, 0x3a000000, v173
	v_mul_f32_e32 v155, 0x4b800000, v154
	v_cmp_gt_f32_e32 vcc, s47, v154
	v_lshlrev_b64 v[148:149], 2, v[148:149]
	v_mul_f32_e32 v94, v94, v207
	v_cndmask_b32_e32 v154, v154, v155, vcc
	v_rsq_f32_e32 v179, v154
	v_lshl_add_u64 v[154:155], s[22:23], 0, v[148:149]
	s_nop 0
	s_nop 0
	v_mul_f32_e32 v181, 0x45800000, v179
	v_cndmask_b32_e32 v179, v179, v181, vcc
	v_mul_f32_e32 v108, v108, v179
	v_mul_f32_e32 v109, v109, v179
	v_mul_f32_e32 v108, 0xbfb8aa3b, v108
	v_mul_f32_e32 v109, 0xbfb8aa3b, v109
	v_mul_f32_e32 v110, v110, v179
	v_mul_f32_e32 v111, v111, v179
	v_exp_f32_e32 v108, v108
	v_exp_f32_e32 v109, v109
	v_mul_f32_e32 v110, 0xbfb8aa3b, v110
	v_mul_f32_e32 v111, 0xbfb8aa3b, v111
	v_mul_f32_e32 v104, v104, v179
	v_mul_f32_e32 v105, v105, v179
	v_exp_f32_e32 v110, v110
	v_exp_f32_e32 v111, v111
	v_mul_f32_e32 v104, 0xbfb8aa3b, v104
	v_mul_f32_e32 v105, 0xbfb8aa3b, v105
	v_mul_f32_e32 v106, v106, v179
	v_mul_f32_e32 v107, v107, v179
	v_exp_f32_e32 v104, v104
	v_exp_f32_e32 v105, v105
	v_mul_f32_e32 v106, 0xbfb8aa3b, v106
	v_mul_f32_e32 v107, 0xbfb8aa3b, v107
	v_exp_f32_e32 v106, v106
	v_exp_f32_e32 v107, v107
	v_add_f32_e32 v108, 1.0, v108
	v_add_f32_e32 v109, 1.0, v109
	v_rcp_f32_e32 v108, v108
	v_rcp_f32_e32 v109, v109
	v_add_f32_e32 v110, 1.0, v110
	v_add_f32_e32 v111, 1.0, v111
	v_fmamk_f32 v181, v206, 0x3a000000, v173
	v_rcp_f32_e32 v110, v110
	v_rcp_f32_e32 v111, v111
	v_add_f32_e32 v104, 1.0, v104
	v_add_f32_e32 v105, 1.0, v105
	v_cmp_gt_f32_e32 vcc, s47, v181
	v_rcp_f32_e32 v104, v104
	v_rcp_f32_e32 v105, v105
	v_add_f32_e32 v106, 1.0, v106
	v_add_f32_e32 v107, 1.0, v107
	v_rcp_f32_e32 v106, v106
	v_rcp_f32_e32 v107, v107
	v_lshl_add_u64 v[148:149], s[8:9], 0, v[148:149]
	v_mul_f32_e32 v95, v95, v207
	v_mul_f32_e32 v94, 0xbfb8aa3b, v94
	v_mul_f32_e32 v95, 0xbfb8aa3b, v95
	v_mul_f32_e32 v88, v88, v207
	v_mul_f32_e32 v89, v89, v207
	v_mul_f32_e32 v92, v92, v207
	v_mul_f32_e32 v93, v93, v207
	v_exp_f32_e32 v94, v94
	v_exp_f32_e32 v95, v95
	v_mul_f32_e32 v88, 0xbfb8aa3b, v88
	v_mul_f32_e32 v89, 0xbfb8aa3b, v89
	v_mul_f32_e32 v90, v90, v207
	v_mul_f32_e32 v91, v91, v207
	v_mul_f32_e32 v92, 0xbfb8aa3b, v92
	v_mul_f32_e32 v93, 0xbfb8aa3b, v93
	v_exp_f32_e32 v88, v88
	v_exp_f32_e32 v89, v89
	v_lshl_add_u64 v[248:249], v[134:135], 0, s[30:31]
	v_lshl_add_u64 v[250:251], v[248:249], 0, v[144:145]
	v_lshl_add_u64 v[200:201], v[250:251], 1, s[24:25]
	global_load_dwordx4 v[232:235], v[200:201], off
	v_lshl_add_u64 v[250:251], v[250:251], 2, s[22:23]
	global_load_dwordx4 v[186:189], v[250:251], off
	global_load_dwordx4 v[190:193], v[250:251], off offset:16
	v_lshl_add_u64 v[200:201], v[248:249], 0, v[146:147]
	v_lshl_add_u64 v[250:251], v[200:201], 1, s[24:25]
	global_load_dwordx4 v[236:239], v[250:251], off
	v_lshl_add_u64 v[248:249], v[200:201], 2, s[22:23]
	global_load_dwordx4 v[240:243], v[248:249], off
	global_load_dwordx4 v[244:247], v[248:249], off offset:16
	s_waitcnt vmcnt(15)
	v_lshlrev_b32_e32 v154, 16, v208
	v_and_b32_e32 v155, 0xffff0000, v208
	v_mul_f32_e32 v182, 0x4b800000, v181
	v_cndmask_b32_e32 v181, v181, v182, vcc
	v_rsq_f32_e32 v181, v181
	s_waitcnt vmcnt(14)
	v_pk_fma_f32 v[108:109], v[108:109], v[154:155], v[212:213]
	v_lshlrev_b32_e32 v154, 16, v209
	v_and_b32_e32 v155, 0xffff0000, v209
	v_pk_fma_f32 v[110:111], v[110:111], v[154:155], v[214:215]
	v_lshlrev_b32_e32 v154, 16, v210
	v_and_b32_e32 v155, 0xffff0000, v210
	s_waitcnt vmcnt(13)
; __device__ __forceinline__ float bf_lo(unsigned u) { return __uint_as_float(u << 16); }
;     __device__ __forceinline__ void operator()(const f32x4 (&acc)[2][2][4][2], const Unit& u, int wr, int wc, int fr, int fq) const {
;     ...
;         for (int ai = 0; ai < 2; ++ai) { float s[4] = {0.f, 0.f, 0.f, 0.f};
; #pragma unroll
;             for (int bj = 0; bj < 2; ++bj)
; #pragma unroll
;               for (int mh = 0; mh < 2; ++mh) { f32x4 x0[2], x1[2]; u32x4 tw[2];
; #pragma unroll
;                 for (int mm = 0; mm < 2; ++mm) { const int m = 2 * mh + mm; const size_t o = (size_t)(row0 + ai * HALF + m * 16) * DM + col0 + bj * HALF; x0[mm] = *(const f32x4*)(X1 + o); x1[mm] = *(const f32x4*)(X1 + o + 4); tw[mm] = *(const u32x4*)(T + o); }
; #pragma unroll
;                 for (int mm = 0; mm < 2; ++mm) { const int m = 2 * mh + mm; const size_t o = (size_t)(row0 + ai * HALF + m * 16) * DM + col0 + bj * HALF;
;                     const float rs = rsqrtf(rsv[ai][m] * (1.f / DM) + EPS);
;                     const f32x4 a0 = acc[ai][bj][m][0], a1 = acc[ai][bj][m][1]; f32x4 v0 = x0[mm], v1 = x1[mm];
;                     v0[0] += sigm(a0[0] * rs) * bf_lo(tw[mm].x); v0[1] += sigm(a0[1] * rs) * bf_hi(tw[mm].x); v0[2] += sigm(a0[2] * rs) * bf_lo(tw[mm].y); v0[3] += sigm(a0[3] * rs) * bf_hi(tw[mm].y);
;                     v1[0] += sigm(a1[0] * rs) * bf_lo(tw[mm].z); v1[1] += sigm(a1[1] * rs) * bf_hi(tw[mm].z); v1[2] += sigm(a1[2] * rs) * bf_lo(tw[mm].w); v1[3] += sigm(a1[3] * rs) * bf_hi(tw[mm].w);
;                     *(f32x4*)(xout + o) = v0; *(f32x4*)(xout + o + 4) = v1;
;                     if (wxb) { u32x4 w; w.x = pk2(v0[0], v0[1]); w.y = pk2(v0[2], v0[3]); w.z = pk2(v1[0], v1[1]); w.w = pk2(v1[2], v1[3]); *(u32x4*)(XB + o) = w;
;                         int q0 = 0, q1 = 0; q0 = __builtin_amdgcn_cvt_pk_fp8_f32(v0[0] * 8.f, v0[1] * 8.f, q0, false); q0 = __builtin_amdgcn_cvt_pk_fp8_f32(v0[2] * 8.f, v0[3] * 8.f, q0, true);
;                         q1 = __builtin_amdgcn_cvt_pk_fp8_f32(v1[0] * 8.f, v1[1] * 8.f, q1, false); q1 = __builtin_amdgcn_cvt_pk_fp8_f32(v1[2] * 8.f, v1[3] * 8.f, q1, true);
;                         *(u32x2*)(XB8 + o) = (u32x2){(unsigned)q0, (unsigned)q1}; }
;                     s[m] += (v0[0] * v0[0] + v0[1] * v0[1]) + (v0[2] * v0[2] + v0[3] * v0[3]) + (v1[0] * v1[0] + v1[1] * v1[1]) + (v1[2] * v1[2] + v1[3] * v1[3]); } }
	v_pk_fma_f32 v[104:105], v[104:105], v[154:155], v[216:217]
	v_lshlrev_b32_e32 v154, 16, v211
	v_and_b32_e32 v155, 0xffff0000, v211
	v_pk_fma_f32 v[106:107], v[106:107], v[154:155], v[218:219]
	v_lshl_add_u64 v[154:155], s[8:9], 0, v[136:137]
	v_mul_f32_e32 v136, 0x45800000, v181
	v_cndmask_b32_e32 v181, v181, v136, vcc
	v_mul_f32_e32 v100, v100, v181
	v_mul_f32_e32 v101, v101, v181
	v_mul_f32_e32 v100, 0xbfb8aa3b, v100
	v_mul_f32_e32 v101, 0xbfb8aa3b, v101
	v_mul_f32_e32 v102, v102, v181
	v_mul_f32_e32 v103, v103, v181
	v_exp_f32_e32 v100, v100
	v_exp_f32_e32 v101, v101
	v_mul_f32_e32 v102, 0xbfb8aa3b, v102
	v_mul_f32_e32 v103, 0xbfb8aa3b, v103
	v_mul_f32_e32 v96, v96, v181
	v_mul_f32_e32 v97, v97, v181
	v_exp_f32_e32 v102, v102
	v_exp_f32_e32 v103, v103
	v_mul_f32_e32 v96, 0xbfb8aa3b, v96
	v_mul_f32_e32 v97, 0xbfb8aa3b, v97
	v_mul_f32_e32 v98, v98, v181
	v_mul_f32_e32 v99, v99, v181
	v_exp_f32_e32 v96, v96
	v_exp_f32_e32 v97, v97
	v_mul_f32_e32 v98, 0xbfb8aa3b, v98
	v_mul_f32_e32 v99, 0xbfb8aa3b, v99
	v_exp_f32_e32 v98, v98
	v_exp_f32_e32 v99, v99
	v_add_f32_e32 v100, 1.0, v100
	v_add_f32_e32 v101, 1.0, v101
	v_rcp_f32_e32 v100, v100
	v_rcp_f32_e32 v101, v101
	v_add_f32_e32 v102, 1.0, v102
	v_add_f32_e32 v103, 1.0, v103
	v_rcp_f32_e32 v102, v102
	v_rcp_f32_e32 v103, v103
	v_add_f32_e32 v96, 1.0, v96
	v_add_f32_e32 v97, 1.0, v97
	v_rcp_f32_e32 v96, v96
	v_rcp_f32_e32 v97, v97
	v_add_f32_e32 v98, 1.0, v98
	v_add_f32_e32 v99, 1.0, v99
	s_waitcnt vmcnt(12)
	v_lshlrev_b32_e32 v136, 16, v220
	v_and_b32_e32 v137, 0xffff0000, v220
	v_rcp_f32_e32 v98, v98
	v_rcp_f32_e32 v99, v99
	s_waitcnt vmcnt(11)
	v_pk_fma_f32 v[100:101], v[100:101], v[136:137], v[224:225]
	v_lshlrev_b32_e32 v136, 16, v221
	v_and_b32_e32 v137, 0xffff0000, v221
	v_pk_fma_f32 v[102:103], v[102:103], v[136:137], v[226:227]
	v_lshlrev_b32_e32 v136, 16, v222
	v_and_b32_e32 v137, 0xffff0000, v222
	s_waitcnt vmcnt(10)
	v_pk_fma_f32 v[96:97], v[96:97], v[136:137], v[228:229]
	v_lshlrev_b32_e32 v136, 16, v223
	v_and_b32_e32 v137, 0xffff0000, v223
	v_pk_fma_f32 v[98:99], v[98:99], v[136:137], v[230:231]
	v_lshl_add_u64 v[136:137], v[134:135], 0, s[30:31]
	v_lshl_add_u64 v[144:145], v[136:137], 0, v[144:145]
	global_store_dwordx4 v[154:155], v[108:111], off
	global_store_dwordx4 v[154:155], v[104:107], off offset:16
	global_store_dwordx4 v[148:149], v[100:103], off
	global_store_dwordx4 v[148:149], v[96:99], off offset:16
	v_lshl_add_u64 v[182:183], v[144:145], 1, s[24:25]
	s_nop 0
	v_lshl_add_u64 v[144:145], v[144:145], 2, s[22:23]
	s_nop 0
	s_nop 0
	v_lshl_add_u64 v[194:195], v[136:137], 0, v[146:147]
	v_lshl_add_u64 v[144:145], v[194:195], 1, s[24:25]
	s_nop 0
	v_lshl_add_u64 v[198:199], v[194:195], 2, s[22:23]
	s_nop 0
	v_mul_f32_e32 v90, 0xbfb8aa3b, v90
	s_nop 0
	v_mul_f32_e32 v91, 0xbfb8aa3b, v91
	v_exp_f32_e32 v92, v92
	v_exp_f32_e32 v93, v93
	v_exp_f32_e32 v90, v90
	v_exp_f32_e32 v91, v91
	v_mul_f32_e32 v86, v86, v180
	v_mul_f32_e32 v87, v87, v180
	v_mul_f32_e32 v84, v84, v180
	v_mul_f32_e32 v85, v85, v180
	v_mul_f32_e32 v86, 0xbfb8aa3b, v86
	v_mul_f32_e32 v87, 0xbfb8aa3b, v87
	v_mul_f32_e32 v80, v80, v180
	v_mul_f32_e32 v81, v81, v180
	v_add_f32_e32 v94, 1.0, v94
	v_add_f32_e32 v95, 1.0, v95
	v_mul_f32_e32 v84, 0xbfb8aa3b, v84
	v_mul_f32_e32 v85, 0xbfb8aa3b, v85
	v_exp_f32_e32 v86, v86
	v_exp_f32_e32 v87, v87
	v_mul_f32_e32 v80, 0xbfb8aa3b, v80
	v_mul_f32_e32 v81, 0xbfb8aa3b, v81
	v_mul_f32_e32 v82, v82, v180
	v_mul_f32_e32 v83, v83, v180
	v_rcp_f32_e32 v94, v94
	v_rcp_f32_e32 v95, v95
	v_add_f32_e32 v88, 1.0, v88
	v_add_f32_e32 v89, 1.0, v89
	v_exp_f32_e32 v84, v84
	v_exp_f32_e32 v85, v85
	v_exp_f32_e32 v80, v80
	v_exp_f32_e32 v81, v81
	v_mul_f32_e32 v82, 0xbfb8aa3b, v82
	v_mul_f32_e32 v83, 0xbfb8aa3b, v83
	v_add_f32_e32 v92, 1.0, v92
	v_add_f32_e32 v93, 1.0, v93
	v_rcp_f32_e32 v88, v88
	v_rcp_f32_e32 v89, v89
	v_add_f32_e32 v90, 1.0, v90
	v_add_f32_e32 v91, 1.0, v91
	v_exp_f32_e32 v82, v82
	v_exp_f32_e32 v83, v83
	v_rcp_f32_e32 v92, v92
	v_rcp_f32_e32 v93, v93
	v_rcp_f32_e32 v90, v90
	v_rcp_f32_e32 v91, v91
	v_add_f32_e32 v86, 1.0, v86
	v_add_f32_e32 v87, 1.0, v87
	v_add_f32_e32 v84, 1.0, v84
	v_add_f32_e32 v85, 1.0, v85
	v_rcp_f32_e32 v86, v86
	v_rcp_f32_e32 v87, v87
	v_add_f32_e32 v80, 1.0, v80
	v_add_f32_e32 v81, 1.0, v81
	v_rcp_f32_e32 v84, v84
	v_rcp_f32_e32 v85, v85
	v_rcp_f32_e32 v80, v80
	v_rcp_f32_e32 v81, v81
	v_add_f32_e32 v82, 1.0, v82
	v_add_f32_e32 v83, 1.0, v83
	v_rcp_f32_e32 v82, v82
	v_rcp_f32_e32 v83, v83
	v_pk_mul_f32 v[124:125], v[124:125], v[124:125]
	v_pk_mul_f32 v[126:127], v[126:127], v[126:127]
	v_cmp_gt_u32_e32 vcc, 16, v178
	v_pk_mul_f32 v[120:121], v[120:121], v[120:121]
	v_add_f32_e32 v178, v126, v127
	v_add_f32_e32 v124, v124, v125
	v_pk_mul_f32 v[122:123], v[122:123], v[122:123]
	v_add_f32_e32 v124, v124, v178
	v_add_f32_e32 v120, v120, v121
	v_lshl_add_u64 v[248:249], v[136:137], 0, v[158:159]
	v_lshl_add_u64 v[182:183], v[248:249], 1, s[24:25]
	global_load_dwordx4 v[208:211], v[182:183], off
	v_lshl_add_u64 v[252:253], v[248:249], 2, s[22:23]
	global_load_dwordx4 v[212:215], v[252:253], off
	global_load_dwordx4 v[216:219], v[252:253], off offset:16
	v_lshl_add_u64 v[248:249], v[136:137], 0, v[156:157]
	v_lshl_add_u64 v[252:253], v[248:249], 2, s[22:23]
	v_lshl_add_u64 v[182:183], v[248:249], 1, s[24:25]
	global_load_dwordx4 v[220:223], v[252:253], off offset:16
	global_load_dwordx4 v[224:227], v[182:183], off
	global_load_dwordx4 v[228:231], v[252:253], off
	s_waitcnt vmcnt(15)
	v_lshlrev_b32_e32 v202, 16, v232
	v_and_b32_e32 v203, 0xffff0000, v232
	v_lshlrev_b32_e32 v182, 16, v233
	v_and_b32_e32 v183, 0xffff0000, v233
	s_waitcnt vmcnt(14)
; __device__ __forceinline__ float bf_lo(unsigned u) { return __uint_as_float(u << 16); }
;     __device__ __forceinline__ void operator()(const f32x4 (&acc)[2][2][4][2], const Unit& u, int wr, int wc, int fr, int fq) const {
;     ...
;         for (int ai = 0; ai < 2; ++ai) { float s[4] = {0.f, 0.f, 0.f, 0.f};
; #pragma unroll
;             for (int bj = 0; bj < 2; ++bj)
; #pragma unroll
;               for (int mh = 0; mh < 2; ++mh) { f32x4 x0[2], x1[2]; u32x4 tw[2];
; #pragma unroll
;                 for (int mm = 0; mm < 2; ++mm) { const int m = 2 * mh + mm; const size_t o = (size_t)(row0 + ai * HALF + m * 16) * DM + col0 + bj * HALF; x0[mm] = *(const f32x4*)(X1 + o); x1[mm] = *(const f32x4*)(X1 + o + 4); tw[mm] = *(const u32x4*)(T + o); }
; #pragma unroll
;                 for (int mm = 0; mm < 2; ++mm) { const int m = 2 * mh + mm; const size_t o = (size_t)(row0 + ai * HALF + m * 16) * DM + col0 + bj * HALF;
;                     const float rs = rsqrtf(rsv[ai][m] * (1.f / DM) + EPS);
;                     const f32x4 a0 = acc[ai][bj][m][0], a1 = acc[ai][bj][m][1]; f32x4 v0 = x0[mm], v1 = x1[mm];
;                     v0[0] += sigm(a0[0] * rs) * bf_lo(tw[mm].x); v0[1] += sigm(a0[1] * rs) * bf_hi(tw[mm].x); v0[2] += sigm(a0[2] * rs) * bf_lo(tw[mm].y); v0[3] += sigm(a0[3] * rs) * bf_hi(tw[mm].y);
;                     v1[0] += sigm(a1[0] * rs) * bf_lo(tw[mm].z); v1[1] += sigm(a1[1] * rs) * bf_hi(tw[mm].z); v1[2] += sigm(a1[2] * rs) * bf_lo(tw[mm].w); v1[3] += sigm(a1[3] * rs) * bf_hi(tw[mm].w);
;                     *(f32x4*)(xout + o) = v0; *(f32x4*)(xout + o + 4) = v1;
;                     if (wxb) { u32x4 w; w.x = pk2(v0[0], v0[1]); w.y = pk2(v0[2], v0[3]); w.z = pk2(v1[0], v1[1]); w.w = pk2(v1[2], v1[3]); *(u32x4*)(XB + o) = w;
;                         int q0 = 0, q1 = 0; q0 = __builtin_amdgcn_cvt_pk_fp8_f32(v0[0] * 8.f, v0[1] * 8.f, q0, false); q0 = __builtin_amdgcn_cvt_pk_fp8_f32(v0[2] * 8.f, v0[3] * 8.f, q0, true);
;                         q1 = __builtin_amdgcn_cvt_pk_fp8_f32(v1[0] * 8.f, v1[1] * 8.f, q1, false); q1 = __builtin_amdgcn_cvt_pk_fp8_f32(v1[2] * 8.f, v1[3] * 8.f, q1, true);
;                         *(u32x2*)(XB8 + o) = (u32x2){(unsigned)q0, (unsigned)q1}; }
;                     s[m] += (v0[0] * v0[0] + v0[1] * v0[1]) + (v0[2] * v0[2] + v0[3] * v0[3]) + (v1[0] * v1[0] + v1[1] * v1[1]) + (v1[2] * v1[2] + v1[3] * v1[3]); } }
; #pragma unroll
	v_pk_fma_f32 v[94:95], v[94:95], v[182:183], v[188:189]
	v_lshlrev_b32_e32 v182, 16, v234
	v_and_b32_e32 v183, 0xffff0000, v234
	s_waitcnt vmcnt(13)
	v_pk_fma_f32 v[88:89], v[88:89], v[182:183], v[190:191]
	v_lshlrev_b32_e32 v182, 16, v235
	v_and_b32_e32 v183, 0xffff0000, v235
	v_pk_fma_f32 v[92:93], v[92:93], v[202:203], v[186:187]
	v_pk_fma_f32 v[90:91], v[90:91], v[182:183], v[192:193]
	global_store_dwordx4 v[150:151], v[92:95], off offset:512
	global_store_dwordx4 v[150:151], v[88:91], off offset:528
	s_waitcnt vmcnt(14)
	v_lshlrev_b32_e32 v150, 16, v236
	v_and_b32_e32 v151, 0xffff0000, v236
	v_lshlrev_b32_e32 v144, 16, v237
	v_and_b32_e32 v145, 0xffff0000, v237
	s_waitcnt vmcnt(13)
	v_pk_fma_f32 v[86:87], v[86:87], v[144:145], v[242:243]
	v_lshlrev_b32_e32 v144, 16, v238
	v_and_b32_e32 v145, 0xffff0000, v238
	v_pk_fma_f32 v[84:85], v[84:85], v[150:151], v[240:241]
	s_waitcnt vmcnt(12)
	v_pk_fma_f32 v[80:81], v[80:81], v[144:145], v[244:245]
	v_lshlrev_b32_e32 v144, 16, v239
	v_and_b32_e32 v145, 0xffff0000, v239
	v_lshl_add_u64 v[150:151], v[136:137], 0, v[158:159]
	v_pk_fma_f32 v[82:83], v[82:83], v[144:145], v[246:247]
	global_store_dwordx4 v[152:153], v[84:87], off offset:512
	global_store_dwordx4 v[152:153], v[80:83], off offset:528
	v_lshl_add_u64 v[144:145], v[150:151], 1, s[24:25]
	s_nop 0
	v_lshl_add_u64 v[158:159], v[150:151], 2, s[22:23]
	s_nop 0
	s_nop 0
	v_pk_mul_f32 v[188:189], v[88:89], v[88:89]
	v_lshl_add_u64 v[88:89], v[136:137], 0, v[156:157]
	v_pk_mul_f32 v[158:159], v[92:93], v[92:93]
	v_lshl_add_u64 v[126:127], v[88:89], 2, s[22:23]
	v_lshl_add_u64 v[92:93], v[88:89], 1, s[24:25]
	v_pk_mul_f32 v[186:187], v[94:95], v[94:95]
	v_pk_mul_f32 v[190:191], v[90:91], v[90:91]
	s_nop 0
	s_nop 0
	s_nop 0
	v_add_f32_e32 v120, v120, v124
	v_add_f32_e32 v121, v122, v123
	v_add_f32_e32 v124, v121, v120
	s_nop 0
	v_mul_f32_e32 v76, v76, v179
	v_mul_f32_e32 v77, v77, v179
	v_mul_f32_e32 v76, 0xbfb8aa3b, v76
	v_mul_f32_e32 v77, 0xbfb8aa3b, v77
	v_mul_f32_e32 v78, v78, v179
	v_mul_f32_e32 v79, v79, v179
	v_exp_f32_e32 v76, v76
	v_exp_f32_e32 v77, v77
	v_mul_f32_e32 v78, 0xbfb8aa3b, v78
	v_mul_f32_e32 v79, 0xbfb8aa3b, v79
	v_mul_f32_e32 v72, v72, v179
	v_mul_f32_e32 v73, v73, v179
	v_exp_f32_e32 v78, v78
	v_exp_f32_e32 v79, v79
	v_mul_f32_e32 v72, 0xbfb8aa3b, v72
	v_mul_f32_e32 v73, 0xbfb8aa3b, v73
	v_mul_f32_e32 v74, v74, v179
	v_mul_f32_e32 v75, v75, v179
	v_exp_f32_e32 v72, v72
	v_exp_f32_e32 v73, v73
	v_mul_f32_e32 v74, 0xbfb8aa3b, v74
	v_mul_f32_e32 v75, 0xbfb8aa3b, v75
	v_mul_f32_e32 v70, v70, v181
	v_mul_f32_e32 v71, v71, v181
	v_exp_f32_e32 v74, v74
	v_exp_f32_e32 v75, v75
	v_mul_f32_e32 v70, 0xbfb8aa3b, v70
	v_mul_f32_e32 v71, 0xbfb8aa3b, v71
	v_mul_f32_e32 v64, v64, v181
	v_mul_f32_e32 v65, v65, v181
	v_add_f32_e32 v125, v186, v187
	v_add_f32_e32 v126, v158, v159
	v_add_f32_e32 v76, 1.0, v76
	v_add_f32_e32 v77, 1.0, v77
	v_exp_f32_e32 v70, v70
	v_exp_f32_e32 v71, v71
	v_mul_f32_e32 v64, 0xbfb8aa3b, v64
	v_mul_f32_e32 v65, 0xbfb8aa3b, v65
	v_add_f32_e32 v125, v126, v125
	v_add_f32_e32 v126, v188, v189
	v_rcp_f32_e32 v76, v76
	v_rcp_f32_e32 v77, v77
	v_add_f32_e32 v78, 1.0, v78
	v_add_f32_e32 v79, 1.0, v79
	v_exp_f32_e32 v64, v64
	v_exp_f32_e32 v65, v65
	v_add_f32_e32 v125, v126, v125
	v_add_f32_e32 v126, v190, v191
	v_rcp_f32_e32 v78, v78
	v_rcp_f32_e32 v79, v79
	v_add_f32_e32 v72, 1.0, v72
	v_add_f32_e32 v73, 1.0, v73
	v_add_f32_e32 v125, v126, v125
	v_rcp_f32_e32 v72, v72
	v_rcp_f32_e32 v73, v73
	v_add_f32_e32 v74, 1.0, v74
	v_add_f32_e32 v75, 1.0, v75
	v_add_f32_e32 v126, v124, v125
	v_rcp_f32_e32 v74, v74
	v_rcp_f32_e32 v75, v75
	v_add_f32_e32 v70, 1.0, v70
	v_add_f32_e32 v71, 1.0, v71
	v_rcp_f32_e32 v70, v70
	v_rcp_f32_e32 v71, v71
	v_add_f32_e32 v64, 1.0, v64
	s_waitcnt vmcnt(9)
	v_lshlrev_b32_e32 v124, 16, v208
	v_and_b32_e32 v125, 0xffff0000, v208
	s_waitcnt vmcnt(8)
	v_pk_fma_f32 v[76:77], v[76:77], v[124:125], v[212:213]
	v_lshlrev_b32_e32 v124, 16, v209
	v_and_b32_e32 v125, 0xffff0000, v209
	v_add_f32_e32 v65, 1.0, v65
	v_pk_fma_f32 v[78:79], v[78:79], v[124:125], v[214:215]
	v_lshlrev_b32_e32 v124, 16, v210
	v_and_b32_e32 v125, 0xffff0000, v210
	v_rcp_f32_e32 v64, v64
	v_rcp_f32_e32 v65, v65
	s_waitcnt vmcnt(7)
	v_pk_fma_f32 v[72:73], v[72:73], v[124:125], v[216:217]
	v_lshlrev_b32_e32 v124, 16, v211
	v_and_b32_e32 v125, 0xffff0000, v211
	v_pk_fma_f32 v[74:75], v[74:75], v[124:125], v[218:219]
	s_waitcnt vmcnt(5)
	v_lshlrev_b32_e32 v124, 16, v224
	v_and_b32_e32 v125, 0xffff0000, v224
	v_lshlrev_b32_e32 v92, 16, v225
	v_and_b32_e32 v93, 0xffff0000, v225
	v_mul_f32_e32 v68, v68, v181
	v_mul_f32_e32 v69, v69, v181
	s_waitcnt vmcnt(4)
	v_pk_fma_f32 v[70:71], v[70:71], v[92:93], v[230:231]
	v_lshlrev_b32_e32 v92, 16, v226
	v_and_b32_e32 v93, 0xffff0000, v226
	v_mul_f32_e32 v66, v66, v181
	v_mul_f32_e32 v67, v67, v181
	v_mul_f32_e32 v68, 0xbfb8aa3b, v68
	v_mul_f32_e32 v69, 0xbfb8aa3b, v69
	v_pk_fma_f32 v[64:65], v[64:65], v[92:93], v[220:221]
	v_mul_f32_e32 v66, 0xbfb8aa3b, v66
	v_mul_f32_e32 v67, 0xbfb8aa3b, v67
	ds_bpermute_b32 v88, v166, v126
	v_exp_f32_e32 v68, v68
	v_exp_f32_e32 v69, v69
	v_exp_f32_e32 v66, v66
	v_exp_f32_e32 v67, v67
	v_add_f32_e32 v68, 1.0, v68
	v_add_f32_e32 v69, 1.0, v69
	v_add_f32_e32 v66, 1.0, v66
	v_add_f32_e32 v67, 1.0, v67
	s_waitcnt lgkmcnt(0)
	v_add_f32_e32 v88, v126, v88
	v_rcp_f32_e32 v68, v68
	v_rcp_f32_e32 v69, v69
	v_rcp_f32_e32 v66, v66
	v_rcp_f32_e32 v67, v67
	ds_bpermute_b32 v89, v167, v88
	v_lshlrev_b32_e32 v92, 16, v227
	v_and_b32_e32 v93, 0xffff0000, v227
	v_pk_fma_f32 v[68:69], v[68:69], v[124:125], v[228:229]
	v_pk_fma_f32 v[66:67], v[66:67], v[92:93], v[222:223]
	global_store_dwordx4 v[154:155], v[76:79], off offset:512
	global_store_dwordx4 v[154:155], v[72:75], off offset:528
	global_store_dwordx4 v[148:149], v[68:71], off offset:512
	global_store_dwordx4 v[148:149], v[64:67], off offset:528
	s_and_saveexec_b64 s[0:1], vcc
	s_cbranch_execz .LBB0_2211
	s_waitcnt lgkmcnt(0)
	v_add_f32_e32 v90, v88, v89
	v_lshl_add_u64 v[88:89], v[132:133], 2, s[10:11]
	global_atomic_add_f32 v[88:89], v90, off

; __device__ __forceinline__ float bf_lo(unsigned u) { return __uint_as_float(u << 16); }
;     __device__ __forceinline__ void operator()(const f32x4 (&acc)[2][2][4][2], const Unit& u, int wr, int wc, int fr, int fq) const {
;     ...
;         for (int ai = 0; ai < 2; ++ai) { float s[4] = {0.f, 0.f, 0.f, 0.f};
; #pragma unroll
;             for (int bj = 0; bj < 2; ++bj)
; #pragma unroll
;               for (int mh = 0; mh < 2; ++mh) { f32x4 x0[2], x1[2]; u32x4 tw[2];
; #pragma unroll
;                 for (int mm = 0; mm < 2; ++mm) { const int m = 2 * mh + mm; const size_t o = (size_t)(row0 + ai * HALF + m * 16) * DM + col0 + bj * HALF; x0[mm] = *(const f32x4*)(X1 + o); x1[mm] = *(const f32x4*)(X1 + o + 4); tw[mm] = *(const u32x4*)(T + o); }
; #pragma unroll
;                 for (int mm = 0; mm < 2; ++mm) { const int m = 2 * mh + mm; const size_t o = (size_t)(row0 + ai * HALF + m * 16) * DM + col0 + bj * HALF;
;                     const float rs = rsqrtf(rsv[ai][m] * (1.f / DM) + EPS);
;                     const f32x4 a0 = acc[ai][bj][m][0], a1 = acc[ai][bj][m][1]; f32x4 v0 = x0[mm], v1 = x1[mm];
;                     v0[0] += sigm(a0[0] * rs) * bf_lo(tw[mm].x); v0[1] += sigm(a0[1] * rs) * bf_hi(tw[mm].x); v0[2] += sigm(a0[2] * rs) * bf_lo(tw[mm].y); v0[3] += sigm(a0[3] * rs) * bf_hi(tw[mm].y);
;                     v1[0] += sigm(a1[0] * rs) * bf_lo(tw[mm].z); v1[1] += sigm(a1[1] * rs) * bf_hi(tw[mm].z); v1[2] += sigm(a1[2] * rs) * bf_lo(tw[mm].w); v1[3] += sigm(a1[3] * rs) * bf_hi(tw[mm].w);
;                     *(f32x4*)(xout + o) = v0; *(f32x4*)(xout + o + 4) = v1;
;                     if (wxb) { u32x4 w; w.x = pk2(v0[0], v0[1]); w.y = pk2(v0[2], v0[3]); w.z = pk2(v1[0], v1[1]); w.w = pk2(v1[2], v1[3]); *(u32x4*)(XB + o) = w;
;                         int q0 = 0, q1 = 0; q0 = __builtin_amdgcn_cvt_pk_fp8_f32(v0[0] * 8.f, v0[1] * 8.f, q0, false); q0 = __builtin_amdgcn_cvt_pk_fp8_f32(v0[2] * 8.f, v0[3] * 8.f, q0, true);
;                         q1 = __builtin_amdgcn_cvt_pk_fp8_f32(v1[0] * 8.f, v1[1] * 8.f, q1, false); q1 = __builtin_amdgcn_cvt_pk_fp8_f32(v1[2] * 8.f, v1[3] * 8.f, q1, true);
;                         *(u32x2*)(XB8 + o) = (u32x2){(unsigned)q0, (unsigned)q1}; }
;                     s[m] += (v0[0] * v0[0] + v0[1] * v0[1]) + (v0[2] * v0[2] + v0[3] * v0[3]) + (v1[0] * v1[0] + v1[1] * v1[1]) + (v1[2] * v1[2] + v1[3] * v1[3]); } }
.LBB0_2217:
	s_or_b64 exec, exec, s[0:1]
	v_add_u32_e32 v68, 0x80, v132
	v_ashrrev_i32_e32 v69, 31, v68
	v_lshlrev_b64 v[74:75], 11, v[68:69]
	s_waitcnt lgkmcnt(0)
	v_lshl_add_u64 v[64:65], v[74:75], 0, v[134:135]
	v_lshl_add_u64 v[66:67], v[64:65], 1, s[24:25]
	v_lshlrev_b64 v[70:71], 2, v[64:65]
	global_load_dwordx4 v[76:79], v[66:67], off
	v_lshl_add_u64 v[64:65], s[22:23], 0, v[70:71]
	global_load_dwordx4 v[80:83], v[64:65], off
	global_load_dwordx4 v[88:91], v[64:65], off offset:16
	v_add_u32_e32 v66, 0x90, v132
	v_ashrrev_i32_e32 v67, 31, v66
	v_lshlrev_b64 v[86:87], 11, v[66:67]
	v_lshl_add_u64 v[72:73], v[86:87], 0, v[134:135]
	v_lshlrev_b64 v[84:85], 2, v[72:73]
	v_fmamk_f32 v102, v177, 0x3a000000, v173
	v_lshl_add_u64 v[72:73], v[72:73], 1, s[24:25]
	v_lshl_add_u64 v[100:101], s[22:23], 0, v[84:85]
	global_load_dwordx4 v[92:95], v[100:101], off offset:16
	global_load_dwordx4 v[96:99], v[72:73], off
	v_mul_f32_e32 v72, 0x4b800000, v102
	v_cmp_gt_f32_e64 s[4:5], s47, v102
	v_fmamk_f32 v104, v176, 0x3a000000, v173
	v_mul_f32_e32 v73, 0x4b800000, v104
	v_cndmask_b32_e64 v72, v102, v72, s[4:5]
	global_load_dwordx4 v[100:103], v[100:101], off
	v_rsq_f32_e32 v105, v72
	v_cmp_gt_f32_e64 s[6:7], s47, v104
	v_add_u32_e32 v64, 0xa0, v132
	v_ashrrev_i32_e32 v65, 31, v64
	v_cndmask_b32_e64 v72, v104, v73, s[6:7]
	v_rsq_f32_e32 v106, v72
	v_lshl_add_u64 v[72:73], s[8:9], 0, v[70:71]
	v_mul_f32_e32 v70, 0x45800000, v105
	v_cndmask_b32_e64 v116, v105, v70, s[4:5]
	v_mul_f32_e32 v60, v60, v116
	v_mul_f32_e32 v61, v61, v116
	v_mul_f32_e32 v56, v56, v116
	v_mul_f32_e32 v57, v57, v116
	v_mul_f32_e32 v60, 0xbfb8aa3b, v60
	v_mul_f32_e32 v61, 0xbfb8aa3b, v61
	v_mul_f32_e32 v56, 0xbfb8aa3b, v56
	v_mul_f32_e32 v57, 0xbfb8aa3b, v57
	v_exp_f32_e32 v60, v60
	v_exp_f32_e32 v61, v61
	v_exp_f32_e32 v56, v56
	v_exp_f32_e32 v57, v57
	v_mul_f32_e32 v62, v62, v116
	v_mul_f32_e32 v63, v63, v116
	v_mul_f32_e32 v58, v58, v116
	v_mul_f32_e32 v59, v59, v116
	v_mul_f32_e32 v62, 0xbfb8aa3b, v62
	v_mul_f32_e32 v63, 0xbfb8aa3b, v63
	v_mul_f32_e32 v58, 0xbfb8aa3b, v58
	v_mul_f32_e32 v59, 0xbfb8aa3b, v59
	v_exp_f32_e32 v62, v62
	v_exp_f32_e32 v63, v63
	v_exp_f32_e32 v58, v58
	v_exp_f32_e32 v59, v59
	v_add_f32_e32 v60, 1.0, v60
	v_add_f32_e32 v61, 1.0, v61
	v_add_f32_e32 v70, 1.0, v56
	v_add_f32_e32 v71, 1.0, v57
	v_rcp_f32_e32 v56, v60
	v_rcp_f32_e32 v57, v61
	v_rcp_f32_e32 v70, v70
	v_rcp_f32_e32 v71, v71
	v_add_f32_e32 v62, 1.0, v62
	v_add_f32_e32 v63, 1.0, v63
	v_add_f32_e32 v104, 1.0, v58
	v_add_f32_e32 v105, 1.0, v59
	v_rcp_f32_e32 v58, v62
	v_rcp_f32_e32 v59, v63
	v_rcp_f32_e32 v104, v104
	v_rcp_f32_e32 v105, v105
	v_lshl_add_u64 v[74:75], v[136:137], 0, v[74:75]
	v_mul_f32_e32 v28, v28, v116
	v_mul_f32_e32 v29, v29, v116
	v_mul_f32_e32 v28, 0xbfb8aa3b, v28
	v_mul_f32_e32 v29, 0xbfb8aa3b, v29
	v_mul_f32_e32 v30, v30, v116
	v_mul_f32_e32 v31, v31, v116
	v_exp_f32_e32 v28, v28
	v_exp_f32_e32 v29, v29
	v_mul_f32_e32 v30, 0xbfb8aa3b, v30
	v_mul_f32_e32 v31, 0xbfb8aa3b, v31
	v_mul_f32_e32 v24, v24, v116
	v_mul_f32_e32 v25, v25, v116
	v_lshlrev_b64 v[232:233], 11, v[64:65]
	v_lshl_add_u64 v[234:235], v[232:233], 0, v[134:135]
	v_lshl_add_u64 v[232:233], v[234:235], 1, s[24:25]
	global_load_dwordx4 v[208:211], v[232:233], off
	v_lshlrev_b64 v[232:233], 2, v[234:235]
	v_lshl_add_u64 v[234:235], s[22:23], 0, v[232:233]
	global_load_dwordx4 v[212:215], v[234:235], off
	global_load_dwordx4 v[216:219], v[234:235], off offset:16
	v_add_u32_e32 v234, 0xb0, v132
	v_ashrrev_i32_e32 v235, 31, v234
	v_lshlrev_b64 v[232:233], 11, v[234:235]
	v_lshl_add_u64 v[234:235], v[232:233], 0, v[134:135]
	v_lshl_add_u64 v[236:237], v[234:235], 1, s[24:25]
	v_lshlrev_b64 v[232:233], 2, v[234:235]
	global_load_dwordx4 v[220:223], v[236:237], off
	v_lshl_add_u64 v[234:235], s[22:23], 0, v[232:233]
	global_load_dwordx4 v[224:227], v[234:235], off
	global_load_dwordx4 v[228:231], v[234:235], off offset:16
	s_waitcnt vmcnt(11)
	v_lshlrev_b32_e32 v60, 16, v76
	v_and_b32_e32 v61, 0xffff0000, v76
	v_lshlrev_b32_e32 v62, 16, v77
	v_and_b32_e32 v63, 0xffff0000, v77
	v_lshlrev_b32_e32 v76, 16, v78
	v_and_b32_e32 v77, 0xffff0000, v78
	s_waitcnt vmcnt(10)
	v_pk_fma_f32 v[60:61], v[56:57], v[60:61], v[80:81]
	s_waitcnt vmcnt(9)
	v_pk_fma_f32 v[56:57], v[70:71], v[76:77], v[88:89]
	v_mul_f32_e32 v70, 0x45800000, v106
	v_cndmask_b32_e64 v89, v106, v70, s[6:7]
	v_mul_f32_e32 v52, v52, v89
	v_mul_f32_e32 v53, v53, v89
	v_mul_f32_e32 v52, 0xbfb8aa3b, v52
	v_mul_f32_e32 v53, 0xbfb8aa3b, v53
	v_mul_f32_e32 v54, v54, v89
	v_mul_f32_e32 v55, v55, v89
	v_exp_f32_e32 v52, v52
	v_exp_f32_e32 v53, v53
	v_mul_f32_e32 v54, 0xbfb8aa3b, v54
	v_mul_f32_e32 v55, 0xbfb8aa3b, v55
	v_mul_f32_e32 v48, v48, v89
	v_mul_f32_e32 v49, v49, v89
	v_exp_f32_e32 v54, v54
	v_exp_f32_e32 v55, v55
	v_mul_f32_e32 v48, 0xbfb8aa3b, v48
	v_mul_f32_e32 v49, 0xbfb8aa3b, v49
	v_mul_f32_e32 v50, v50, v89
	v_mul_f32_e32 v51, v51, v89
	v_exp_f32_e32 v48, v48
	v_exp_f32_e32 v49, v49
	v_mul_f32_e32 v50, 0xbfb8aa3b, v50
	v_mul_f32_e32 v51, 0xbfb8aa3b, v51
	v_exp_f32_e32 v50, v50
	v_exp_f32_e32 v51, v51
	v_add_f32_e32 v52, 1.0, v52
	v_add_f32_e32 v53, 1.0, v53
	v_rcp_f32_e32 v52, v52
	v_rcp_f32_e32 v53, v53
	v_add_f32_e32 v54, 1.0, v54
	v_add_f32_e32 v55, 1.0, v55
	v_rcp_f32_e32 v54, v54
	v_rcp_f32_e32 v55, v55
	v_add_f32_e32 v48, 1.0, v48
	v_add_f32_e32 v49, 1.0, v49
	v_rcp_f32_e32 v48, v48
	v_rcp_f32_e32 v49, v49
	v_add_f32_e32 v50, 1.0, v50
	v_add_f32_e32 v51, 1.0, v51
	s_waitcnt vmcnt(7)
	v_lshlrev_b32_e32 v70, 16, v96
	v_and_b32_e32 v71, 0xffff0000, v96
	v_rcp_f32_e32 v50, v50
	v_rcp_f32_e32 v51, v51
	s_waitcnt vmcnt(6)
; __device__ __forceinline__ float bf_lo(unsigned u) { return __uint_as_float(u << 16); }
; __device__ __forceinline__ float bf_hi(unsigned u) { return __uint_as_float(u & 0xffff0000u); }
; __device__ __forceinline__ float sigm(float v) { return __builtin_amdgcn_rcpf(1.f + __expf(-v)); }
;     __device__ __forceinline__ void operator()(const f32x4 (&acc)[2][2][4][2], const Unit& u, int wr, int wc, int fr, int fq) const {
;     ...
;               for (int mh = 0; mh < 2; ++mh) { f32x4 x0[2], x1[2]; u32x4 tw[2];
; #pragma unroll
;                 for (int mm = 0; mm < 2; ++mm) { const int m = 2 * mh + mm; const size_t o = (size_t)(row0 + ai * HALF + m * 16) * DM + col0 + bj * HALF; x0[mm] = *(const f32x4*)(X1 + o); x1[mm] = *(const f32x4*)(X1 + o + 4); tw[mm] = *(const u32x4*)(T + o); }
; #pragma unroll
;                 for (int mm = 0; mm < 2; ++mm) { const int m = 2 * mh + mm; const size_t o = (size_t)(row0 + ai * HALF + m * 16) * DM + col0 + bj * HALF;
;                     const float rs = rsqrtf(rsv[ai][m] * (1.f / DM) + EPS);
;                     const f32x4 a0 = acc[ai][bj][m][0], a1 = acc[ai][bj][m][1]; f32x4 v0 = x0[mm], v1 = x1[mm];
;                     v0[0] += sigm(a0[0] * rs) * bf_lo(tw[mm].x); v0[1] += sigm(a0[1] * rs) * bf_hi(tw[mm].x); v0[2] += sigm(a0[2] * rs) * bf_lo(tw[mm].y); v0[3] += sigm(a0[3] * rs) * bf_hi(tw[mm].y);
;                     v1[0] += sigm(a1[0] * rs) * bf_lo(tw[mm].z); v1[1] += sigm(a1[1] * rs) * bf_hi(tw[mm].z); v1[2] += sigm(a1[2] * rs) * bf_lo(tw[mm].w); v1[3] += sigm(a1[3] * rs) * bf_hi(tw[mm].w);
;                     *(f32x4*)(xout + o) = v0; *(f32x4*)(xout + o + 4) = v1;
	v_pk_fma_f32 v[52:53], v[52:53], v[70:71], v[100:101]
	v_lshlrev_b32_e32 v70, 16, v97
	v_and_b32_e32 v71, 0xffff0000, v97
	v_lshlrev_b32_e32 v78, 16, v79
	v_and_b32_e32 v79, 0xffff0000, v79
	v_pk_fma_f32 v[54:55], v[54:55], v[70:71], v[102:103]
	v_lshlrev_b32_e32 v70, 16, v98
	v_and_b32_e32 v71, 0xffff0000, v98
	v_pk_fma_f32 v[62:63], v[58:59], v[62:63], v[82:83]
	v_pk_fma_f32 v[58:59], v[104:105], v[78:79], v[90:91]
	v_pk_fma_f32 v[48:49], v[48:49], v[70:71], v[92:93]
	v_lshlrev_b32_e32 v70, 16, v99
	v_and_b32_e32 v71, 0xffff0000, v99
	v_lshl_add_u64 v[78:79], s[8:9], 0, v[84:85]
	v_lshlrev_b64 v[84:85], 11, v[64:65]
	v_pk_fma_f32 v[50:51], v[50:51], v[70:71], v[94:95]
	v_lshl_add_u64 v[70:71], v[84:85], 0, v[134:135]
	global_store_dwordx4 v[72:73], v[60:63], off
	global_store_dwordx4 v[72:73], v[56:59], off offset:16
	global_store_dwordx4 v[78:79], v[52:55], off
	global_store_dwordx4 v[78:79], v[48:51], off offset:16
	v_lshl_add_u64 v[76:77], v[70:71], 1, s[24:25]
	s_nop 0
	v_lshlrev_b64 v[76:77], 2, v[70:71]
	v_lshl_add_u64 v[70:71], s[22:23], 0, v[76:77]
	s_nop 0
	s_nop 0
	v_add_u32_e32 v70, 0xb0, v132
	v_fmamk_f32 v88, v175, 0x3a000000, v173
	v_ashrrev_i32_e32 v71, 31, v70
	v_mul_f32_e32 v106, 0x4b800000, v88
	v_cmp_gt_f32_e64 s[4:5], s47, v88
	v_lshlrev_b64 v[82:83], 11, v[70:71]
	v_lshl_add_u64 v[80:81], v[82:83], 0, v[134:135]
	v_cndmask_b32_e64 v88, v88, v106, s[4:5]
	v_rsq_f32_e32 v88, v88
	v_lshl_add_u64 v[102:103], v[80:81], 1, s[24:25]
	v_lshlrev_b64 v[114:115], 2, v[80:81]
	s_nop 0
	v_lshl_add_u64 v[80:81], s[22:23], 0, v[114:115]
	s_nop 0
	v_mul_f32_e32 v110, 0x45800000, v88
	v_cndmask_b32_e64 v88, v88, v110, s[4:5]
	s_nop 0
	v_mul_f32_e32 v44, v44, v88
	v_mul_f32_e32 v45, v45, v88
	v_mul_f32_e32 v44, 0xbfb8aa3b, v44
	v_mul_f32_e32 v45, 0xbfb8aa3b, v45
	v_exp_f32_e32 v44, v44
	v_exp_f32_e32 v45, v45
	v_mul_f32_e32 v46, v46, v88
	v_mul_f32_e32 v47, v47, v88
	v_mul_f32_e32 v46, 0xbfb8aa3b, v46
	v_mul_f32_e32 v47, 0xbfb8aa3b, v47
	v_mul_f32_e32 v40, v40, v88
	v_mul_f32_e32 v41, v41, v88
	v_add_f32_e32 v44, 1.0, v44
	v_add_f32_e32 v45, 1.0, v45
	v_exp_f32_e32 v46, v46
	v_exp_f32_e32 v47, v47
	v_mul_f32_e32 v40, 0xbfb8aa3b, v40
	v_mul_f32_e32 v41, 0xbfb8aa3b, v41
	v_mul_f32_e32 v42, v42, v88
	v_mul_f32_e32 v43, v43, v88
	v_rcp_f32_e32 v44, v44
	v_rcp_f32_e32 v45, v45
	v_exp_f32_e32 v40, v40
	v_exp_f32_e32 v41, v41
	v_mul_f32_e32 v42, 0xbfb8aa3b, v42
	v_mul_f32_e32 v43, 0xbfb8aa3b, v43
	v_exp_f32_e32 v42, v42
	v_exp_f32_e32 v43, v43
	v_add_f32_e32 v46, 1.0, v46
	v_add_f32_e32 v47, 1.0, v47
	v_rcp_f32_e32 v46, v46
	v_rcp_f32_e32 v47, v47
	v_add_f32_e32 v40, 1.0, v40
	v_add_f32_e32 v41, 1.0, v41
	v_rcp_f32_e32 v40, v40
	v_rcp_f32_e32 v41, v41
	v_add_f32_e32 v42, 1.0, v42
	v_add_f32_e32 v43, 1.0, v43
	v_rcp_f32_e32 v42, v42
	v_rcp_f32_e32 v43, v43
	v_exp_f32_e32 v30, v30
	v_exp_f32_e32 v31, v31
	v_mul_f32_e32 v24, 0xbfb8aa3b, v24
	v_mul_f32_e32 v25, 0xbfb8aa3b, v25
	v_mul_f32_e32 v26, v26, v116
	v_mul_f32_e32 v27, v27, v116
	v_exp_f32_e32 v24, v24
	v_exp_f32_e32 v25, v25
	v_mul_f32_e32 v26, 0xbfb8aa3b, v26
	v_mul_f32_e32 v27, 0xbfb8aa3b, v27
	v_exp_f32_e32 v26, v26
	v_exp_f32_e32 v27, v27
	v_mul_f32_e32 v20, v20, v89
	v_mul_f32_e32 v21, v21, v89
	v_add_f32_e32 v28, 1.0, v28
	v_add_f32_e32 v29, 1.0, v29
	v_mul_f32_e32 v20, 0xbfb8aa3b, v20
	v_mul_f32_e32 v21, 0xbfb8aa3b, v21
	v_mul_f32_e32 v22, v22, v89
	v_lshl_add_u64 v[240:241], v[74:75], 1, s[24:25]
	global_load_dwordx4 v[232:235], v[240:241], off
	v_lshl_add_u64 v[240:241], v[74:75], 2, s[22:23]
	global_load_dwordx4 v[96:99], v[240:241], off
	global_load_dwordx4 v[100:103], v[240:241], off offset:16
	v_lshl_add_u64 v[240:241], v[136:137], 0, v[86:87]
	v_lshl_add_u64 v[242:243], v[240:241], 1, s[24:25]
	global_load_dwordx4 v[104:107], v[242:243], off
	v_lshl_add_u64 v[240:241], v[240:241], 2, s[22:23]
	global_load_dwordx4 v[108:111], v[240:241], off
	global_load_dwordx4 v[236:239], v[240:241], off offset:16
	s_waitcnt vmcnt(15)
	v_lshlrev_b32_e32 v80, 16, v208
	v_and_b32_e32 v81, 0xffff0000, v208
	v_fmamk_f32 v90, v174, 0x3a000000, v173
	s_waitcnt vmcnt(14)
	v_pk_fma_f32 v[44:45], v[44:45], v[80:81], v[212:213]
	v_lshlrev_b32_e32 v80, 16, v209
	v_and_b32_e32 v81, 0xffff0000, v209
	v_mul_f32_e32 v91, 0x4b800000, v90
	v_cmp_gt_f32_e64 s[4:5], s47, v90
	v_pk_fma_f32 v[46:47], v[46:47], v[80:81], v[214:215]
	v_lshlrev_b32_e32 v80, 16, v210
	v_cndmask_b32_e64 v90, v90, v91, s[4:5]
	v_rsq_f32_e32 v90, v90
	v_and_b32_e32 v81, 0xffff0000, v210
	s_waitcnt vmcnt(13)
	v_pk_fma_f32 v[40:41], v[40:41], v[80:81], v[216:217]
	v_lshlrev_b32_e32 v80, 16, v211
	v_and_b32_e32 v81, 0xffff0000, v211
	v_pk_fma_f32 v[42:43], v[42:43], v[80:81], v[218:219]
	v_lshl_add_u64 v[80:81], s[8:9], 0, v[76:77]
	v_mul_f32_e32 v76, 0x45800000, v90
	v_cndmask_b32_e64 v90, v90, v76, s[4:5]
	v_mul_f32_e32 v36, v36, v90
	v_mul_f32_e32 v37, v37, v90
	v_mul_f32_e32 v36, 0xbfb8aa3b, v36
	v_mul_f32_e32 v37, 0xbfb8aa3b, v37
	v_mul_f32_e32 v38, v38, v90
	v_mul_f32_e32 v39, v39, v90
	v_exp_f32_e32 v36, v36
	v_exp_f32_e32 v37, v37
	v_mul_f32_e32 v38, 0xbfb8aa3b, v38
	v_mul_f32_e32 v39, 0xbfb8aa3b, v39
	v_mul_f32_e32 v32, v32, v90
	v_mul_f32_e32 v33, v33, v90
	v_exp_f32_e32 v38, v38
	v_exp_f32_e32 v39, v39
	v_mul_f32_e32 v32, 0xbfb8aa3b, v32
	v_mul_f32_e32 v33, 0xbfb8aa3b, v33
	v_mul_f32_e32 v34, v34, v90
	v_mul_f32_e32 v35, v35, v90
	v_exp_f32_e32 v32, v32
	v_exp_f32_e32 v33, v33
	v_mul_f32_e32 v34, 0xbfb8aa3b, v34
	v_mul_f32_e32 v35, 0xbfb8aa3b, v35
	v_exp_f32_e32 v34, v34
	v_exp_f32_e32 v35, v35
	v_add_f32_e32 v36, 1.0, v36
	v_add_f32_e32 v37, 1.0, v37
	v_rcp_f32_e32 v36, v36
	v_rcp_f32_e32 v37, v37
	v_add_f32_e32 v38, 1.0, v38
	v_add_f32_e32 v39, 1.0, v39
	v_rcp_f32_e32 v38, v38
	v_rcp_f32_e32 v39, v39
	v_add_f32_e32 v32, 1.0, v32
	v_add_f32_e32 v33, 1.0, v33
	v_rcp_f32_e32 v32, v32
	v_rcp_f32_e32 v33, v33
	v_add_f32_e32 v34, 1.0, v34
	v_add_f32_e32 v35, 1.0, v35
	s_waitcnt vmcnt(12)
; __device__ __forceinline__ unsigned pk2(float lo, float hi) { f32x2 v = {lo, hi}; bf16x2_t b = __builtin_convertvector(v, bf16x2_t); return __builtin_bit_cast(unsigned, b); }
;     __device__ __forceinline__ void operator()(const f32x4 (&acc)[2][2][4][2], const Unit& u, int wr, int wc, int fr, int fq) const {
;     ...
;               for (int mh = 0; mh < 2; ++mh) { f32x4 x0[2], x1[2]; u32x4 tw[2];
; #pragma unroll
;                 for (int mm = 0; mm < 2; ++mm) { const int m = 2 * mh + mm; const size_t o = (size_t)(row0 + ai * HALF + m * 16) * DM + col0 + bj * HALF; x0[mm] = *(const f32x4*)(X1 + o); x1[mm] = *(const f32x4*)(X1 + o + 4); tw[mm] = *(const u32x4*)(T + o); }
; #pragma unroll
;                 for (int mm = 0; mm < 2; ++mm) { const int m = 2 * mh + mm; const size_t o = (size_t)(row0 + ai * HALF + m * 16) * DM + col0 + bj * HALF;
;                     const float rs = rsqrtf(rsv[ai][m] * (1.f / DM) + EPS);
;                     const f32x4 a0 = acc[ai][bj][m][0], a1 = acc[ai][bj][m][1]; f32x4 v0 = x0[mm], v1 = x1[mm];
;                     v0[0] += sigm(a0[0] * rs) * bf_lo(tw[mm].x); v0[1] += sigm(a0[1] * rs) * bf_hi(tw[mm].x); v0[2] += sigm(a0[2] * rs) * bf_lo(tw[mm].y); v0[3] += sigm(a0[3] * rs) * bf_hi(tw[mm].y);
;                     v1[0] += sigm(a1[0] * rs) * bf_lo(tw[mm].z); v1[1] += sigm(a1[1] * rs) * bf_hi(tw[mm].z); v1[2] += sigm(a1[2] * rs) * bf_lo(tw[mm].w); v1[3] += sigm(a1[3] * rs) * bf_hi(tw[mm].w);
;                     *(f32x4*)(xout + o) = v0; *(f32x4*)(xout + o + 4) = v1;
;                     if (wxb) { u32x4 w; w.x = pk2(v0[0], v0[1]); w.y = pk2(v0[2], v0[3]); w.z = pk2(v1[0], v1[1]); w.w = pk2(v1[2], v1[3]); *(u32x4*)(XB + o) = w;
;                         int q0 = 0, q1 = 0; q0 = __builtin_amdgcn_cvt_pk_fp8_f32(v0[0] * 8.f, v0[1] * 8.f, q0, false); q0 = __builtin_amdgcn_cvt_pk_fp8_f32(v0[2] * 8.f, v0[3] * 8.f, q0, true);
;                         q1 = __builtin_amdgcn_cvt_pk_fp8_f32(v1[0] * 8.f, v1[1] * 8.f, q1, false); q1 = __builtin_amdgcn_cvt_pk_fp8_f32(v1[2] * 8.f, v1[3] * 8.f, q1, true);
;                         *(u32x2*)(XB8 + o) = (u32x2){(unsigned)q0, (unsigned)q1}; }
;                     s[m] += (v0[0] * v0[0] + v0[1] * v0[1]) + (v0[2] * v0[2] + v0[3] * v0[3]) + (v1[0] * v1[0] + v1[1] * v1[1]) + (v1[2] * v1[2] + v1[3] * v1[3]); } }
	v_lshlrev_b32_e32 v76, 16, v220
	v_and_b32_e32 v77, 0xffff0000, v220
	v_rcp_f32_e32 v34, v34
	v_rcp_f32_e32 v35, v35
	s_waitcnt vmcnt(11)
	v_pk_fma_f32 v[36:37], v[36:37], v[76:77], v[224:225]
	v_lshlrev_b32_e32 v76, 16, v221
	v_and_b32_e32 v77, 0xffff0000, v221
	v_pk_fma_f32 v[38:39], v[38:39], v[76:77], v[226:227]
	v_lshlrev_b32_e32 v76, 16, v222
	v_and_b32_e32 v77, 0xffff0000, v222
	s_waitcnt vmcnt(10)
	v_pk_fma_f32 v[32:33], v[32:33], v[76:77], v[228:229]
	v_lshlrev_b32_e32 v76, 16, v223
	v_and_b32_e32 v77, 0xffff0000, v223
	v_pk_fma_f32 v[34:35], v[34:35], v[76:77], v[230:231]
	v_lshl_add_u64 v[76:77], s[8:9], 0, v[114:115]
	global_store_dwordx4 v[80:81], v[44:47], off
	global_store_dwordx4 v[80:81], v[40:43], off offset:16
	global_store_dwordx4 v[76:77], v[36:39], off
	global_store_dwordx4 v[76:77], v[32:35], off offset:16
	v_lshl_add_u64 v[92:93], v[74:75], 1, s[24:25]
	s_nop 0
	v_lshl_add_u64 v[74:75], v[74:75], 2, s[22:23]
	s_nop 0
	s_nop 0
	v_lshl_add_u64 v[74:75], v[136:137], 0, v[86:87]
	v_lshl_add_u64 v[86:87], v[74:75], 1, s[24:25]
	s_nop 0
	v_lshl_add_u64 v[74:75], v[74:75], 2, s[22:23]
	s_nop 0
	s_nop 0
	v_mul_f32_e32 v23, v23, v89
	v_rcp_f32_e32 v28, v28
	v_rcp_f32_e32 v29, v29
	v_add_f32_e32 v30, 1.0, v30
	v_add_f32_e32 v31, 1.0, v31
	v_exp_f32_e32 v20, v20
	v_exp_f32_e32 v21, v21
	v_mul_f32_e32 v22, 0xbfb8aa3b, v22
	v_mul_f32_e32 v23, 0xbfb8aa3b, v23
	v_mul_f32_e32 v16, v16, v89
	v_mul_f32_e32 v17, v17, v89
	v_rcp_f32_e32 v30, v30
	v_rcp_f32_e32 v31, v31
	v_add_f32_e32 v24, 1.0, v24
	v_add_f32_e32 v25, 1.0, v25
	v_exp_f32_e32 v22, v22
	v_exp_f32_e32 v23, v23
	v_mul_f32_e32 v16, 0xbfb8aa3b, v16
	v_mul_f32_e32 v17, 0xbfb8aa3b, v17
	v_mul_f32_e32 v18, v18, v89
	v_mul_f32_e32 v19, v19, v89
	v_rcp_f32_e32 v24, v24
	v_rcp_f32_e32 v25, v25
	v_add_f32_e32 v26, 1.0, v26
	v_add_f32_e32 v27, 1.0, v27
	v_exp_f32_e32 v16, v16
	v_exp_f32_e32 v17, v17
	v_mul_f32_e32 v18, 0xbfb8aa3b, v18
	v_mul_f32_e32 v19, 0xbfb8aa3b, v19
	v_rcp_f32_e32 v26, v26
	v_rcp_f32_e32 v27, v27
	v_exp_f32_e32 v18, v18
	v_exp_f32_e32 v19, v19
	v_add_f32_e32 v20, 1.0, v20
	v_add_f32_e32 v21, 1.0, v21
	v_rcp_f32_e32 v20, v20
	v_rcp_f32_e32 v21, v21
	v_add_f32_e32 v22, 1.0, v22
	v_add_f32_e32 v23, 1.0, v23
	v_rcp_f32_e32 v22, v22
	v_rcp_f32_e32 v23, v23
	v_add_f32_e32 v16, 1.0, v16
	v_add_f32_e32 v17, 1.0, v17
	v_rcp_f32_e32 v16, v16
	v_rcp_f32_e32 v17, v17
	v_add_f32_e32 v18, 1.0, v18
	v_add_f32_e32 v19, 1.0, v19
	v_rcp_f32_e32 v18, v18
	v_rcp_f32_e32 v19, v19
	v_pk_mul_f32 v[60:61], v[60:61], v[60:61]
	v_pk_mul_f32 v[62:63], v[62:63], v[62:63]
	v_pk_mul_f32 v[56:57], v[56:57], v[56:57]
	v_add_f32_e32 v89, v62, v63
	v_add_f32_e32 v60, v60, v61
	v_pk_mul_f32 v[58:59], v[58:59], v[58:59]
	v_add_f32_e32 v60, v60, v89
	v_add_f32_e32 v56, v56, v57
	v_add_f32_e32 v56, v56, v60
	v_add_f32_e32 v57, v58, v59
	v_add_f32_e32 v60, v57, v56
	v_mul_f32_e32 v12, v12, v88
	v_mul_f32_e32 v13, v13, v88
	v_mul_f32_e32 v12, 0xbfb8aa3b, v12
	v_mul_f32_e32 v13, 0xbfb8aa3b, v13
	v_mul_f32_e32 v14, v14, v88
	v_mul_f32_e32 v15, v15, v88
	v_exp_f32_e32 v12, v12
	v_exp_f32_e32 v13, v13
	v_mul_f32_e32 v14, 0xbfb8aa3b, v14
	v_mul_f32_e32 v15, 0xbfb8aa3b, v15
	v_mul_f32_e32 v8, v8, v88
	v_lshl_add_u64 v[224:225], v[136:137], 0, v[84:85]
	v_lshl_add_u64 v[226:227], v[224:225], 1, s[24:25]
	global_load_dwordx4 v[208:211], v[226:227], off
	v_lshl_add_u64 v[224:225], v[224:225], 2, s[22:23]
	global_load_dwordx4 v[212:215], v[224:225], off
	global_load_dwordx4 v[92:95], v[224:225], off offset:16
	v_lshl_add_u64 v[224:225], v[136:137], 0, v[82:83]
	v_lshl_add_u64 v[228:229], v[224:225], 2, s[22:23]
	v_lshl_add_u64 v[240:241], v[224:225], 1, s[24:25]
	global_load_dwordx4 v[216:219], v[228:229], off offset:16
	global_load_dwordx4 v[220:223], v[240:241], off
	global_load_dwordx4 v[56:59], v[228:229], off
	s_waitcnt vmcnt(15)
	v_lshlrev_b32_e32 v74, 16, v232
	v_and_b32_e32 v75, 0xffff0000, v232
	s_waitcnt vmcnt(14)
	v_pk_fma_f32 v[28:29], v[28:29], v[74:75], v[96:97]
	v_lshlrev_b32_e32 v74, 16, v233
	v_and_b32_e32 v75, 0xffff0000, v233
	v_pk_fma_f32 v[30:31], v[30:31], v[74:75], v[98:99]
	v_lshlrev_b32_e32 v74, 16, v234
	v_and_b32_e32 v75, 0xffff0000, v234
	s_waitcnt vmcnt(13)
	v_pk_fma_f32 v[24:25], v[24:25], v[74:75], v[100:101]
	v_lshlrev_b32_e32 v74, 16, v235
	v_and_b32_e32 v75, 0xffff0000, v235
	v_pk_fma_f32 v[26:27], v[26:27], v[74:75], v[102:103]
	global_store_dwordx4 v[72:73], v[28:31], off offset:512
	global_store_dwordx4 v[72:73], v[24:27], off offset:528
	s_waitcnt vmcnt(14)
	v_lshlrev_b32_e32 v72, 16, v104
	v_and_b32_e32 v73, 0xffff0000, v104
	s_waitcnt vmcnt(13)
; __device__ __forceinline__ float bf_lo(unsigned u) { return __uint_as_float(u << 16); }
;     __device__ __forceinline__ void operator()(const f32x4 (&acc)[2][2][4][2], const Unit& u, int wr, int wc, int fr, int fq) const {
;     ...
;                 for (int mm = 0; mm < 2; ++mm) { const int m = 2 * mh + mm; const size_t o = (size_t)(row0 + ai * HALF + m * 16) * DM + col0 + bj * HALF; x0[mm] = *(const f32x4*)(X1 + o); x1[mm] = *(const f32x4*)(X1 + o + 4); tw[mm] = *(const u32x4*)(T + o); }
; #pragma unroll
;                 for (int mm = 0; mm < 2; ++mm) { const int m = 2 * mh + mm; const size_t o = (size_t)(row0 + ai * HALF + m * 16) * DM + col0 + bj * HALF;
;                     const float rs = rsqrtf(rsv[ai][m] * (1.f / DM) + EPS);
;                     const f32x4 a0 = acc[ai][bj][m][0], a1 = acc[ai][bj][m][1]; f32x4 v0 = x0[mm], v1 = x1[mm];
;                     v0[0] += sigm(a0[0] * rs) * bf_lo(tw[mm].x); v0[1] += sigm(a0[1] * rs) * bf_hi(tw[mm].x); v0[2] += sigm(a0[2] * rs) * bf_lo(tw[mm].y); v0[3] += sigm(a0[3] * rs) * bf_hi(tw[mm].y);
;                     v1[0] += sigm(a1[0] * rs) * bf_lo(tw[mm].z); v1[1] += sigm(a1[1] * rs) * bf_hi(tw[mm].z); v1[2] += sigm(a1[2] * rs) * bf_lo(tw[mm].w); v1[3] += sigm(a1[3] * rs) * bf_hi(tw[mm].w);
;                     *(f32x4*)(xout + o) = v0; *(f32x4*)(xout + o + 4) = v1;
;                     if (wxb) { u32x4 w; w.x = pk2(v0[0], v0[1]); w.y = pk2(v0[2], v0[3]); w.z = pk2(v1[0], v1[1]); w.w = pk2(v1[2], v1[3]); *(u32x4*)(XB + o) = w;
;                         int q0 = 0, q1 = 0; q0 = __builtin_amdgcn_cvt_pk_fp8_f32(v0[0] * 8.f, v0[1] * 8.f, q0, false); q0 = __builtin_amdgcn_cvt_pk_fp8_f32(v0[2] * 8.f, v0[3] * 8.f, q0, true);
;                         q1 = __builtin_amdgcn_cvt_pk_fp8_f32(v1[0] * 8.f, v1[1] * 8.f, q1, false); q1 = __builtin_amdgcn_cvt_pk_fp8_f32(v1[2] * 8.f, v1[3] * 8.f, q1, true);
;                         *(u32x2*)(XB8 + o) = (u32x2){(unsigned)q0, (unsigned)q1}; }
;                     s[m] += (v0[0] * v0[0] + v0[1] * v0[1]) + (v0[2] * v0[2] + v0[3] * v0[3]) + (v1[0] * v1[0] + v1[1] * v1[1]) + (v1[2] * v1[2] + v1[3] * v1[3]); } }
; #pragma unroll
;             for (int m = 0; m < 4; ++m) { float t = s[m]; t += __shfl_xor(t, 16); t += __shfl_xor(t, 32);
;                 if (fq == 0) atomicAdd(ssq2 + (row0 + ai * HALF + m * 16), t); } }
	v_pk_fma_f32 v[20:21], v[20:21], v[72:73], v[108:109]
	v_lshlrev_b32_e32 v72, 16, v105
	v_and_b32_e32 v73, 0xffff0000, v105
	v_pk_fma_f32 v[22:23], v[22:23], v[72:73], v[110:111]
	v_lshlrev_b32_e32 v72, 16, v106
	v_and_b32_e32 v73, 0xffff0000, v106
	s_waitcnt vmcnt(12)
	v_pk_fma_f32 v[16:17], v[16:17], v[72:73], v[236:237]
	v_lshlrev_b32_e32 v72, 16, v107
	v_and_b32_e32 v73, 0xffff0000, v107
	v_pk_fma_f32 v[18:19], v[18:19], v[72:73], v[238:239]
	global_store_dwordx4 v[78:79], v[20:23], off offset:512
	global_store_dwordx4 v[78:79], v[16:19], off offset:528
	v_lshl_add_u64 v[78:79], v[136:137], 0, v[84:85]
	v_lshl_add_u64 v[72:73], v[78:79], 1, s[24:25]
	s_nop 0
	v_lshl_add_u64 v[78:79], v[78:79], 2, s[22:23]
	s_nop 0
	s_nop 0
	v_pk_mul_f32 v[98:99], v[24:25], v[24:25]
	v_lshl_add_u64 v[24:25], v[136:137], 0, v[82:83]
	v_pk_mul_f32 v[78:79], v[28:29], v[28:29]
	v_lshl_add_u64 v[62:63], v[24:25], 2, s[22:23]
	v_lshl_add_u64 v[28:29], v[24:25], 1, s[24:25]
	v_pk_mul_f32 v[96:97], v[30:31], v[30:31]
	v_pk_mul_f32 v[100:101], v[26:27], v[26:27]
	s_nop 0
	s_nop 0
	s_nop 0
	v_mul_f32_e32 v9, v9, v88
	s_nop 0
	v_exp_f32_e32 v14, v14
	v_exp_f32_e32 v15, v15
	v_mul_f32_e32 v8, 0xbfb8aa3b, v8
	v_mul_f32_e32 v9, 0xbfb8aa3b, v9
	v_mul_f32_e32 v10, v10, v88
	v_mul_f32_e32 v11, v11, v88
	v_exp_f32_e32 v8, v8
	v_exp_f32_e32 v9, v9
	v_mul_f32_e32 v10, 0xbfb8aa3b, v10
	v_mul_f32_e32 v11, 0xbfb8aa3b, v11
	v_mul_f32_e32 v6, v6, v90
	v_mul_f32_e32 v7, v7, v90
	v_exp_f32_e32 v10, v10
	v_exp_f32_e32 v11, v11
	v_mul_f32_e32 v6, 0xbfb8aa3b, v6
	v_mul_f32_e32 v7, 0xbfb8aa3b, v7
	v_mul_f32_e32 v0, v0, v90
	v_mul_f32_e32 v1, v1, v90
	v_add_f32_e32 v61, v96, v97
	v_add_f32_e32 v62, v78, v79
	v_add_f32_e32 v12, 1.0, v12
	v_add_f32_e32 v13, 1.0, v13
	v_exp_f32_e32 v6, v6
	v_exp_f32_e32 v7, v7
	v_mul_f32_e32 v0, 0xbfb8aa3b, v0
	v_mul_f32_e32 v1, 0xbfb8aa3b, v1
	v_add_f32_e32 v61, v62, v61
	v_add_f32_e32 v62, v98, v99
	v_rcp_f32_e32 v12, v12
	v_rcp_f32_e32 v13, v13
	v_add_f32_e32 v14, 1.0, v14
	v_add_f32_e32 v15, 1.0, v15
	v_exp_f32_e32 v0, v0
	v_exp_f32_e32 v1, v1
	v_add_f32_e32 v61, v62, v61
	v_add_f32_e32 v62, v100, v101
	v_rcp_f32_e32 v14, v14
	v_rcp_f32_e32 v15, v15
	v_add_f32_e32 v8, 1.0, v8
	v_add_f32_e32 v9, 1.0, v9
	v_add_f32_e32 v61, v62, v61
	v_rcp_f32_e32 v8, v8
	v_rcp_f32_e32 v9, v9
	v_add_f32_e32 v10, 1.0, v10
	v_add_f32_e32 v11, 1.0, v11
	v_add_f32_e32 v62, v60, v61
	v_rcp_f32_e32 v10, v10
	v_rcp_f32_e32 v11, v11
	v_add_f32_e32 v6, 1.0, v6
	v_add_f32_e32 v7, 1.0, v7
	v_rcp_f32_e32 v6, v6
	v_rcp_f32_e32 v7, v7
	v_add_f32_e32 v0, 1.0, v0
	v_add_f32_e32 v1, 1.0, v1
	v_rcp_f32_e32 v0, v0
	v_rcp_f32_e32 v1, v1
	v_mul_f32_e32 v4, v4, v90
	v_mul_f32_e32 v5, v5, v90
	v_mul_f32_e32 v2, v2, v90
	v_mul_f32_e32 v3, v3, v90
	v_mul_f32_e32 v4, 0xbfb8aa3b, v4
	v_mul_f32_e32 v5, 0xbfb8aa3b, v5
	v_mul_f32_e32 v2, 0xbfb8aa3b, v2
	v_mul_f32_e32 v3, 0xbfb8aa3b, v3
	v_exp_f32_e32 v4, v4
	v_exp_f32_e32 v5, v5
	v_exp_f32_e32 v2, v2
	s_waitcnt vmcnt(9)
	v_lshlrev_b32_e32 v60, 16, v208
	v_and_b32_e32 v61, 0xffff0000, v208
	s_waitcnt vmcnt(8)
	v_pk_fma_f32 v[12:13], v[12:13], v[60:61], v[212:213]
	v_lshlrev_b32_e32 v60, 16, v209
	v_and_b32_e32 v61, 0xffff0000, v209
	v_pk_fma_f32 v[14:15], v[14:15], v[60:61], v[214:215]
	v_lshlrev_b32_e32 v60, 16, v210
	v_and_b32_e32 v61, 0xffff0000, v210
	s_waitcnt vmcnt(7)
	v_pk_fma_f32 v[8:9], v[8:9], v[60:61], v[92:93]
	v_lshlrev_b32_e32 v60, 16, v211
	v_and_b32_e32 v61, 0xffff0000, v211
	v_pk_fma_f32 v[10:11], v[10:11], v[60:61], v[94:95]
	s_waitcnt vmcnt(5)
	v_lshlrev_b32_e32 v60, 16, v220
	v_and_b32_e32 v61, 0xffff0000, v220
	v_lshlrev_b32_e32 v28, 16, v221
	v_and_b32_e32 v29, 0xffff0000, v221
	s_waitcnt vmcnt(4)
	v_pk_fma_f32 v[6:7], v[6:7], v[28:29], v[58:59]
	v_lshlrev_b32_e32 v28, 16, v222
	v_and_b32_e32 v29, 0xffff0000, v222
	v_pk_fma_f32 v[0:1], v[0:1], v[28:29], v[216:217]
	ds_bpermute_b32 v24, v166, v62
	v_exp_f32_e32 v3, v3
	v_add_f32_e32 v4, 1.0, v4
	v_add_f32_e32 v5, 1.0, v5
	v_add_f32_e32 v2, 1.0, v2
	v_add_f32_e32 v3, 1.0, v3
	s_waitcnt lgkmcnt(0)
	v_add_f32_e32 v24, v62, v24
	v_rcp_f32_e32 v4, v4
	v_rcp_f32_e32 v5, v5
	v_rcp_f32_e32 v2, v2
	v_rcp_f32_e32 v3, v3
	ds_bpermute_b32 v25, v167, v24
	v_lshlrev_b32_e32 v28, 16, v223
	v_and_b32_e32 v29, 0xffff0000, v223
	v_pk_fma_f32 v[4:5], v[4:5], v[60:61], v[56:57]
	v_pk_fma_f32 v[2:3], v[2:3], v[28:29], v[218:219]
	global_store_dwordx4 v[80:81], v[12:15], off offset:512
	global_store_dwordx4 v[80:81], v[8:11], off offset:528
	global_store_dwordx4 v[76:77], v[4:7], off offset:512
	global_store_dwordx4 v[76:77], v[0:3], off offset:528
	s_and_saveexec_b64 s[0:1], vcc
	s_cbranch_execz .LBB0_2219
	s_waitcnt lgkmcnt(0)
	v_add_f32_e32 v26, v24, v25
	v_lshl_add_u64 v[24:25], v[68:69], 2, s[10:11]
	global_atomic_add_f32 v[24:25], v26, off
